# E31: leading half runs its epilogue at raised wave priority (s_setprio 2 after the align barrier, 0 at the unit-loop latch); on E28
# speedup vs baseline: 1.0047x; 1.0008x over previous
.LBB0_293:
	s_setprio 0
	s_andn2_b64 vcc, exec, s[8:9]
	s_mov_b32 s92, s90
	s_mov_b32 s93, s91
	s_mov_b32 s95, s19
	s_mov_b32 s94, s18
	s_mov_b32 s18, s89
	s_cbranch_vccz .LBB0_310

.LBB0_304:
	ds_read_b128 v[142:145], v136
	ds_read_b128 v[170:173], v136 offset:1024
	ds_read_b128 v[174:177], v136 offset:2048
	ds_read_b128 v[178:181], v136 offset:3072
	ds_read_b128 v[182:185], v137
	ds_read_b128 v[186:189], v137 offset:1024
	ds_read_b128 v[190:193], v137 offset:2048
	ds_read_b128 v[194:197], v137 offset:3072
	s_add_i32 s42, s94, 0xfff80080
	s_cmp_eq_u32 vcc_lo, 28
	s_cselect_b32 s97, s8, s42
	s_cselect_b32 s52, s9, s95
	s_or_b32 vcc_hi, s97, 0x80
	s_mov_b32 m0, s72
	ds_read_b128 v[198:201], v138
	ds_read_b128 v[202:205], v138 offset:1024
	ds_read_b128 v[228:231], v138 offset:2048
	ds_read_b128 v[232:235], v138 offset:3072
	ds_read_b128 v[236:239], v138 offset:4096
	ds_read_b128 v[240:243], v138 offset:5120
	ds_read_b128 v[244:247], v138 offset:6144
	ds_read_b128 v[248:251], v138 offset:7168
	buffer_load_dwordx4 v132, s[60:63], s94 offen lds
	s_mov_b32 m0, s47
	s_nop 0
	buffer_load_dwordx4 v134, s[60:63], s94 offen lds
	s_waitcnt vmcnt(8)
	s_waitcnt lgkmcnt(0)
	s_setprio 1
	s_barrier
	v_mfma_f32_16x16x32_bf16 v[114:117], v[142:145], v[198:201], v[114:117]
	v_mfma_f32_16x16x32_bf16 v[114:117], v[170:173], v[202:205], v[114:117]
	v_mfma_f32_16x16x32_bf16 v[110:113], v[174:177], v[198:201], v[110:113]
	v_mfma_f32_16x16x32_bf16 v[110:113], v[178:181], v[202:205], v[110:113]
	v_mfma_f32_16x16x32_bf16 v[122:125], v[190:193], v[198:201], v[122:125]
	v_mfma_f32_16x16x32_bf16 v[122:125], v[194:197], v[202:205], v[122:125]
	v_mfma_f32_16x16x32_bf16 v[126:129], v[182:185], v[198:201], v[126:129]
	v_mfma_f32_16x16x32_bf16 v[126:129], v[186:189], v[202:205], v[126:129]
	v_mfma_f32_16x16x32_bf16 v[118:121], v[182:185], v[228:231], v[118:121]
	v_mfma_f32_16x16x32_bf16 v[118:121], v[186:189], v[232:235], v[118:121]
	v_mfma_f32_16x16x32_bf16 v[98:101], v[190:193], v[228:231], v[98:101]
	v_mfma_f32_16x16x32_bf16 v[98:101], v[194:197], v[232:235], v[98:101]
	v_mfma_f32_16x16x32_bf16 v[102:105], v[174:177], v[228:231], v[102:105]
	v_mfma_f32_16x16x32_bf16 v[102:105], v[178:181], v[232:235], v[102:105]
	v_mfma_f32_16x16x32_bf16 v[106:109], v[142:145], v[228:231], v[106:109]
	v_mfma_f32_16x16x32_bf16 v[106:109], v[170:173], v[232:235], v[106:109]
	v_mfma_f32_16x16x32_bf16 v[94:97], v[142:145], v[236:239], v[94:97]
	v_mfma_f32_16x16x32_bf16 v[94:97], v[170:173], v[240:243], v[94:97]
	v_mfma_f32_16x16x32_bf16 v[86:89], v[174:177], v[236:239], v[86:89]
	v_mfma_f32_16x16x32_bf16 v[86:89], v[178:181], v[240:243], v[86:89]
	v_mfma_f32_16x16x32_bf16 v[82:85], v[190:193], v[236:239], v[82:85]
	v_mfma_f32_16x16x32_bf16 v[82:85], v[194:197], v[240:243], v[82:85]
	v_mfma_f32_16x16x32_bf16 v[90:93], v[182:185], v[236:239], v[90:93]
	v_mfma_f32_16x16x32_bf16 v[90:93], v[186:189], v[240:243], v[90:93]
	v_mfma_f32_16x16x32_bf16 v[74:77], v[182:185], v[244:247], v[74:77]
	v_mfma_f32_16x16x32_bf16 v[74:77], v[186:189], v[248:251], v[74:77]
	v_mfma_f32_16x16x32_bf16 v[66:69], v[190:193], v[244:247], v[66:69]
	v_mfma_f32_16x16x32_bf16 v[66:69], v[194:197], v[248:251], v[66:69]
	v_mfma_f32_16x16x32_bf16 v[70:73], v[174:177], v[244:247], v[70:73]
	v_mfma_f32_16x16x32_bf16 v[70:73], v[178:181], v[248:251], v[70:73]
	v_mfma_f32_16x16x32_bf16 v[78:81], v[142:145], v[244:247], v[78:81]
	v_mfma_f32_16x16x32_bf16 v[78:81], v[170:173], v[248:251], v[78:81]
	s_barrier
	s_setprio 0
	s_mov_b32 s42, s62
	s_mov_b32 s43, s63
	s_mov_b32 m0, s13
	ds_read_b128 v[198:201], v138 offset:16384
	buffer_load_dwordx4 v133, s[40:43], s52 offen lds
	s_add_i32 s96, s52, 0x80000
	s_mov_b32 m0, s14
	ds_read_b128 v[202:205], v138 offset:17408
	buffer_load_dwordx4 v135, s[40:43], s52 offen lds
	s_mov_b32 m0, s15
	ds_read_b128 v[228:231], v138 offset:18432
	buffer_load_dwordx4 v133, s[40:43], s96 offen lds
	s_mov_b32 m0, s16
	ds_read_b128 v[232:235], v138 offset:19456
	buffer_load_dwordx4 v135, s[40:43], s96 offen lds
	s_mov_b32 m0, s2
	ds_read_b128 v[236:239], v138 offset:20480
	buffer_load_dwordx4 v132, s[60:63], s97 offen lds
	s_mov_b32 m0, s21
	ds_read_b128 v[240:243], v138 offset:21504
	buffer_load_dwordx4 v134, s[60:63], s97 offen lds
	ds_read_b128 v[244:247], v138 offset:22528
	ds_read_b128 v[248:251], v138 offset:23552
	s_waitcnt vmcnt(8)
	s_waitcnt lgkmcnt(0)
	s_setprio 1
	s_barrier
	v_mfma_f32_16x16x32_bf16 v[62:65], v[142:145], v[198:201], v[62:65]
	v_mfma_f32_16x16x32_bf16 v[62:65], v[170:173], v[202:205], v[62:65]
	v_mfma_f32_16x16x32_bf16 v[54:57], v[174:177], v[198:201], v[54:57]
	v_mfma_f32_16x16x32_bf16 v[54:57], v[178:181], v[202:205], v[54:57]
	v_mfma_f32_16x16x32_bf16 v[50:53], v[190:193], v[198:201], v[50:53]
	v_mfma_f32_16x16x32_bf16 v[50:53], v[194:197], v[202:205], v[50:53]
	v_mfma_f32_16x16x32_bf16 v[58:61], v[182:185], v[198:201], v[58:61]
	v_mfma_f32_16x16x32_bf16 v[58:61], v[186:189], v[202:205], v[58:61]
	v_mfma_f32_16x16x32_bf16 v[42:45], v[182:185], v[228:231], v[42:45]
	v_mfma_f32_16x16x32_bf16 v[42:45], v[186:189], v[232:235], v[42:45]
	v_mfma_f32_16x16x32_bf16 v[34:37], v[190:193], v[228:231], v[34:37]
	v_mfma_f32_16x16x32_bf16 v[34:37], v[194:197], v[232:235], v[34:37]
	v_mfma_f32_16x16x32_bf16 v[38:41], v[174:177], v[228:231], v[38:41]
	v_mfma_f32_16x16x32_bf16 v[38:41], v[178:181], v[232:235], v[38:41]
	v_mfma_f32_16x16x32_bf16 v[46:49], v[142:145], v[228:231], v[46:49]
	v_mfma_f32_16x16x32_bf16 v[46:49], v[170:173], v[232:235], v[46:49]
	v_mfma_f32_16x16x32_bf16 v[30:33], v[142:145], v[236:239], v[30:33]
	v_mfma_f32_16x16x32_bf16 v[30:33], v[170:173], v[240:243], v[30:33]
	v_mfma_f32_16x16x32_bf16 v[22:25], v[174:177], v[236:239], v[22:25]
	v_mfma_f32_16x16x32_bf16 v[22:25], v[178:181], v[240:243], v[22:25]
	v_mfma_f32_16x16x32_bf16 v[18:21], v[190:193], v[236:239], v[18:21]
	v_mfma_f32_16x16x32_bf16 v[18:21], v[194:197], v[240:243], v[18:21]
	v_mfma_f32_16x16x32_bf16 v[26:29], v[182:185], v[236:239], v[26:29]
	v_mfma_f32_16x16x32_bf16 v[26:29], v[186:189], v[240:243], v[26:29]
	v_mfma_f32_16x16x32_bf16 v[10:13], v[182:185], v[244:247], v[10:13]
	v_mfma_f32_16x16x32_bf16 v[10:13], v[186:189], v[248:251], v[10:13]
	v_mfma_f32_16x16x32_bf16 v[2:5], v[190:193], v[244:247], v[2:5]
	v_mfma_f32_16x16x32_bf16 v[2:5], v[194:197], v[248:251], v[2:5]
	v_mfma_f32_16x16x32_bf16 v[6:9], v[174:177], v[244:247], v[6:9]
	v_mfma_f32_16x16x32_bf16 v[6:9], v[178:181], v[248:251], v[6:9]
	v_mfma_f32_16x16x32_bf16 v[14:17], v[142:145], v[244:247], v[14:17]
	v_mfma_f32_16x16x32_bf16 v[14:17], v[170:173], v[248:251], v[14:17]
	s_barrier
	s_setprio 0
	ds_read_b128 v[142:145], v139
	ds_read_b128 v[170:173], v139 offset:1024
	ds_read_b128 v[174:177], v139 offset:2048
	ds_read_b128 v[178:181], v139 offset:3072
	ds_read_b128 v[182:185], v140
	ds_read_b128 v[186:189], v140 offset:1024
	ds_read_b128 v[190:193], v140 offset:2048
	ds_read_b128 v[194:197], v140 offset:3072
	s_add_i32 s97, s97, 0x80000
	s_mov_b32 m0, s23
	ds_read_b128 v[198:201], v138 offset:32768
	ds_read_b128 v[202:205], v138 offset:33792
	ds_read_b128 v[228:231], v138 offset:34816
	ds_read_b128 v[232:235], v138 offset:35840
	ds_read_b128 v[236:239], v138 offset:36864
	ds_read_b128 v[240:243], v138 offset:37888
	ds_read_b128 v[244:247], v138 offset:38912
	ds_read_b128 v[248:251], v138 offset:39936
	buffer_load_dwordx4 v132, s[60:63], s97 offen lds
	s_mov_b32 m0, s24
	s_nop 0
	buffer_load_dwordx4 v134, s[60:63], s97 offen lds
	s_waitcnt vmcnt(8)
	s_waitcnt lgkmcnt(0)
	s_setprio 1
	s_barrier
	v_mfma_f32_16x16x32_bf16 v[114:117], v[142:145], v[198:201], v[114:117]
	v_mfma_f32_16x16x32_bf16 v[114:117], v[170:173], v[202:205], v[114:117]
	v_mfma_f32_16x16x32_bf16 v[110:113], v[174:177], v[198:201], v[110:113]
	v_mfma_f32_16x16x32_bf16 v[110:113], v[178:181], v[202:205], v[110:113]
	v_mfma_f32_16x16x32_bf16 v[122:125], v[190:193], v[198:201], v[122:125]
	v_mfma_f32_16x16x32_bf16 v[122:125], v[194:197], v[202:205], v[122:125]
	v_mfma_f32_16x16x32_bf16 v[126:129], v[182:185], v[198:201], v[126:129]
	v_mfma_f32_16x16x32_bf16 v[126:129], v[186:189], v[202:205], v[126:129]
	v_mfma_f32_16x16x32_bf16 v[118:121], v[182:185], v[228:231], v[118:121]
	v_mfma_f32_16x16x32_bf16 v[118:121], v[186:189], v[232:235], v[118:121]
	v_mfma_f32_16x16x32_bf16 v[98:101], v[190:193], v[228:231], v[98:101]
	v_mfma_f32_16x16x32_bf16 v[98:101], v[194:197], v[232:235], v[98:101]
	v_mfma_f32_16x16x32_bf16 v[102:105], v[174:177], v[228:231], v[102:105]
	v_mfma_f32_16x16x32_bf16 v[102:105], v[178:181], v[232:235], v[102:105]
	v_mfma_f32_16x16x32_bf16 v[106:109], v[142:145], v[228:231], v[106:109]
	v_mfma_f32_16x16x32_bf16 v[106:109], v[170:173], v[232:235], v[106:109]
	v_mfma_f32_16x16x32_bf16 v[94:97], v[142:145], v[236:239], v[94:97]
	v_mfma_f32_16x16x32_bf16 v[94:97], v[170:173], v[240:243], v[94:97]
	v_mfma_f32_16x16x32_bf16 v[86:89], v[174:177], v[236:239], v[86:89]
	v_mfma_f32_16x16x32_bf16 v[86:89], v[178:181], v[240:243], v[86:89]
	v_mfma_f32_16x16x32_bf16 v[82:85], v[190:193], v[236:239], v[82:85]
	v_mfma_f32_16x16x32_bf16 v[82:85], v[194:197], v[240:243], v[82:85]
	v_mfma_f32_16x16x32_bf16 v[90:93], v[182:185], v[236:239], v[90:93]
	v_mfma_f32_16x16x32_bf16 v[90:93], v[186:189], v[240:243], v[90:93]
	v_mfma_f32_16x16x32_bf16 v[74:77], v[182:185], v[244:247], v[74:77]
	v_mfma_f32_16x16x32_bf16 v[74:77], v[186:189], v[248:251], v[74:77]
	v_mfma_f32_16x16x32_bf16 v[66:69], v[190:193], v[244:247], v[66:69]
	v_mfma_f32_16x16x32_bf16 v[66:69], v[194:197], v[248:251], v[66:69]
	v_mfma_f32_16x16x32_bf16 v[70:73], v[174:177], v[244:247], v[70:73]
	v_mfma_f32_16x16x32_bf16 v[70:73], v[178:181], v[248:251], v[70:73]
	v_mfma_f32_16x16x32_bf16 v[78:81], v[142:145], v[244:247], v[78:81]
	v_mfma_f32_16x16x32_bf16 v[78:81], v[170:173], v[248:251], v[78:81]
	s_barrier
	s_setprio 0
	s_or_b32 s53, s52, 0x80
	s_mov_b32 m0, s31
	ds_read_b128 v[198:201], v138 offset:49152
	buffer_load_dwordx4 v133, s[40:43], s53 offen lds
	s_add_i32 s52, s52, 0x80080
	s_mov_b32 m0, s33
	ds_read_b128 v[202:205], v138 offset:50176
	buffer_load_dwordx4 v135, s[40:43], s53 offen lds
	s_mov_b32 m0, s68
	ds_read_b128 v[228:231], v138 offset:51200
	buffer_load_dwordx4 v133, s[40:43], s52 offen lds
	s_mov_b32 m0, s69
	ds_read_b128 v[232:235], v138 offset:52224
	buffer_load_dwordx4 v135, s[40:43], s52 offen lds
	s_mov_b32 m0, s36
	ds_read_b128 v[236:239], v138 offset:53248
	buffer_load_dwordx4 v132, s[60:63], vcc_hi offen lds
	s_mov_b32 m0, s37
	ds_read_b128 v[240:243], v138 offset:54272
	buffer_load_dwordx4 v134, s[60:63], vcc_hi offen lds
	ds_read_b128 v[244:247], v138 offset:55296
	ds_read_b128 v[248:251], v138 offset:56320
	s_waitcnt vmcnt(8)
	s_waitcnt lgkmcnt(0)
	s_setprio 1
	s_barrier
	v_mfma_f32_16x16x32_bf16 v[62:65], v[142:145], v[198:201], v[62:65]
	v_mfma_f32_16x16x32_bf16 v[62:65], v[170:173], v[202:205], v[62:65]
	v_mfma_f32_16x16x32_bf16 v[54:57], v[174:177], v[198:201], v[54:57]
	v_mfma_f32_16x16x32_bf16 v[54:57], v[178:181], v[202:205], v[54:57]
	v_mfma_f32_16x16x32_bf16 v[50:53], v[190:193], v[198:201], v[50:53]
	v_mfma_f32_16x16x32_bf16 v[50:53], v[194:197], v[202:205], v[50:53]
	v_mfma_f32_16x16x32_bf16 v[58:61], v[182:185], v[198:201], v[58:61]
	v_mfma_f32_16x16x32_bf16 v[58:61], v[186:189], v[202:205], v[58:61]
	v_mfma_f32_16x16x32_bf16 v[42:45], v[182:185], v[228:231], v[42:45]
	v_mfma_f32_16x16x32_bf16 v[42:45], v[186:189], v[232:235], v[42:45]
	v_mfma_f32_16x16x32_bf16 v[34:37], v[190:193], v[228:231], v[34:37]
	v_mfma_f32_16x16x32_bf16 v[34:37], v[194:197], v[232:235], v[34:37]
	v_mfma_f32_16x16x32_bf16 v[38:41], v[174:177], v[228:231], v[38:41]
	v_mfma_f32_16x16x32_bf16 v[38:41], v[178:181], v[232:235], v[38:41]
	v_mfma_f32_16x16x32_bf16 v[46:49], v[142:145], v[228:231], v[46:49]
	v_mfma_f32_16x16x32_bf16 v[46:49], v[170:173], v[232:235], v[46:49]
	v_mfma_f32_16x16x32_bf16 v[30:33], v[142:145], v[236:239], v[30:33]
	v_mfma_f32_16x16x32_bf16 v[30:33], v[170:173], v[240:243], v[30:33]
	v_mfma_f32_16x16x32_bf16 v[22:25], v[174:177], v[236:239], v[22:25]
	v_mfma_f32_16x16x32_bf16 v[22:25], v[178:181], v[240:243], v[22:25]
	v_mfma_f32_16x16x32_bf16 v[18:21], v[190:193], v[236:239], v[18:21]
	v_mfma_f32_16x16x32_bf16 v[18:21], v[194:197], v[240:243], v[18:21]
	v_mfma_f32_16x16x32_bf16 v[26:29], v[182:185], v[236:239], v[26:29]
	v_mfma_f32_16x16x32_bf16 v[26:29], v[186:189], v[240:243], v[26:29]
	v_mfma_f32_16x16x32_bf16 v[10:13], v[182:185], v[244:247], v[10:13]
	v_mfma_f32_16x16x32_bf16 v[10:13], v[186:189], v[248:251], v[10:13]
	v_mfma_f32_16x16x32_bf16 v[2:5], v[190:193], v[244:247], v[2:5]
	v_mfma_f32_16x16x32_bf16 v[2:5], v[194:197], v[248:251], v[2:5]
	v_mfma_f32_16x16x32_bf16 v[6:9], v[174:177], v[244:247], v[6:9]
	v_mfma_f32_16x16x32_bf16 v[6:9], v[178:181], v[248:251], v[6:9]
	v_mfma_f32_16x16x32_bf16 v[14:17], v[142:145], v[244:247], v[14:17]
	v_mfma_f32_16x16x32_bf16 v[14:17], v[170:173], v[248:251], v[14:17]
	s_barrier
	s_setprio 0
	s_add_i32 vcc_lo, vcc_lo, 2
	s_addk_i32 s94, 0x100
	s_addk_i32 s95, 0x100
	s_cmp_gt_u32 vcc_lo, 29
	s_cbranch_scc0 .LBB0_304
	s_and_b64 vcc, exec, s[48:49]
	s_cbranch_vccz .LBB0_307
	s_barrier
	s_setprio 2

.LBB0_576:
	s_setprio 0
	s_andn2_b64 vcc, exec, s[8:9]
	s_mov_b32 s2, s71
	s_mov_b32 s12, s72
	s_mov_b32 s13, s84
	s_mov_b32 s21, s73
	s_cbranch_vccz .LBB0_588

.LBB0_580:
	v_add_u32_e32 v154, 0x10000, v140
	ds_read_b128 v[132:135], v154
	ds_read_b128 v[142:145], v154 offset:1024
	ds_read_b128 v[170:173], v154 offset:2048
	ds_read_b128 v[174:177], v154 offset:3072
	v_add_u32_e32 v154, 0x14000, v140
	ds_read_b128 v[178:181], v154
	ds_read_b128 v[182:185], v154 offset:1024
	ds_read_b128 v[186:189], v154 offset:2048
	ds_read_b128 v[190:193], v154 offset:3072
	s_add_i32 s23, s21, 0x4000
	s_cmpk_eq_i32 s22, 0x54
	s_cselect_b32 s27, s8, s23
	s_cselect_b32 s26, s9, s13
	s_or_b32 s23, s27, 0x8000
	s_mov_b32 m0, s68
	ds_read_b128 v[194:197], v141
	ds_read_b128 v[198:201], v141 offset:1024
	ds_read_b128 v[202:205], v141 offset:2048
	ds_read_b128 v[228:231], v141 offset:3072
	ds_read_b128 v[232:235], v141 offset:4096
	ds_read_b128 v[236:239], v141 offset:5120
	ds_read_b128 v[240:243], v141 offset:6144
	ds_read_b128 v[244:247], v141 offset:7168
	buffer_load_dwordx4 v136, s[60:63], s21 offen lds
	s_mov_b32 m0, s70
	s_nop 0
	buffer_load_dwordx4 v138, s[60:63], s21 offen lds
	s_waitcnt vmcnt(8)
	s_waitcnt lgkmcnt(0)
	s_setprio 1
	s_barrier
	v_mfma_f32_16x16x32_bf16 v[126:129], v[132:135], v[194:197], v[126:129]
	v_mfma_f32_16x16x32_bf16 v[126:129], v[142:145], v[198:201], v[126:129]
	v_mfma_f32_16x16x32_bf16 v[106:109], v[170:173], v[194:197], v[106:109]
	v_mfma_f32_16x16x32_bf16 v[106:109], v[174:177], v[198:201], v[106:109]
	v_mfma_f32_16x16x32_bf16 v[110:113], v[186:189], v[194:197], v[110:113]
	v_mfma_f32_16x16x32_bf16 v[110:113], v[190:193], v[198:201], v[110:113]
	v_mfma_f32_16x16x32_bf16 v[122:125], v[178:181], v[194:197], v[122:125]
	v_mfma_f32_16x16x32_bf16 v[122:125], v[182:185], v[198:201], v[122:125]
	v_mfma_f32_16x16x32_bf16 v[102:105], v[178:181], v[202:205], v[102:105]
	v_mfma_f32_16x16x32_bf16 v[102:105], v[182:185], v[228:231], v[102:105]
	v_mfma_f32_16x16x32_bf16 v[98:101], v[186:189], v[202:205], v[98:101]
	v_mfma_f32_16x16x32_bf16 v[98:101], v[190:193], v[228:231], v[98:101]
	v_mfma_f32_16x16x32_bf16 v[114:117], v[170:173], v[202:205], v[114:117]
	v_mfma_f32_16x16x32_bf16 v[114:117], v[174:177], v[228:231], v[114:117]
	v_mfma_f32_16x16x32_bf16 v[118:121], v[132:135], v[202:205], v[118:121]
	v_mfma_f32_16x16x32_bf16 v[118:121], v[142:145], v[228:231], v[118:121]
	v_mfma_f32_16x16x32_bf16 v[94:97], v[132:135], v[232:235], v[94:97]
	v_mfma_f32_16x16x32_bf16 v[94:97], v[142:145], v[236:239], v[94:97]
	v_mfma_f32_16x16x32_bf16 v[90:93], v[170:173], v[232:235], v[90:93]
	v_mfma_f32_16x16x32_bf16 v[90:93], v[174:177], v[236:239], v[90:93]
	v_mfma_f32_16x16x32_bf16 v[82:85], v[186:189], v[232:235], v[82:85]
	v_mfma_f32_16x16x32_bf16 v[82:85], v[190:193], v[236:239], v[82:85]
	v_mfma_f32_16x16x32_bf16 v[86:89], v[178:181], v[232:235], v[86:89]
	v_mfma_f32_16x16x32_bf16 v[86:89], v[182:185], v[236:239], v[86:89]
	v_mfma_f32_16x16x32_bf16 v[70:73], v[178:181], v[240:243], v[70:73]
	v_mfma_f32_16x16x32_bf16 v[70:73], v[182:185], v[244:247], v[70:73]
	v_mfma_f32_16x16x32_bf16 v[66:69], v[186:189], v[240:243], v[66:69]
	v_mfma_f32_16x16x32_bf16 v[66:69], v[190:193], v[244:247], v[66:69]
	v_mfma_f32_16x16x32_bf16 v[74:77], v[170:173], v[240:243], v[74:77]
	v_mfma_f32_16x16x32_bf16 v[74:77], v[174:177], v[244:247], v[74:77]
	v_mfma_f32_16x16x32_bf16 v[78:81], v[132:135], v[240:243], v[78:81]
	v_mfma_f32_16x16x32_bf16 v[78:81], v[142:145], v[244:247], v[78:81]
	s_barrier
	s_setprio 0
	s_mov_b32 s46, s62
	s_mov_b32 s47, s63
	s_mov_b32 m0, s15
	ds_read_b128 v[194:197], v141 offset:16384
	buffer_load_dwordx4 v137, s[44:47], s26 offen lds
	s_add_i32 s52, s26, 0x160000
	s_mov_b32 m0, s16
	ds_read_b128 v[198:201], v141 offset:17408
	buffer_load_dwordx4 v139, s[44:47], s26 offen lds
	s_mov_b32 m0, s18
	ds_read_b128 v[202:205], v141 offset:18432
	buffer_load_dwordx4 v137, s[44:47], s52 offen lds
	s_mov_b32 m0, s19
	ds_read_b128 v[228:231], v141 offset:19456
	buffer_load_dwordx4 v139, s[44:47], s52 offen lds
	s_mov_b32 m0, s14
	ds_read_b128 v[232:235], v141 offset:20480
	buffer_load_dwordx4 v136, s[60:63], s27 offen lds
	s_mov_b32 m0, s24
	ds_read_b128 v[236:239], v141 offset:21504
	buffer_load_dwordx4 v138, s[60:63], s27 offen lds
	ds_read_b128 v[240:243], v141 offset:22528
	ds_read_b128 v[244:247], v141 offset:23552
	s_waitcnt vmcnt(8)
	s_waitcnt lgkmcnt(0)
	s_setprio 1
	s_barrier
	v_mfma_f32_16x16x32_bf16 v[62:65], v[132:135], v[194:197], v[62:65]
	v_mfma_f32_16x16x32_bf16 v[62:65], v[142:145], v[198:201], v[62:65]
	v_mfma_f32_16x16x32_bf16 v[58:61], v[170:173], v[194:197], v[58:61]
	v_mfma_f32_16x16x32_bf16 v[58:61], v[174:177], v[198:201], v[58:61]
	v_mfma_f32_16x16x32_bf16 v[50:53], v[186:189], v[194:197], v[50:53]
	v_mfma_f32_16x16x32_bf16 v[50:53], v[190:193], v[198:201], v[50:53]
	v_mfma_f32_16x16x32_bf16 v[54:57], v[178:181], v[194:197], v[54:57]
	v_mfma_f32_16x16x32_bf16 v[54:57], v[182:185], v[198:201], v[54:57]
	v_mfma_f32_16x16x32_bf16 v[38:41], v[178:181], v[202:205], v[38:41]
	v_mfma_f32_16x16x32_bf16 v[38:41], v[182:185], v[228:231], v[38:41]
	v_mfma_f32_16x16x32_bf16 v[34:37], v[186:189], v[202:205], v[34:37]
	v_mfma_f32_16x16x32_bf16 v[34:37], v[190:193], v[228:231], v[34:37]
	v_mfma_f32_16x16x32_bf16 v[42:45], v[170:173], v[202:205], v[42:45]
	v_mfma_f32_16x16x32_bf16 v[42:45], v[174:177], v[228:231], v[42:45]
	v_mfma_f32_16x16x32_bf16 v[46:49], v[132:135], v[202:205], v[46:49]
	v_mfma_f32_16x16x32_bf16 v[46:49], v[142:145], v[228:231], v[46:49]
	v_mfma_f32_16x16x32_bf16 v[30:33], v[132:135], v[232:235], v[30:33]
	v_mfma_f32_16x16x32_bf16 v[30:33], v[142:145], v[236:239], v[30:33]
	v_mfma_f32_16x16x32_bf16 v[26:29], v[170:173], v[232:235], v[26:29]
	v_mfma_f32_16x16x32_bf16 v[26:29], v[174:177], v[236:239], v[26:29]
	v_mfma_f32_16x16x32_bf16 v[18:21], v[186:189], v[232:235], v[18:21]
	v_mfma_f32_16x16x32_bf16 v[18:21], v[190:193], v[236:239], v[18:21]
	v_mfma_f32_16x16x32_bf16 v[22:25], v[178:181], v[232:235], v[22:25]
	v_mfma_f32_16x16x32_bf16 v[22:25], v[182:185], v[236:239], v[22:25]
	v_mfma_f32_16x16x32_bf16 v[6:9], v[178:181], v[240:243], v[6:9]
	v_mfma_f32_16x16x32_bf16 v[6:9], v[182:185], v[244:247], v[6:9]
	v_mfma_f32_16x16x32_bf16 v[2:5], v[186:189], v[240:243], v[2:5]
	v_mfma_f32_16x16x32_bf16 v[2:5], v[190:193], v[244:247], v[2:5]
	v_mfma_f32_16x16x32_bf16 v[10:13], v[170:173], v[240:243], v[10:13]
	v_mfma_f32_16x16x32_bf16 v[10:13], v[174:177], v[244:247], v[10:13]
	v_mfma_f32_16x16x32_bf16 v[14:17], v[132:135], v[240:243], v[14:17]
	v_mfma_f32_16x16x32_bf16 v[14:17], v[142:145], v[244:247], v[14:17]
	s_barrier
	s_setprio 0
	v_add_u32_e32 v154, 0x18000, v140
	ds_read_b128 v[132:135], v154
	ds_read_b128 v[142:145], v154 offset:1024
	ds_read_b128 v[170:173], v154 offset:2048
	ds_read_b128 v[174:177], v154 offset:3072
	v_add_u32_e32 v154, 0x1c000, v140
	ds_read_b128 v[178:181], v154
	ds_read_b128 v[182:185], v154 offset:1024
	ds_read_b128 v[186:189], v154 offset:2048
	ds_read_b128 v[190:193], v154 offset:3072
	s_bitset1_b32 s27, 14
	s_mov_b32 m0, s25
	ds_read_b128 v[194:197], v141 offset:32768
	ds_read_b128 v[198:201], v141 offset:33792
	ds_read_b128 v[202:205], v141 offset:34816
	ds_read_b128 v[228:231], v141 offset:35840
	ds_read_b128 v[232:235], v141 offset:36864
	ds_read_b128 v[236:239], v141 offset:37888
	ds_read_b128 v[240:243], v141 offset:38912
	ds_read_b128 v[244:247], v141 offset:39936
	buffer_load_dwordx4 v136, s[60:63], s27 offen lds
	s_mov_b32 m0, s30
	s_nop 0
	buffer_load_dwordx4 v138, s[60:63], s27 offen lds
	s_waitcnt vmcnt(8)
	s_waitcnt lgkmcnt(0)
	s_setprio 1
	s_barrier
	v_mfma_f32_16x16x32_bf16 v[126:129], v[132:135], v[194:197], v[126:129]
	v_mfma_f32_16x16x32_bf16 v[126:129], v[142:145], v[198:201], v[126:129]
	v_mfma_f32_16x16x32_bf16 v[106:109], v[170:173], v[194:197], v[106:109]
	v_mfma_f32_16x16x32_bf16 v[106:109], v[174:177], v[198:201], v[106:109]
	v_mfma_f32_16x16x32_bf16 v[110:113], v[186:189], v[194:197], v[110:113]
	v_mfma_f32_16x16x32_bf16 v[110:113], v[190:193], v[198:201], v[110:113]
	v_mfma_f32_16x16x32_bf16 v[122:125], v[178:181], v[194:197], v[122:125]
	v_mfma_f32_16x16x32_bf16 v[122:125], v[182:185], v[198:201], v[122:125]
	v_mfma_f32_16x16x32_bf16 v[102:105], v[178:181], v[202:205], v[102:105]
	v_mfma_f32_16x16x32_bf16 v[102:105], v[182:185], v[228:231], v[102:105]
	v_mfma_f32_16x16x32_bf16 v[98:101], v[186:189], v[202:205], v[98:101]
	v_mfma_f32_16x16x32_bf16 v[98:101], v[190:193], v[228:231], v[98:101]
	v_mfma_f32_16x16x32_bf16 v[114:117], v[170:173], v[202:205], v[114:117]
	v_mfma_f32_16x16x32_bf16 v[114:117], v[174:177], v[228:231], v[114:117]
	v_mfma_f32_16x16x32_bf16 v[118:121], v[132:135], v[202:205], v[118:121]
	v_mfma_f32_16x16x32_bf16 v[118:121], v[142:145], v[228:231], v[118:121]
	v_mfma_f32_16x16x32_bf16 v[94:97], v[132:135], v[232:235], v[94:97]
	v_mfma_f32_16x16x32_bf16 v[94:97], v[142:145], v[236:239], v[94:97]
	v_mfma_f32_16x16x32_bf16 v[90:93], v[170:173], v[232:235], v[90:93]
	v_mfma_f32_16x16x32_bf16 v[90:93], v[174:177], v[236:239], v[90:93]
	v_mfma_f32_16x16x32_bf16 v[82:85], v[186:189], v[232:235], v[82:85]
	v_mfma_f32_16x16x32_bf16 v[82:85], v[190:193], v[236:239], v[82:85]
	v_mfma_f32_16x16x32_bf16 v[86:89], v[178:181], v[232:235], v[86:89]
	v_mfma_f32_16x16x32_bf16 v[86:89], v[182:185], v[236:239], v[86:89]
	v_mfma_f32_16x16x32_bf16 v[70:73], v[178:181], v[240:243], v[70:73]
	v_mfma_f32_16x16x32_bf16 v[70:73], v[182:185], v[244:247], v[70:73]
	v_mfma_f32_16x16x32_bf16 v[66:69], v[186:189], v[240:243], v[66:69]
	v_mfma_f32_16x16x32_bf16 v[66:69], v[190:193], v[244:247], v[66:69]
	v_mfma_f32_16x16x32_bf16 v[74:77], v[170:173], v[240:243], v[74:77]
	v_mfma_f32_16x16x32_bf16 v[74:77], v[174:177], v[244:247], v[74:77]
	v_mfma_f32_16x16x32_bf16 v[78:81], v[132:135], v[240:243], v[78:81]
	v_mfma_f32_16x16x32_bf16 v[78:81], v[142:145], v[244:247], v[78:81]
	s_barrier
	s_setprio 0
	s_or_b32 s27, s26, 0x80
	s_mov_b32 m0, s36
	ds_read_b128 v[194:197], v141 offset:49152
	buffer_load_dwordx4 v137, s[44:47], s27 offen lds
	s_add_i32 s26, s26, 0x160080
	s_mov_b32 m0, s37
	ds_read_b128 v[198:201], v141 offset:50176
	buffer_load_dwordx4 v139, s[44:47], s27 offen lds
	s_mov_b32 m0, s66
	ds_read_b128 v[202:205], v141 offset:51200
	buffer_load_dwordx4 v137, s[44:47], s26 offen lds
	s_mov_b32 m0, s67
	ds_read_b128 v[228:231], v141 offset:52224
	buffer_load_dwordx4 v139, s[44:47], s26 offen lds
	s_mov_b32 m0, s48
	ds_read_b128 v[232:235], v141 offset:53248
	buffer_load_dwordx4 v136, s[60:63], s23 offen lds
	s_mov_b32 m0, s49
	ds_read_b128 v[236:239], v141 offset:54272
	buffer_load_dwordx4 v138, s[60:63], s23 offen lds
	ds_read_b128 v[240:243], v141 offset:55296
	ds_read_b128 v[244:247], v141 offset:56320
	s_waitcnt vmcnt(8)
	s_waitcnt lgkmcnt(0)
	s_setprio 1
	s_barrier
	v_mfma_f32_16x16x32_bf16 v[62:65], v[132:135], v[194:197], v[62:65]
	v_mfma_f32_16x16x32_bf16 v[62:65], v[142:145], v[198:201], v[62:65]
	v_mfma_f32_16x16x32_bf16 v[58:61], v[170:173], v[194:197], v[58:61]
	v_mfma_f32_16x16x32_bf16 v[58:61], v[174:177], v[198:201], v[58:61]
	v_mfma_f32_16x16x32_bf16 v[50:53], v[186:189], v[194:197], v[50:53]
	v_mfma_f32_16x16x32_bf16 v[50:53], v[190:193], v[198:201], v[50:53]
	v_mfma_f32_16x16x32_bf16 v[54:57], v[178:181], v[194:197], v[54:57]
	v_mfma_f32_16x16x32_bf16 v[54:57], v[182:185], v[198:201], v[54:57]
	v_mfma_f32_16x16x32_bf16 v[38:41], v[178:181], v[202:205], v[38:41]
	v_mfma_f32_16x16x32_bf16 v[38:41], v[182:185], v[228:231], v[38:41]
	v_mfma_f32_16x16x32_bf16 v[34:37], v[186:189], v[202:205], v[34:37]
	v_mfma_f32_16x16x32_bf16 v[34:37], v[190:193], v[228:231], v[34:37]
	v_mfma_f32_16x16x32_bf16 v[42:45], v[170:173], v[202:205], v[42:45]
	v_mfma_f32_16x16x32_bf16 v[42:45], v[174:177], v[228:231], v[42:45]
	v_mfma_f32_16x16x32_bf16 v[46:49], v[132:135], v[202:205], v[46:49]
	v_mfma_f32_16x16x32_bf16 v[46:49], v[142:145], v[228:231], v[46:49]
	v_mfma_f32_16x16x32_bf16 v[30:33], v[132:135], v[232:235], v[30:33]
	v_mfma_f32_16x16x32_bf16 v[30:33], v[142:145], v[236:239], v[30:33]
	v_mfma_f32_16x16x32_bf16 v[26:29], v[170:173], v[232:235], v[26:29]
	v_mfma_f32_16x16x32_bf16 v[26:29], v[174:177], v[236:239], v[26:29]
	v_mfma_f32_16x16x32_bf16 v[18:21], v[186:189], v[232:235], v[18:21]
	v_mfma_f32_16x16x32_bf16 v[18:21], v[190:193], v[236:239], v[18:21]
	v_mfma_f32_16x16x32_bf16 v[22:25], v[178:181], v[232:235], v[22:25]
	v_mfma_f32_16x16x32_bf16 v[22:25], v[182:185], v[236:239], v[22:25]
	v_mfma_f32_16x16x32_bf16 v[6:9], v[178:181], v[240:243], v[6:9]
	v_mfma_f32_16x16x32_bf16 v[6:9], v[182:185], v[244:247], v[6:9]
	v_mfma_f32_16x16x32_bf16 v[2:5], v[186:189], v[240:243], v[2:5]
	v_mfma_f32_16x16x32_bf16 v[2:5], v[190:193], v[244:247], v[2:5]
	v_mfma_f32_16x16x32_bf16 v[10:13], v[170:173], v[240:243], v[10:13]
	v_mfma_f32_16x16x32_bf16 v[10:13], v[174:177], v[244:247], v[10:13]
	v_mfma_f32_16x16x32_bf16 v[14:17], v[132:135], v[240:243], v[14:17]
	v_mfma_f32_16x16x32_bf16 v[14:17], v[142:145], v[244:247], v[14:17]
	s_barrier
	s_setprio 0
	s_addk_i32 s13, 0x100
	s_add_i32 s22, s22, 2
	s_add_i32 s21, s21, 0x10000
	s_cmpk_gt_u32 s22, 0x55
	s_cbranch_scc0 .LBB0_580
	s_and_b64 vcc, exec, s[64:65]
	s_cbranch_vccz .LBB0_583
	s_barrier
	s_setprio 2

.LBB0_855:
	s_setprio 0
	s_andn2_b64 vcc, exec, s[8:9]
	s_mov_b32 s12, s71
	s_mov_b32 s16, s21
	s_mov_b32 s19, s82
	s_mov_b32 s18, s2
	s_cbranch_vccz .LBB0_869

.LBB0_859:
	v_add_u32_e32 v146, 0x10000, v195
	ds_read_b128 v[130:133], v146
	ds_read_b128 v[138:141], v146 offset:1024
	ds_read_b128 v[142:145], v146 offset:2048
	ds_read_b128 v[154:157], v146 offset:3072
	v_add_u32_e32 v146, 0x14000, v195
	ds_read_b128 v[170:173], v146
	ds_read_b128 v[174:177], v146 offset:1024
	ds_read_b128 v[178:181], v146 offset:2048
	ds_read_b128 v[182:185], v146 offset:3072
	s_add_i32 s26, s18, 0xfff80080
	s_cmp_eq_u32 s22, 28
	s_cselect_b32 s52, s8, s26
	s_cselect_b32 s27, s9, s19
	s_or_b32 s26, s52, 0x80
	s_mov_b32 m0, s85
	ds_read_b128 v[186:189], v196
	ds_read_b128 v[198:201], v196 offset:1024
	ds_read_b128 v[202:205], v196 offset:2048
	ds_read_b128 v[228:231], v196 offset:3072
	ds_read_b128 v[232:235], v196 offset:4096
	ds_read_b128 v[236:239], v196 offset:5120
	ds_read_b128 v[240:243], v196 offset:6144
	ds_read_b128 v[244:247], v196 offset:7168
	buffer_load_dwordx4 v135, s[44:47], s18 offen lds
	s_mov_b32 m0, s15
	s_nop 0
	buffer_load_dwordx4 v193, s[44:47], s18 offen lds
	s_waitcnt vmcnt(8)
	s_waitcnt lgkmcnt(0)
	s_setprio 1
	s_barrier
	v_mfma_f32_16x16x32_bf16 v[126:129], v[130:133], v[186:189], v[126:129]
	v_mfma_f32_16x16x32_bf16 v[126:129], v[138:141], v[198:201], v[126:129]
	v_mfma_f32_16x16x32_bf16 v[122:125], v[142:145], v[186:189], v[122:125]
	v_mfma_f32_16x16x32_bf16 v[122:125], v[154:157], v[198:201], v[122:125]
	v_mfma_f32_16x16x32_bf16 v[114:117], v[178:181], v[186:189], v[114:117]
	v_mfma_f32_16x16x32_bf16 v[114:117], v[182:185], v[198:201], v[114:117]
	v_mfma_f32_16x16x32_bf16 v[118:121], v[170:173], v[186:189], v[118:121]
	v_mfma_f32_16x16x32_bf16 v[118:121], v[174:177], v[198:201], v[118:121]
	v_mfma_f32_16x16x32_bf16 v[102:105], v[170:173], v[202:205], v[102:105]
	v_mfma_f32_16x16x32_bf16 v[102:105], v[174:177], v[228:231], v[102:105]
	v_mfma_f32_16x16x32_bf16 v[98:101], v[178:181], v[202:205], v[98:101]
	v_mfma_f32_16x16x32_bf16 v[98:101], v[182:185], v[228:231], v[98:101]
	v_mfma_f32_16x16x32_bf16 v[106:109], v[142:145], v[202:205], v[106:109]
	v_mfma_f32_16x16x32_bf16 v[106:109], v[154:157], v[228:231], v[106:109]
	v_mfma_f32_16x16x32_bf16 v[110:113], v[130:133], v[202:205], v[110:113]
	v_mfma_f32_16x16x32_bf16 v[110:113], v[138:141], v[228:231], v[110:113]
	v_mfma_f32_16x16x32_bf16 v[94:97], v[130:133], v[232:235], v[94:97]
	v_mfma_f32_16x16x32_bf16 v[94:97], v[138:141], v[236:239], v[94:97]
	v_mfma_f32_16x16x32_bf16 v[90:93], v[142:145], v[232:235], v[90:93]
	v_mfma_f32_16x16x32_bf16 v[90:93], v[154:157], v[236:239], v[90:93]
	v_mfma_f32_16x16x32_bf16 v[82:85], v[178:181], v[232:235], v[82:85]
	v_mfma_f32_16x16x32_bf16 v[82:85], v[182:185], v[236:239], v[82:85]
	v_mfma_f32_16x16x32_bf16 v[86:89], v[170:173], v[232:235], v[86:89]
	v_mfma_f32_16x16x32_bf16 v[86:89], v[174:177], v[236:239], v[86:89]
	v_mfma_f32_16x16x32_bf16 v[70:73], v[170:173], v[240:243], v[70:73]
	v_mfma_f32_16x16x32_bf16 v[70:73], v[174:177], v[244:247], v[70:73]
	v_mfma_f32_16x16x32_bf16 v[66:69], v[178:181], v[240:243], v[66:69]
	v_mfma_f32_16x16x32_bf16 v[66:69], v[182:185], v[244:247], v[66:69]
	v_mfma_f32_16x16x32_bf16 v[74:77], v[142:145], v[240:243], v[74:77]
	v_mfma_f32_16x16x32_bf16 v[74:77], v[154:157], v[244:247], v[74:77]
	v_mfma_f32_16x16x32_bf16 v[78:81], v[130:133], v[240:243], v[78:81]
	v_mfma_f32_16x16x32_bf16 v[78:81], v[138:141], v[244:247], v[78:81]
	s_barrier
	s_setprio 0
	s_mov_b32 s66, s46
	s_mov_b32 s67, s47
	s_mov_b32 m0, s23
	ds_read_b128 v[186:189], v196 offset:16384
	buffer_load_dwordx4 v192, s[64:67], s27 offen lds
	s_add_i32 s53, s27, 0x80000
	s_mov_b32 m0, s24
	ds_read_b128 v[198:201], v196 offset:17408
	buffer_load_dwordx4 v194, s[64:67], s27 offen lds
	s_mov_b32 m0, s25
	ds_read_b128 v[202:205], v196 offset:18432
	buffer_load_dwordx4 v192, s[64:67], s53 offen lds
	s_mov_b32 m0, s33
	ds_read_b128 v[228:231], v196 offset:19456
	buffer_load_dwordx4 v194, s[64:67], s53 offen lds
	s_mov_b32 m0, s13
	ds_read_b128 v[232:235], v196 offset:20480
	buffer_load_dwordx4 v135, s[44:47], s52 offen lds
	s_mov_b32 m0, s34
	ds_read_b128 v[236:239], v196 offset:21504
	buffer_load_dwordx4 v193, s[44:47], s52 offen lds
	ds_read_b128 v[240:243], v196 offset:22528
	ds_read_b128 v[244:247], v196 offset:23552
	s_waitcnt vmcnt(8)
	s_waitcnt lgkmcnt(0)
	s_setprio 1
	s_barrier
	v_mfma_f32_16x16x32_bf16 v[62:65], v[130:133], v[186:189], v[62:65]
	v_mfma_f32_16x16x32_bf16 v[62:65], v[138:141], v[198:201], v[62:65]
	v_mfma_f32_16x16x32_bf16 v[58:61], v[142:145], v[186:189], v[58:61]
	v_mfma_f32_16x16x32_bf16 v[58:61], v[154:157], v[198:201], v[58:61]
	v_mfma_f32_16x16x32_bf16 v[50:53], v[178:181], v[186:189], v[50:53]
	v_mfma_f32_16x16x32_bf16 v[50:53], v[182:185], v[198:201], v[50:53]
	v_mfma_f32_16x16x32_bf16 v[54:57], v[170:173], v[186:189], v[54:57]
	v_mfma_f32_16x16x32_bf16 v[54:57], v[174:177], v[198:201], v[54:57]
	v_mfma_f32_16x16x32_bf16 v[38:41], v[170:173], v[202:205], v[38:41]
	v_mfma_f32_16x16x32_bf16 v[38:41], v[174:177], v[228:231], v[38:41]
	v_mfma_f32_16x16x32_bf16 v[34:37], v[178:181], v[202:205], v[34:37]
	v_mfma_f32_16x16x32_bf16 v[34:37], v[182:185], v[228:231], v[34:37]
	v_mfma_f32_16x16x32_bf16 v[42:45], v[142:145], v[202:205], v[42:45]
	v_mfma_f32_16x16x32_bf16 v[42:45], v[154:157], v[228:231], v[42:45]
	v_mfma_f32_16x16x32_bf16 v[46:49], v[130:133], v[202:205], v[46:49]
	v_mfma_f32_16x16x32_bf16 v[46:49], v[138:141], v[228:231], v[46:49]
	v_mfma_f32_16x16x32_bf16 v[30:33], v[130:133], v[232:235], v[30:33]
	v_mfma_f32_16x16x32_bf16 v[30:33], v[138:141], v[236:239], v[30:33]
	v_mfma_f32_16x16x32_bf16 v[26:29], v[142:145], v[232:235], v[26:29]
	v_mfma_f32_16x16x32_bf16 v[26:29], v[154:157], v[236:239], v[26:29]
	v_mfma_f32_16x16x32_bf16 v[18:21], v[178:181], v[232:235], v[18:21]
	v_mfma_f32_16x16x32_bf16 v[18:21], v[182:185], v[236:239], v[18:21]
	v_mfma_f32_16x16x32_bf16 v[22:25], v[170:173], v[232:235], v[22:25]
	v_mfma_f32_16x16x32_bf16 v[22:25], v[174:177], v[236:239], v[22:25]
	v_mfma_f32_16x16x32_bf16 v[6:9], v[170:173], v[240:243], v[6:9]
	v_mfma_f32_16x16x32_bf16 v[6:9], v[174:177], v[244:247], v[6:9]
	v_mfma_f32_16x16x32_bf16 v[2:5], v[178:181], v[240:243], v[2:5]
	v_mfma_f32_16x16x32_bf16 v[2:5], v[182:185], v[244:247], v[2:5]
	v_mfma_f32_16x16x32_bf16 v[10:13], v[142:145], v[240:243], v[10:13]
	v_mfma_f32_16x16x32_bf16 v[10:13], v[154:157], v[244:247], v[10:13]
	v_mfma_f32_16x16x32_bf16 v[14:17], v[130:133], v[240:243], v[14:17]
	v_mfma_f32_16x16x32_bf16 v[14:17], v[138:141], v[244:247], v[14:17]
	s_barrier
	s_setprio 0
	v_add_u32_e32 v146, 0x18000, v195
	ds_read_b128 v[130:133], v146
	ds_read_b128 v[138:141], v146 offset:1024
	ds_read_b128 v[142:145], v146 offset:2048
	ds_read_b128 v[154:157], v146 offset:3072
	v_add_u32_e32 v146, 0x1c000, v195
	ds_read_b128 v[170:173], v146
	ds_read_b128 v[174:177], v146 offset:1024
	ds_read_b128 v[178:181], v146 offset:2048
	ds_read_b128 v[182:185], v146 offset:3072
	s_add_i32 s52, s52, 0x80000
	s_mov_b32 m0, s35
	ds_read_b128 v[186:189], v196 offset:32768
	ds_read_b128 v[198:201], v196 offset:33792
	ds_read_b128 v[202:205], v196 offset:34816
	ds_read_b128 v[228:231], v196 offset:35840
	ds_read_b128 v[232:235], v196 offset:36864
	ds_read_b128 v[236:239], v196 offset:37888
	ds_read_b128 v[240:243], v196 offset:38912
	ds_read_b128 v[244:247], v196 offset:39936
	buffer_load_dwordx4 v135, s[44:47], s52 offen lds
	s_mov_b32 m0, s36
	s_nop 0
	buffer_load_dwordx4 v193, s[44:47], s52 offen lds
	s_waitcnt vmcnt(8)
	s_waitcnt lgkmcnt(0)
	s_setprio 1
	s_barrier
	v_mfma_f32_16x16x32_bf16 v[126:129], v[130:133], v[186:189], v[126:129]
	v_mfma_f32_16x16x32_bf16 v[126:129], v[138:141], v[198:201], v[126:129]
	v_mfma_f32_16x16x32_bf16 v[122:125], v[142:145], v[186:189], v[122:125]
	v_mfma_f32_16x16x32_bf16 v[122:125], v[154:157], v[198:201], v[122:125]
	v_mfma_f32_16x16x32_bf16 v[114:117], v[178:181], v[186:189], v[114:117]
	v_mfma_f32_16x16x32_bf16 v[114:117], v[182:185], v[198:201], v[114:117]
	v_mfma_f32_16x16x32_bf16 v[118:121], v[170:173], v[186:189], v[118:121]
	v_mfma_f32_16x16x32_bf16 v[118:121], v[174:177], v[198:201], v[118:121]
	v_mfma_f32_16x16x32_bf16 v[102:105], v[170:173], v[202:205], v[102:105]
	v_mfma_f32_16x16x32_bf16 v[102:105], v[174:177], v[228:231], v[102:105]
	v_mfma_f32_16x16x32_bf16 v[98:101], v[178:181], v[202:205], v[98:101]
	v_mfma_f32_16x16x32_bf16 v[98:101], v[182:185], v[228:231], v[98:101]
	v_mfma_f32_16x16x32_bf16 v[106:109], v[142:145], v[202:205], v[106:109]
	v_mfma_f32_16x16x32_bf16 v[106:109], v[154:157], v[228:231], v[106:109]
	v_mfma_f32_16x16x32_bf16 v[110:113], v[130:133], v[202:205], v[110:113]
	v_mfma_f32_16x16x32_bf16 v[110:113], v[138:141], v[228:231], v[110:113]
	v_mfma_f32_16x16x32_bf16 v[94:97], v[130:133], v[232:235], v[94:97]
	v_mfma_f32_16x16x32_bf16 v[94:97], v[138:141], v[236:239], v[94:97]
	v_mfma_f32_16x16x32_bf16 v[90:93], v[142:145], v[232:235], v[90:93]
	v_mfma_f32_16x16x32_bf16 v[90:93], v[154:157], v[236:239], v[90:93]
	v_mfma_f32_16x16x32_bf16 v[82:85], v[178:181], v[232:235], v[82:85]
	v_mfma_f32_16x16x32_bf16 v[82:85], v[182:185], v[236:239], v[82:85]
	v_mfma_f32_16x16x32_bf16 v[86:89], v[170:173], v[232:235], v[86:89]
	v_mfma_f32_16x16x32_bf16 v[86:89], v[174:177], v[236:239], v[86:89]
	v_mfma_f32_16x16x32_bf16 v[70:73], v[170:173], v[240:243], v[70:73]
	v_mfma_f32_16x16x32_bf16 v[70:73], v[174:177], v[244:247], v[70:73]
	v_mfma_f32_16x16x32_bf16 v[66:69], v[178:181], v[240:243], v[66:69]
	v_mfma_f32_16x16x32_bf16 v[66:69], v[182:185], v[244:247], v[66:69]
	v_mfma_f32_16x16x32_bf16 v[74:77], v[142:145], v[240:243], v[74:77]
	v_mfma_f32_16x16x32_bf16 v[74:77], v[154:157], v[244:247], v[74:77]
	v_mfma_f32_16x16x32_bf16 v[78:81], v[130:133], v[240:243], v[78:81]
	v_mfma_f32_16x16x32_bf16 v[78:81], v[138:141], v[244:247], v[78:81]
	s_barrier
	s_setprio 0
	s_or_b32 s52, s27, 0x80
	s_mov_b32 m0, s41
	ds_read_b128 v[186:189], v196 offset:49152
	buffer_load_dwordx4 v192, s[64:67], s52 offen lds
	s_add_i32 s27, s27, 0x80080
	s_mov_b32 m0, s48
	ds_read_b128 v[198:201], v196 offset:50176
	buffer_load_dwordx4 v194, s[64:67], s52 offen lds
	s_mov_b32 m0, s69
	ds_read_b128 v[202:205], v196 offset:51200
	buffer_load_dwordx4 v192, s[64:67], s27 offen lds
	s_mov_b32 m0, s72
	ds_read_b128 v[228:231], v196 offset:52224
	buffer_load_dwordx4 v194, s[64:67], s27 offen lds
	s_mov_b32 m0, s49
	ds_read_b128 v[232:235], v196 offset:53248
	buffer_load_dwordx4 v135, s[44:47], s26 offen lds
	s_mov_b32 m0, s68
	ds_read_b128 v[236:239], v196 offset:54272
	buffer_load_dwordx4 v193, s[44:47], s26 offen lds
	ds_read_b128 v[240:243], v196 offset:55296
	ds_read_b128 v[244:247], v196 offset:56320
	s_waitcnt vmcnt(8)
	s_waitcnt lgkmcnt(0)
	s_setprio 1
	s_barrier
	v_mfma_f32_16x16x32_bf16 v[62:65], v[130:133], v[186:189], v[62:65]
	v_mfma_f32_16x16x32_bf16 v[62:65], v[138:141], v[198:201], v[62:65]
	v_mfma_f32_16x16x32_bf16 v[58:61], v[142:145], v[186:189], v[58:61]
	v_mfma_f32_16x16x32_bf16 v[58:61], v[154:157], v[198:201], v[58:61]
	v_mfma_f32_16x16x32_bf16 v[50:53], v[178:181], v[186:189], v[50:53]
	v_mfma_f32_16x16x32_bf16 v[50:53], v[182:185], v[198:201], v[50:53]
	v_mfma_f32_16x16x32_bf16 v[54:57], v[170:173], v[186:189], v[54:57]
	v_mfma_f32_16x16x32_bf16 v[54:57], v[174:177], v[198:201], v[54:57]
	v_mfma_f32_16x16x32_bf16 v[38:41], v[170:173], v[202:205], v[38:41]
	v_mfma_f32_16x16x32_bf16 v[38:41], v[174:177], v[228:231], v[38:41]
	v_mfma_f32_16x16x32_bf16 v[34:37], v[178:181], v[202:205], v[34:37]
	v_mfma_f32_16x16x32_bf16 v[34:37], v[182:185], v[228:231], v[34:37]
	v_mfma_f32_16x16x32_bf16 v[42:45], v[142:145], v[202:205], v[42:45]
	v_mfma_f32_16x16x32_bf16 v[42:45], v[154:157], v[228:231], v[42:45]
	v_mfma_f32_16x16x32_bf16 v[46:49], v[130:133], v[202:205], v[46:49]
	v_mfma_f32_16x16x32_bf16 v[46:49], v[138:141], v[228:231], v[46:49]
	v_mfma_f32_16x16x32_bf16 v[30:33], v[130:133], v[232:235], v[30:33]
	v_mfma_f32_16x16x32_bf16 v[30:33], v[138:141], v[236:239], v[30:33]
	v_mfma_f32_16x16x32_bf16 v[26:29], v[142:145], v[232:235], v[26:29]
	v_mfma_f32_16x16x32_bf16 v[26:29], v[154:157], v[236:239], v[26:29]
	v_mfma_f32_16x16x32_bf16 v[18:21], v[178:181], v[232:235], v[18:21]
	v_mfma_f32_16x16x32_bf16 v[18:21], v[182:185], v[236:239], v[18:21]
	v_mfma_f32_16x16x32_bf16 v[22:25], v[170:173], v[232:235], v[22:25]
	v_mfma_f32_16x16x32_bf16 v[22:25], v[174:177], v[236:239], v[22:25]
	v_mfma_f32_16x16x32_bf16 v[6:9], v[170:173], v[240:243], v[6:9]
	v_mfma_f32_16x16x32_bf16 v[6:9], v[174:177], v[244:247], v[6:9]
	v_mfma_f32_16x16x32_bf16 v[2:5], v[178:181], v[240:243], v[2:5]
	v_mfma_f32_16x16x32_bf16 v[2:5], v[182:185], v[244:247], v[2:5]
	v_mfma_f32_16x16x32_bf16 v[10:13], v[142:145], v[240:243], v[10:13]
	v_mfma_f32_16x16x32_bf16 v[10:13], v[154:157], v[244:247], v[10:13]
	v_mfma_f32_16x16x32_bf16 v[14:17], v[130:133], v[240:243], v[14:17]
	v_mfma_f32_16x16x32_bf16 v[14:17], v[138:141], v[244:247], v[14:17]
	s_barrier
	s_setprio 0
	s_add_i32 s22, s22, 2
	s_addk_i32 s18, 0x100
	s_addk_i32 s19, 0x100
	s_cmp_gt_u32 s22, 29
	s_cbranch_scc0 .LBB0_859
	s_and_b64 vcc, exec, s[60:61]
	s_cbranch_vccz .LBB0_862
	s_barrier
	s_setprio 2

.LBB0_877:
	s_setprio 0
	s_andn2_b64 vcc, exec, s[8:9]
	s_mov_b32 s84, s66
	s_mov_b32 s2, s85
	s_mov_b32 s13, s15
	s_mov_b32 s12, s14
	s_cbranch_vccz .LBB0_895

.LBB0_881:
	v_add_u32_e32 v139, 0x10000, v234
	ds_read_b128 v[130:133], v139
	ds_read_b128 v[140:143], v139 offset:1024
	ds_read_b128 v[170:173], v139 offset:2048
	ds_read_b128 v[174:177], v139 offset:3072
	v_add_u32_e32 v139, 0x14000, v234
	ds_read_b128 v[178:181], v139
	ds_read_b128 v[182:185], v139 offset:1024
	ds_read_b128 v[186:189], v139 offset:2048
	ds_read_b128 v[190:193], v139 offset:3072
	s_add_i32 s21, s12, 0xfff80080
	s_cmp_eq_u32 s16, 28
	s_cselect_b32 s23, s8, s21
	s_cselect_b32 s22, s9, s13
	s_or_b32 s21, s23, 0x80
	s_mov_b32 m0, s72
	ds_read_b128 v[194:197], v235
	ds_read_b128 v[198:201], v235 offset:1024
	ds_read_b128 v[202:205], v235 offset:2048
	ds_read_b128 v[236:239], v235 offset:3072
	ds_read_b128 v[240:243], v235 offset:4096
	ds_read_b128 v[244:247], v235 offset:5120
	ds_read_b128 v[248:251], v235 offset:6144
	ds_read_b128 v[154:157], v235 offset:7168
	buffer_load_dwordx4 v228, s[60:63], s12 offen lds
	s_mov_b32 m0, s73
	s_nop 0
	buffer_load_dwordx4 v230, s[60:63], s12 offen lds
	s_waitcnt vmcnt(8)
	s_waitcnt lgkmcnt(0)
	s_setprio 1
	s_barrier
	v_mfma_f32_16x16x32_bf16 v[126:129], v[130:133], v[194:197], v[126:129]
	v_mfma_f32_16x16x32_bf16 v[126:129], v[140:143], v[198:201], v[126:129]
	v_mfma_f32_16x16x32_bf16 v[122:125], v[170:173], v[194:197], v[122:125]
	v_mfma_f32_16x16x32_bf16 v[122:125], v[174:177], v[198:201], v[122:125]
	v_mfma_f32_16x16x32_bf16 v[110:113], v[186:189], v[194:197], v[110:113]
	v_mfma_f32_16x16x32_bf16 v[110:113], v[190:193], v[198:201], v[110:113]
	v_mfma_f32_16x16x32_bf16 v[118:121], v[178:181], v[194:197], v[118:121]
	v_mfma_f32_16x16x32_bf16 v[118:121], v[182:185], v[198:201], v[118:121]
	v_mfma_f32_16x16x32_bf16 v[102:105], v[178:181], v[202:205], v[102:105]
	v_mfma_f32_16x16x32_bf16 v[102:105], v[182:185], v[236:239], v[102:105]
	v_mfma_f32_16x16x32_bf16 v[94:97], v[186:189], v[202:205], v[94:97]
	v_mfma_f32_16x16x32_bf16 v[94:97], v[190:193], v[236:239], v[94:97]
	v_mfma_f32_16x16x32_bf16 v[106:109], v[170:173], v[202:205], v[106:109]
	v_mfma_f32_16x16x32_bf16 v[106:109], v[174:177], v[236:239], v[106:109]
	v_mfma_f32_16x16x32_bf16 v[114:117], v[130:133], v[202:205], v[114:117]
	v_mfma_f32_16x16x32_bf16 v[114:117], v[140:143], v[236:239], v[114:117]
	v_mfma_f32_16x16x32_bf16 v[98:101], v[130:133], v[240:243], v[98:101]
	v_mfma_f32_16x16x32_bf16 v[98:101], v[140:143], v[244:247], v[98:101]
	v_mfma_f32_16x16x32_bf16 v[90:93], v[170:173], v[240:243], v[90:93]
	v_mfma_f32_16x16x32_bf16 v[90:93], v[174:177], v[244:247], v[90:93]
	v_mfma_f32_16x16x32_bf16 v[78:81], v[186:189], v[240:243], v[78:81]
	v_mfma_f32_16x16x32_bf16 v[78:81], v[190:193], v[244:247], v[78:81]
	v_mfma_f32_16x16x32_bf16 v[86:89], v[178:181], v[240:243], v[86:89]
	v_mfma_f32_16x16x32_bf16 v[86:89], v[182:185], v[244:247], v[86:89]
	v_mfma_f32_16x16x32_bf16 v[70:73], v[178:181], v[248:251], v[70:73]
	v_mfma_f32_16x16x32_bf16 v[70:73], v[182:185], v[154:157], v[70:73]
	v_mfma_f32_16x16x32_bf16 v[66:69], v[186:189], v[248:251], v[66:69]
	v_mfma_f32_16x16x32_bf16 v[66:69], v[190:193], v[154:157], v[66:69]
	v_mfma_f32_16x16x32_bf16 v[74:77], v[170:173], v[248:251], v[74:77]
	v_mfma_f32_16x16x32_bf16 v[74:77], v[174:177], v[154:157], v[74:77]
	v_mfma_f32_16x16x32_bf16 v[82:85], v[130:133], v[248:251], v[82:85]
	v_mfma_f32_16x16x32_bf16 v[82:85], v[140:143], v[154:157], v[82:85]
	s_barrier
	s_setprio 0
	s_mov_b32 s46, s62
	s_mov_b32 s47, s63
	s_mov_b32 m0, s26
	ds_read_b128 v[154:157], v235 offset:16384
	buffer_load_dwordx4 v229, s[44:47], s22 offen lds
	s_add_i32 s38, s22, 0x80000
	s_mov_b32 m0, s27
	ds_read_b128 v[194:197], v235 offset:17408
	buffer_load_dwordx4 v231, s[44:47], s22 offen lds
	s_mov_b32 m0, s34
	ds_read_b128 v[198:201], v235 offset:18432
	buffer_load_dwordx4 v229, s[44:47], s38 offen lds
	s_mov_b32 m0, s35
	ds_read_b128 v[202:205], v235 offset:19456
	buffer_load_dwordx4 v231, s[44:47], s38 offen lds
	s_mov_b32 m0, s19
	ds_read_b128 v[236:239], v235 offset:20480
	buffer_load_dwordx4 v228, s[60:63], s23 offen lds
	s_mov_b32 m0, s36
	ds_read_b128 v[240:243], v235 offset:21504
	buffer_load_dwordx4 v230, s[60:63], s23 offen lds
	ds_read_b128 v[244:247], v235 offset:22528
	ds_read_b128 v[248:251], v235 offset:23552
	s_waitcnt vmcnt(8)
	s_waitcnt lgkmcnt(0)
	s_setprio 1
	s_barrier
	v_mfma_f32_16x16x32_bf16 v[62:65], v[130:133], v[154:157], v[62:65]
	v_mfma_f32_16x16x32_bf16 v[62:65], v[140:143], v[194:197], v[62:65]
	v_mfma_f32_16x16x32_bf16 v[58:61], v[170:173], v[154:157], v[58:61]
	v_mfma_f32_16x16x32_bf16 v[58:61], v[174:177], v[194:197], v[58:61]
	v_mfma_f32_16x16x32_bf16 v[46:49], v[186:189], v[154:157], v[46:49]
	v_mfma_f32_16x16x32_bf16 v[46:49], v[190:193], v[194:197], v[46:49]
	v_mfma_f32_16x16x32_bf16 v[54:57], v[178:181], v[154:157], v[54:57]
	v_mfma_f32_16x16x32_bf16 v[54:57], v[182:185], v[194:197], v[54:57]
	v_mfma_f32_16x16x32_bf16 v[38:41], v[178:181], v[198:201], v[38:41]
	v_mfma_f32_16x16x32_bf16 v[38:41], v[182:185], v[202:205], v[38:41]
	v_mfma_f32_16x16x32_bf16 v[30:33], v[186:189], v[198:201], v[30:33]
	v_mfma_f32_16x16x32_bf16 v[30:33], v[190:193], v[202:205], v[30:33]
	v_mfma_f32_16x16x32_bf16 v[42:45], v[170:173], v[198:201], v[42:45]
	v_mfma_f32_16x16x32_bf16 v[42:45], v[174:177], v[202:205], v[42:45]
	v_mfma_f32_16x16x32_bf16 v[50:53], v[130:133], v[198:201], v[50:53]
	v_mfma_f32_16x16x32_bf16 v[50:53], v[140:143], v[202:205], v[50:53]
	v_mfma_f32_16x16x32_bf16 v[34:37], v[130:133], v[236:239], v[34:37]
	v_mfma_f32_16x16x32_bf16 v[34:37], v[140:143], v[240:243], v[34:37]
	v_mfma_f32_16x16x32_bf16 v[26:29], v[170:173], v[236:239], v[26:29]
	v_mfma_f32_16x16x32_bf16 v[26:29], v[174:177], v[240:243], v[26:29]
	v_mfma_f32_16x16x32_bf16 v[14:17], v[186:189], v[236:239], v[14:17]
	v_mfma_f32_16x16x32_bf16 v[14:17], v[190:193], v[240:243], v[14:17]
	v_mfma_f32_16x16x32_bf16 v[22:25], v[178:181], v[236:239], v[22:25]
	v_mfma_f32_16x16x32_bf16 v[22:25], v[182:185], v[240:243], v[22:25]
	v_mfma_f32_16x16x32_bf16 v[6:9], v[178:181], v[244:247], v[6:9]
	v_mfma_f32_16x16x32_bf16 v[6:9], v[182:185], v[248:251], v[6:9]
	v_mfma_f32_16x16x32_bf16 v[2:5], v[186:189], v[244:247], v[2:5]
	v_mfma_f32_16x16x32_bf16 v[2:5], v[190:193], v[248:251], v[2:5]
	v_mfma_f32_16x16x32_bf16 v[10:13], v[170:173], v[244:247], v[10:13]
	v_mfma_f32_16x16x32_bf16 v[10:13], v[174:177], v[248:251], v[10:13]
	v_mfma_f32_16x16x32_bf16 v[18:21], v[130:133], v[244:247], v[18:21]
	v_mfma_f32_16x16x32_bf16 v[18:21], v[140:143], v[248:251], v[18:21]
	s_barrier
	s_setprio 0
	v_add_u32_e32 v139, 0x18000, v234
	ds_read_b128 v[130:133], v139
	ds_read_b128 v[140:143], v139 offset:1024
	ds_read_b128 v[154:157], v139 offset:2048
	ds_read_b128 v[170:173], v139 offset:3072
	v_add_u32_e32 v139, 0x1c000, v234
	ds_read_b128 v[174:177], v139
	ds_read_b128 v[178:181], v139 offset:1024
	ds_read_b128 v[182:185], v139 offset:2048
	ds_read_b128 v[186:189], v139 offset:3072
	s_add_i32 s23, s23, 0x80000
	s_mov_b32 m0, s37
	ds_read_b128 v[190:193], v235 offset:32768
	ds_read_b128 v[194:197], v235 offset:33792
	ds_read_b128 v[198:201], v235 offset:34816
	ds_read_b128 v[202:205], v235 offset:35840
	ds_read_b128 v[236:239], v235 offset:36864
	ds_read_b128 v[240:243], v235 offset:37888
	ds_read_b128 v[244:247], v235 offset:38912
	ds_read_b128 v[248:251], v235 offset:39936
	buffer_load_dwordx4 v228, s[60:63], s23 offen lds
	s_mov_b32 m0, s18
	s_nop 0
	buffer_load_dwordx4 v230, s[60:63], s23 offen lds
	s_waitcnt vmcnt(8)
	s_waitcnt lgkmcnt(0)
	s_setprio 1
	s_barrier
	v_mfma_f32_16x16x32_bf16 v[126:129], v[130:133], v[190:193], v[126:129]
	v_mfma_f32_16x16x32_bf16 v[126:129], v[140:143], v[194:197], v[126:129]
	v_mfma_f32_16x16x32_bf16 v[122:125], v[154:157], v[190:193], v[122:125]
	v_mfma_f32_16x16x32_bf16 v[122:125], v[170:173], v[194:197], v[122:125]
	v_mfma_f32_16x16x32_bf16 v[110:113], v[182:185], v[190:193], v[110:113]
	v_mfma_f32_16x16x32_bf16 v[110:113], v[186:189], v[194:197], v[110:113]
	v_mfma_f32_16x16x32_bf16 v[118:121], v[174:177], v[190:193], v[118:121]
	v_mfma_f32_16x16x32_bf16 v[118:121], v[178:181], v[194:197], v[118:121]
	v_mfma_f32_16x16x32_bf16 v[102:105], v[174:177], v[198:201], v[102:105]
	v_mfma_f32_16x16x32_bf16 v[102:105], v[178:181], v[202:205], v[102:105]
	v_mfma_f32_16x16x32_bf16 v[94:97], v[182:185], v[198:201], v[94:97]
	v_mfma_f32_16x16x32_bf16 v[94:97], v[186:189], v[202:205], v[94:97]
	v_mfma_f32_16x16x32_bf16 v[106:109], v[154:157], v[198:201], v[106:109]
	v_mfma_f32_16x16x32_bf16 v[106:109], v[170:173], v[202:205], v[106:109]
	v_mfma_f32_16x16x32_bf16 v[114:117], v[130:133], v[198:201], v[114:117]
	v_mfma_f32_16x16x32_bf16 v[114:117], v[140:143], v[202:205], v[114:117]
	v_mfma_f32_16x16x32_bf16 v[98:101], v[130:133], v[236:239], v[98:101]
	v_mfma_f32_16x16x32_bf16 v[98:101], v[140:143], v[240:243], v[98:101]
	v_mfma_f32_16x16x32_bf16 v[90:93], v[154:157], v[236:239], v[90:93]
	v_mfma_f32_16x16x32_bf16 v[90:93], v[170:173], v[240:243], v[90:93]
	v_mfma_f32_16x16x32_bf16 v[78:81], v[182:185], v[236:239], v[78:81]
	v_mfma_f32_16x16x32_bf16 v[78:81], v[186:189], v[240:243], v[78:81]
	v_mfma_f32_16x16x32_bf16 v[86:89], v[174:177], v[236:239], v[86:89]
	v_mfma_f32_16x16x32_bf16 v[86:89], v[178:181], v[240:243], v[86:89]
	v_mfma_f32_16x16x32_bf16 v[70:73], v[174:177], v[244:247], v[70:73]
	v_mfma_f32_16x16x32_bf16 v[70:73], v[178:181], v[248:251], v[70:73]
	v_mfma_f32_16x16x32_bf16 v[66:69], v[182:185], v[244:247], v[66:69]
	v_mfma_f32_16x16x32_bf16 v[66:69], v[186:189], v[248:251], v[66:69]
	v_mfma_f32_16x16x32_bf16 v[74:77], v[154:157], v[244:247], v[74:77]
	v_mfma_f32_16x16x32_bf16 v[74:77], v[170:173], v[248:251], v[74:77]
	v_mfma_f32_16x16x32_bf16 v[82:85], v[130:133], v[244:247], v[82:85]
	v_mfma_f32_16x16x32_bf16 v[82:85], v[140:143], v[248:251], v[82:85]
	s_barrier
	s_setprio 0
	s_or_b32 s23, s22, 0x80
	s_mov_b32 m0, s24
	ds_read_b128 v[190:193], v235 offset:49152
	buffer_load_dwordx4 v229, s[44:47], s23 offen lds
	s_add_i32 s22, s22, 0x80080
	s_mov_b32 m0, s25
	ds_read_b128 v[194:197], v235 offset:50176
	buffer_load_dwordx4 v231, s[44:47], s23 offen lds
	s_mov_b32 m0, s64
	ds_read_b128 v[198:201], v235 offset:51200
	buffer_load_dwordx4 v229, s[44:47], s22 offen lds
	s_mov_b32 m0, s65
	ds_read_b128 v[202:205], v235 offset:52224
	buffer_load_dwordx4 v231, s[44:47], s22 offen lds
	s_mov_b32 m0, s48
	ds_read_b128 v[236:239], v235 offset:53248
	buffer_load_dwordx4 v228, s[60:63], s21 offen lds
	s_mov_b32 m0, s49
	ds_read_b128 v[240:243], v235 offset:54272
	buffer_load_dwordx4 v230, s[60:63], s21 offen lds
	ds_read_b128 v[244:247], v235 offset:55296
	ds_read_b128 v[248:251], v235 offset:56320
	s_waitcnt vmcnt(8)
	s_waitcnt lgkmcnt(0)
	s_setprio 1
	s_barrier
	v_mfma_f32_16x16x32_bf16 v[62:65], v[130:133], v[190:193], v[62:65]
	v_mfma_f32_16x16x32_bf16 v[62:65], v[140:143], v[194:197], v[62:65]
	v_mfma_f32_16x16x32_bf16 v[58:61], v[154:157], v[190:193], v[58:61]
	v_mfma_f32_16x16x32_bf16 v[58:61], v[170:173], v[194:197], v[58:61]
	v_mfma_f32_16x16x32_bf16 v[46:49], v[182:185], v[190:193], v[46:49]
	v_mfma_f32_16x16x32_bf16 v[46:49], v[186:189], v[194:197], v[46:49]
	v_mfma_f32_16x16x32_bf16 v[54:57], v[174:177], v[190:193], v[54:57]
	v_mfma_f32_16x16x32_bf16 v[54:57], v[178:181], v[194:197], v[54:57]
	v_mfma_f32_16x16x32_bf16 v[38:41], v[174:177], v[198:201], v[38:41]
	v_mfma_f32_16x16x32_bf16 v[38:41], v[178:181], v[202:205], v[38:41]
	v_mfma_f32_16x16x32_bf16 v[30:33], v[182:185], v[198:201], v[30:33]
	v_mfma_f32_16x16x32_bf16 v[30:33], v[186:189], v[202:205], v[30:33]
	v_mfma_f32_16x16x32_bf16 v[42:45], v[154:157], v[198:201], v[42:45]
	v_mfma_f32_16x16x32_bf16 v[42:45], v[170:173], v[202:205], v[42:45]
	v_mfma_f32_16x16x32_bf16 v[50:53], v[130:133], v[198:201], v[50:53]
	v_mfma_f32_16x16x32_bf16 v[50:53], v[140:143], v[202:205], v[50:53]
	v_mfma_f32_16x16x32_bf16 v[34:37], v[130:133], v[236:239], v[34:37]
	v_mfma_f32_16x16x32_bf16 v[34:37], v[140:143], v[240:243], v[34:37]
	v_mfma_f32_16x16x32_bf16 v[26:29], v[154:157], v[236:239], v[26:29]
	v_mfma_f32_16x16x32_bf16 v[26:29], v[170:173], v[240:243], v[26:29]
	v_mfma_f32_16x16x32_bf16 v[14:17], v[182:185], v[236:239], v[14:17]
	v_mfma_f32_16x16x32_bf16 v[14:17], v[186:189], v[240:243], v[14:17]
	v_mfma_f32_16x16x32_bf16 v[22:25], v[174:177], v[236:239], v[22:25]
	v_mfma_f32_16x16x32_bf16 v[22:25], v[178:181], v[240:243], v[22:25]
	v_mfma_f32_16x16x32_bf16 v[6:9], v[174:177], v[244:247], v[6:9]
	v_mfma_f32_16x16x32_bf16 v[6:9], v[178:181], v[248:251], v[6:9]
	v_mfma_f32_16x16x32_bf16 v[2:5], v[182:185], v[244:247], v[2:5]
	v_mfma_f32_16x16x32_bf16 v[2:5], v[186:189], v[248:251], v[2:5]
	v_mfma_f32_16x16x32_bf16 v[10:13], v[154:157], v[244:247], v[10:13]
	v_mfma_f32_16x16x32_bf16 v[10:13], v[170:173], v[248:251], v[10:13]
	v_mfma_f32_16x16x32_bf16 v[18:21], v[130:133], v[244:247], v[18:21]
	v_mfma_f32_16x16x32_bf16 v[18:21], v[140:143], v[248:251], v[18:21]
	s_barrier
	s_setprio 0
	s_add_i32 s16, s16, 2
	s_addk_i32 s12, 0x100
	s_addk_i32 s13, 0x100
	s_cmp_gt_u32 s16, 29
	s_cbranch_scc0 .LBB0_881
	v_readlane_b32 s8, v255, 44
	v_readlane_b32 s9, v255, 45
	s_and_b64 vcc, exec, s[8:9]
	s_cbranch_vccz .LBB0_884
	s_barrier
	s_setprio 2

.LBB0_901:
	s_setprio 0
	s_andn2_b64 vcc, exec, s[8:9]
	s_mov_b32 s2, s71
	s_mov_b32 s12, s72
	s_mov_b32 s21, s84
	s_mov_b32 s13, s73
	s_cbranch_vccz .LBB0_911

.LBB0_905:
	v_add_u32_e32 v133, 0x10000, v178
	ds_read_b128 v[134:137], v133
	ds_read_b128 v[138:141], v133 offset:1024
	ds_read_b128 v[142:145], v133 offset:2048
	ds_read_b128 v[154:157], v133 offset:3072
	v_add_u32_e32 v133, 0x14000, v178
	ds_read_b128 v[170:173], v133
	ds_read_b128 v[180:183], v133 offset:1024
	ds_read_b128 v[184:187], v133 offset:2048
	ds_read_b128 v[188:191], v133 offset:3072
	s_add_i32 s23, s13, 0xfff80080
	s_cmp_eq_u32 s22, 28
	s_cselect_b32 s27, s8, s23
	s_cselect_b32 s26, s9, s21
	s_or_b32 s23, s27, 0x80
	s_mov_b32 s46, s62
	s_mov_b32 s47, s63
	s_mov_b32 m0, s68
	ds_read_b128 v[192:195], v179
	ds_read_b128 v[196:199], v179 offset:1024
	ds_read_b128 v[200:203], v179 offset:2048
	ds_read_b128 v[204:207], v179 offset:3072
	ds_read_b128 v[228:231], v179 offset:4096
	ds_read_b128 v[232:235], v179 offset:5120
	ds_read_b128 v[236:239], v179 offset:6144
	ds_read_b128 v[240:243], v179 offset:7168
	buffer_load_dwordx4 v174, s[44:47], s13 offen lds
	s_mov_b32 m0, s69
	s_nop 0
	buffer_load_dwordx4 v176, s[44:47], s13 offen lds
	s_waitcnt vmcnt(8)
	s_waitcnt lgkmcnt(0)
	s_setprio 1
	s_barrier
	v_mfma_f32_16x16x32_bf16 v[126:129], v[134:137], v[192:195], v[126:129]
	v_mfma_f32_16x16x32_bf16 v[126:129], v[138:141], v[196:199], v[126:129]
	v_mfma_f32_16x16x32_bf16 v[122:125], v[142:145], v[192:195], v[122:125]
	v_mfma_f32_16x16x32_bf16 v[122:125], v[154:157], v[196:199], v[122:125]
	v_mfma_f32_16x16x32_bf16 v[114:117], v[184:187], v[192:195], v[114:117]
	v_mfma_f32_16x16x32_bf16 v[114:117], v[188:191], v[196:199], v[114:117]
	v_mfma_f32_16x16x32_bf16 v[118:121], v[170:173], v[192:195], v[118:121]
	v_mfma_f32_16x16x32_bf16 v[118:121], v[180:183], v[196:199], v[118:121]
	v_mfma_f32_16x16x32_bf16 v[102:105], v[170:173], v[200:203], v[102:105]
	v_mfma_f32_16x16x32_bf16 v[102:105], v[180:183], v[204:207], v[102:105]
	v_mfma_f32_16x16x32_bf16 v[98:101], v[184:187], v[200:203], v[98:101]
	v_mfma_f32_16x16x32_bf16 v[98:101], v[188:191], v[204:207], v[98:101]
	v_mfma_f32_16x16x32_bf16 v[106:109], v[142:145], v[200:203], v[106:109]
	v_mfma_f32_16x16x32_bf16 v[106:109], v[154:157], v[204:207], v[106:109]
	v_mfma_f32_16x16x32_bf16 v[110:113], v[134:137], v[200:203], v[110:113]
	v_mfma_f32_16x16x32_bf16 v[110:113], v[138:141], v[204:207], v[110:113]
	v_mfma_f32_16x16x32_bf16 v[94:97], v[134:137], v[228:231], v[94:97]
	v_mfma_f32_16x16x32_bf16 v[94:97], v[138:141], v[232:235], v[94:97]
	v_mfma_f32_16x16x32_bf16 v[90:93], v[142:145], v[228:231], v[90:93]
	v_mfma_f32_16x16x32_bf16 v[90:93], v[154:157], v[232:235], v[90:93]
	v_mfma_f32_16x16x32_bf16 v[82:85], v[184:187], v[228:231], v[82:85]
	v_mfma_f32_16x16x32_bf16 v[82:85], v[188:191], v[232:235], v[82:85]
	v_mfma_f32_16x16x32_bf16 v[86:89], v[170:173], v[228:231], v[86:89]
	v_mfma_f32_16x16x32_bf16 v[86:89], v[180:183], v[232:235], v[86:89]
	v_mfma_f32_16x16x32_bf16 v[70:73], v[170:173], v[236:239], v[70:73]
	v_mfma_f32_16x16x32_bf16 v[70:73], v[180:183], v[240:243], v[70:73]
	v_mfma_f32_16x16x32_bf16 v[66:69], v[184:187], v[236:239], v[66:69]
	v_mfma_f32_16x16x32_bf16 v[66:69], v[188:191], v[240:243], v[66:69]
	v_mfma_f32_16x16x32_bf16 v[74:77], v[142:145], v[236:239], v[74:77]
	v_mfma_f32_16x16x32_bf16 v[74:77], v[154:157], v[240:243], v[74:77]
	v_mfma_f32_16x16x32_bf16 v[78:81], v[134:137], v[236:239], v[78:81]
	v_mfma_f32_16x16x32_bf16 v[78:81], v[138:141], v[240:243], v[78:81]
	s_barrier
	s_setprio 0
	s_mov_b32 m0, s15
	ds_read_b128 v[192:195], v179 offset:16384
	buffer_load_dwordx4 v175, s[60:63], s26 offen lds
	s_add_i32 s34, s26, 0x80000
	s_mov_b32 m0, s16
	ds_read_b128 v[196:199], v179 offset:17408
	buffer_load_dwordx4 v177, s[60:63], s26 offen lds
	s_mov_b32 m0, s18
	ds_read_b128 v[200:203], v179 offset:18432
	buffer_load_dwordx4 v175, s[60:63], s34 offen lds
	s_mov_b32 m0, s19
	ds_read_b128 v[204:207], v179 offset:19456
	buffer_load_dwordx4 v177, s[60:63], s34 offen lds
	s_mov_b32 m0, s14
	ds_read_b128 v[228:231], v179 offset:20480
	buffer_load_dwordx4 v174, s[44:47], s27 offen lds
	s_mov_b32 m0, s24
	ds_read_b128 v[232:235], v179 offset:21504
	buffer_load_dwordx4 v176, s[44:47], s27 offen lds
	ds_read_b128 v[236:239], v179 offset:22528
	ds_read_b128 v[240:243], v179 offset:23552
	s_waitcnt vmcnt(8)
	s_waitcnt lgkmcnt(0)
	s_setprio 1
	s_barrier
	v_mfma_f32_16x16x32_bf16 v[62:65], v[134:137], v[192:195], v[62:65]
	v_mfma_f32_16x16x32_bf16 v[62:65], v[138:141], v[196:199], v[62:65]
	v_mfma_f32_16x16x32_bf16 v[58:61], v[142:145], v[192:195], v[58:61]
	v_mfma_f32_16x16x32_bf16 v[58:61], v[154:157], v[196:199], v[58:61]
	v_mfma_f32_16x16x32_bf16 v[50:53], v[184:187], v[192:195], v[50:53]
	v_mfma_f32_16x16x32_bf16 v[50:53], v[188:191], v[196:199], v[50:53]
	v_mfma_f32_16x16x32_bf16 v[54:57], v[170:173], v[192:195], v[54:57]
	v_mfma_f32_16x16x32_bf16 v[54:57], v[180:183], v[196:199], v[54:57]
	v_mfma_f32_16x16x32_bf16 v[38:41], v[170:173], v[200:203], v[38:41]
	v_mfma_f32_16x16x32_bf16 v[38:41], v[180:183], v[204:207], v[38:41]
	v_mfma_f32_16x16x32_bf16 v[34:37], v[184:187], v[200:203], v[34:37]
	v_mfma_f32_16x16x32_bf16 v[34:37], v[188:191], v[204:207], v[34:37]
	v_mfma_f32_16x16x32_bf16 v[42:45], v[142:145], v[200:203], v[42:45]
	v_mfma_f32_16x16x32_bf16 v[42:45], v[154:157], v[204:207], v[42:45]
	v_mfma_f32_16x16x32_bf16 v[46:49], v[134:137], v[200:203], v[46:49]
	v_mfma_f32_16x16x32_bf16 v[46:49], v[138:141], v[204:207], v[46:49]
	v_mfma_f32_16x16x32_bf16 v[30:33], v[134:137], v[228:231], v[30:33]
	v_mfma_f32_16x16x32_bf16 v[30:33], v[138:141], v[232:235], v[30:33]
	v_mfma_f32_16x16x32_bf16 v[26:29], v[142:145], v[228:231], v[26:29]
	v_mfma_f32_16x16x32_bf16 v[26:29], v[154:157], v[232:235], v[26:29]
	v_mfma_f32_16x16x32_bf16 v[18:21], v[184:187], v[228:231], v[18:21]
	v_mfma_f32_16x16x32_bf16 v[18:21], v[188:191], v[232:235], v[18:21]
	v_mfma_f32_16x16x32_bf16 v[22:25], v[170:173], v[228:231], v[22:25]
	v_mfma_f32_16x16x32_bf16 v[22:25], v[180:183], v[232:235], v[22:25]
	v_mfma_f32_16x16x32_bf16 v[6:9], v[170:173], v[236:239], v[6:9]
	v_mfma_f32_16x16x32_bf16 v[6:9], v[180:183], v[240:243], v[6:9]
	v_mfma_f32_16x16x32_bf16 v[2:5], v[184:187], v[236:239], v[2:5]
	v_mfma_f32_16x16x32_bf16 v[2:5], v[188:191], v[240:243], v[2:5]
	v_mfma_f32_16x16x32_bf16 v[10:13], v[142:145], v[236:239], v[10:13]
	v_mfma_f32_16x16x32_bf16 v[10:13], v[154:157], v[240:243], v[10:13]
	v_mfma_f32_16x16x32_bf16 v[14:17], v[134:137], v[236:239], v[14:17]
	v_mfma_f32_16x16x32_bf16 v[14:17], v[138:141], v[240:243], v[14:17]
	s_barrier
	s_setprio 0
	v_add_u32_e32 v133, 0x18000, v178
	ds_read_b128 v[134:137], v133
	ds_read_b128 v[138:141], v133 offset:1024
	ds_read_b128 v[142:145], v133 offset:2048
	ds_read_b128 v[154:157], v133 offset:3072
	v_add_u32_e32 v133, 0x1c000, v178
	ds_read_b128 v[170:173], v133
	ds_read_b128 v[180:183], v133 offset:1024
	ds_read_b128 v[184:187], v133 offset:2048
	ds_read_b128 v[188:191], v133 offset:3072
	s_add_i32 s27, s27, 0x80000
	s_mov_b32 m0, s25
	ds_read_b128 v[192:195], v179 offset:32768
	ds_read_b128 v[196:199], v179 offset:33792
	ds_read_b128 v[200:203], v179 offset:34816
	ds_read_b128 v[204:207], v179 offset:35840
	ds_read_b128 v[228:231], v179 offset:36864
	ds_read_b128 v[232:235], v179 offset:37888
	ds_read_b128 v[236:239], v179 offset:38912
	ds_read_b128 v[240:243], v179 offset:39936
	buffer_load_dwordx4 v174, s[44:47], s27 offen lds
	s_mov_b32 m0, s30
	s_nop 0
	buffer_load_dwordx4 v176, s[44:47], s27 offen lds
	s_waitcnt vmcnt(8)
	s_waitcnt lgkmcnt(0)
	s_setprio 1
	s_barrier
	v_mfma_f32_16x16x32_bf16 v[126:129], v[134:137], v[192:195], v[126:129]
	v_mfma_f32_16x16x32_bf16 v[126:129], v[138:141], v[196:199], v[126:129]
	v_mfma_f32_16x16x32_bf16 v[122:125], v[142:145], v[192:195], v[122:125]
	v_mfma_f32_16x16x32_bf16 v[122:125], v[154:157], v[196:199], v[122:125]
	v_mfma_f32_16x16x32_bf16 v[114:117], v[184:187], v[192:195], v[114:117]
	v_mfma_f32_16x16x32_bf16 v[114:117], v[188:191], v[196:199], v[114:117]
	v_mfma_f32_16x16x32_bf16 v[118:121], v[170:173], v[192:195], v[118:121]
	v_mfma_f32_16x16x32_bf16 v[118:121], v[180:183], v[196:199], v[118:121]
	v_mfma_f32_16x16x32_bf16 v[102:105], v[170:173], v[200:203], v[102:105]
	v_mfma_f32_16x16x32_bf16 v[102:105], v[180:183], v[204:207], v[102:105]
	v_mfma_f32_16x16x32_bf16 v[98:101], v[184:187], v[200:203], v[98:101]
	v_mfma_f32_16x16x32_bf16 v[98:101], v[188:191], v[204:207], v[98:101]
	v_mfma_f32_16x16x32_bf16 v[106:109], v[142:145], v[200:203], v[106:109]
	v_mfma_f32_16x16x32_bf16 v[106:109], v[154:157], v[204:207], v[106:109]
	v_mfma_f32_16x16x32_bf16 v[110:113], v[134:137], v[200:203], v[110:113]
	v_mfma_f32_16x16x32_bf16 v[110:113], v[138:141], v[204:207], v[110:113]
	v_mfma_f32_16x16x32_bf16 v[94:97], v[134:137], v[228:231], v[94:97]
	v_mfma_f32_16x16x32_bf16 v[94:97], v[138:141], v[232:235], v[94:97]
	v_mfma_f32_16x16x32_bf16 v[90:93], v[142:145], v[228:231], v[90:93]
	v_mfma_f32_16x16x32_bf16 v[90:93], v[154:157], v[232:235], v[90:93]
	v_mfma_f32_16x16x32_bf16 v[82:85], v[184:187], v[228:231], v[82:85]
	v_mfma_f32_16x16x32_bf16 v[82:85], v[188:191], v[232:235], v[82:85]
	v_mfma_f32_16x16x32_bf16 v[86:89], v[170:173], v[228:231], v[86:89]
	v_mfma_f32_16x16x32_bf16 v[86:89], v[180:183], v[232:235], v[86:89]
	v_mfma_f32_16x16x32_bf16 v[70:73], v[170:173], v[236:239], v[70:73]
	v_mfma_f32_16x16x32_bf16 v[70:73], v[180:183], v[240:243], v[70:73]
	v_mfma_f32_16x16x32_bf16 v[66:69], v[184:187], v[236:239], v[66:69]
	v_mfma_f32_16x16x32_bf16 v[66:69], v[188:191], v[240:243], v[66:69]
	v_mfma_f32_16x16x32_bf16 v[74:77], v[142:145], v[236:239], v[74:77]
	v_mfma_f32_16x16x32_bf16 v[74:77], v[154:157], v[240:243], v[74:77]
	v_mfma_f32_16x16x32_bf16 v[78:81], v[134:137], v[236:239], v[78:81]
	v_mfma_f32_16x16x32_bf16 v[78:81], v[138:141], v[240:243], v[78:81]
	s_barrier
	s_setprio 0
	s_or_b32 s27, s26, 0x80
	s_mov_b32 m0, s36
	ds_read_b128 v[192:195], v179 offset:49152
	buffer_load_dwordx4 v175, s[60:63], s27 offen lds
	s_add_i32 s26, s26, 0x80080
	s_mov_b32 m0, s37
	ds_read_b128 v[196:199], v179 offset:50176
	buffer_load_dwordx4 v177, s[60:63], s27 offen lds
	s_mov_b32 m0, s48
	ds_read_b128 v[200:203], v179 offset:51200
	buffer_load_dwordx4 v175, s[60:63], s26 offen lds
	s_mov_b32 m0, s49
	ds_read_b128 v[204:207], v179 offset:52224
	buffer_load_dwordx4 v177, s[60:63], s26 offen lds
	s_mov_b32 m0, s40
	ds_read_b128 v[228:231], v179 offset:53248
	buffer_load_dwordx4 v174, s[44:47], s23 offen lds
	s_mov_b32 m0, s41
	ds_read_b128 v[232:235], v179 offset:54272
	buffer_load_dwordx4 v176, s[44:47], s23 offen lds
	ds_read_b128 v[236:239], v179 offset:55296
	ds_read_b128 v[240:243], v179 offset:56320
	s_waitcnt vmcnt(8)
	s_waitcnt lgkmcnt(0)
	s_setprio 1
	s_barrier
	v_mfma_f32_16x16x32_bf16 v[62:65], v[134:137], v[192:195], v[62:65]
	v_mfma_f32_16x16x32_bf16 v[62:65], v[138:141], v[196:199], v[62:65]
	v_mfma_f32_16x16x32_bf16 v[58:61], v[142:145], v[192:195], v[58:61]
	v_mfma_f32_16x16x32_bf16 v[58:61], v[154:157], v[196:199], v[58:61]
	v_mfma_f32_16x16x32_bf16 v[50:53], v[184:187], v[192:195], v[50:53]
	v_mfma_f32_16x16x32_bf16 v[50:53], v[188:191], v[196:199], v[50:53]
	v_mfma_f32_16x16x32_bf16 v[54:57], v[170:173], v[192:195], v[54:57]
	v_mfma_f32_16x16x32_bf16 v[54:57], v[180:183], v[196:199], v[54:57]
	v_mfma_f32_16x16x32_bf16 v[38:41], v[170:173], v[200:203], v[38:41]
	v_mfma_f32_16x16x32_bf16 v[38:41], v[180:183], v[204:207], v[38:41]
	v_mfma_f32_16x16x32_bf16 v[34:37], v[184:187], v[200:203], v[34:37]
	v_mfma_f32_16x16x32_bf16 v[34:37], v[188:191], v[204:207], v[34:37]
	v_mfma_f32_16x16x32_bf16 v[42:45], v[142:145], v[200:203], v[42:45]
	v_mfma_f32_16x16x32_bf16 v[42:45], v[154:157], v[204:207], v[42:45]
	v_mfma_f32_16x16x32_bf16 v[46:49], v[134:137], v[200:203], v[46:49]
	v_mfma_f32_16x16x32_bf16 v[46:49], v[138:141], v[204:207], v[46:49]
	v_mfma_f32_16x16x32_bf16 v[30:33], v[134:137], v[228:231], v[30:33]
	v_mfma_f32_16x16x32_bf16 v[30:33], v[138:141], v[232:235], v[30:33]
	v_mfma_f32_16x16x32_bf16 v[26:29], v[142:145], v[228:231], v[26:29]
	v_mfma_f32_16x16x32_bf16 v[26:29], v[154:157], v[232:235], v[26:29]
	v_mfma_f32_16x16x32_bf16 v[18:21], v[184:187], v[228:231], v[18:21]
	v_mfma_f32_16x16x32_bf16 v[18:21], v[188:191], v[232:235], v[18:21]
	v_mfma_f32_16x16x32_bf16 v[22:25], v[170:173], v[228:231], v[22:25]
	v_mfma_f32_16x16x32_bf16 v[22:25], v[180:183], v[232:235], v[22:25]
	v_mfma_f32_16x16x32_bf16 v[6:9], v[170:173], v[236:239], v[6:9]
	v_mfma_f32_16x16x32_bf16 v[6:9], v[180:183], v[240:243], v[6:9]
	v_mfma_f32_16x16x32_bf16 v[2:5], v[184:187], v[236:239], v[2:5]
	v_mfma_f32_16x16x32_bf16 v[2:5], v[188:191], v[240:243], v[2:5]
	v_mfma_f32_16x16x32_bf16 v[10:13], v[142:145], v[236:239], v[10:13]
	v_mfma_f32_16x16x32_bf16 v[10:13], v[154:157], v[240:243], v[10:13]
	v_mfma_f32_16x16x32_bf16 v[14:17], v[134:137], v[236:239], v[14:17]
	v_mfma_f32_16x16x32_bf16 v[14:17], v[138:141], v[240:243], v[14:17]
	s_barrier
	s_setprio 0
	s_add_i32 s22, s22, 2
	s_addk_i32 s13, 0x100
	s_addk_i32 s21, 0x100
	s_cmp_gt_u32 s22, 29
	s_cbranch_scc0 .LBB0_905
	s_and_b64 vcc, exec, s[64:65]
	s_cbranch_vccz .LBB0_908
	s_barrier
	s_setprio 2

.LBB0_1189:
	s_setprio 0
	s_andn2_b64 vcc, exec, s[8:9]
	s_mov_b32 s18, s71
	s_mov_b32 s19, s70
	s_mov_b32 s31, s22
	s_mov_b32 s30, s12
	s_cbranch_vccz .LBB0_1211

.LBB0_1193:
	v_add_u32_e32 v141, 0x10000, v139
	ds_read_b128 v[142:145], v141
	ds_read_b128 v[154:157], v141 offset:1024
	ds_read_b128 v[170:173], v141 offset:2048
	ds_read_b128 v[174:177], v141 offset:3072
	v_add_u32_e32 v141, 0x14000, v139
	ds_read_b128 v[178:181], v141
	ds_read_b128 v[182:185], v141 offset:1024
	ds_read_b128 v[186:189], v141 offset:2048
	ds_read_b128 v[190:193], v141 offset:3072
	s_add_i32 s52, s30, 0xffe00080
	s_cmpk_eq_i32 s72, 0x7c
	s_cselect_b32 s52, s8, s52
	s_cselect_b32 s82, s9, s31
	s_or_b32 s73, s52, 0x80
	s_mov_b32 m0, s69
	ds_read_b128 v[194:197], v140
	ds_read_b128 v[198:201], v140 offset:1024
	ds_read_b128 v[202:205], v140 offset:2048
	ds_read_b128 v[228:231], v140 offset:3072
	ds_read_b128 v[232:235], v140 offset:4096
	ds_read_b128 v[236:239], v140 offset:5120
	ds_read_b128 v[240:243], v140 offset:6144
	ds_read_b128 v[244:247], v140 offset:7168
	buffer_load_dwordx4 v131, s[60:63], s30 offen lds
	s_mov_b32 m0, s46
	s_nop 0
	buffer_load_dwordx4 v135, s[60:63], s30 offen lds
	s_waitcnt vmcnt(8)
	s_waitcnt lgkmcnt(0)
	s_setprio 1
	s_barrier
	v_mfma_f32_16x16x32_bf16 v[126:129], v[142:145], v[194:197], v[126:129]
	v_mfma_f32_16x16x32_bf16 v[126:129], v[154:157], v[198:201], v[126:129]
	v_mfma_f32_16x16x32_bf16 v[122:125], v[170:173], v[194:197], v[122:125]
	v_mfma_f32_16x16x32_bf16 v[122:125], v[174:177], v[198:201], v[122:125]
	v_mfma_f32_16x16x32_bf16 v[58:61], v[186:189], v[194:197], v[58:61]
	v_mfma_f32_16x16x32_bf16 v[58:61], v[190:193], v[198:201], v[58:61]
	v_mfma_f32_16x16x32_bf16 v[62:65], v[178:181], v[194:197], v[62:65]
	v_mfma_f32_16x16x32_bf16 v[62:65], v[182:185], v[198:201], v[62:65]
	v_mfma_f32_16x16x32_bf16 v[54:57], v[178:181], v[202:205], v[54:57]
	v_mfma_f32_16x16x32_bf16 v[54:57], v[182:185], v[228:231], v[54:57]
	v_mfma_f32_16x16x32_bf16 v[50:53], v[186:189], v[202:205], v[50:53]
	v_mfma_f32_16x16x32_bf16 v[50:53], v[190:193], v[228:231], v[50:53]
	v_mfma_f32_16x16x32_bf16 v[114:117], v[170:173], v[202:205], v[114:117]
	v_mfma_f32_16x16x32_bf16 v[114:117], v[174:177], v[228:231], v[114:117]
	v_mfma_f32_16x16x32_bf16 v[118:121], v[142:145], v[202:205], v[118:121]
	v_mfma_f32_16x16x32_bf16 v[118:121], v[154:157], v[228:231], v[118:121]
	v_mfma_f32_16x16x32_bf16 v[110:113], v[142:145], v[232:235], v[110:113]
	v_mfma_f32_16x16x32_bf16 v[110:113], v[154:157], v[236:239], v[110:113]
	v_mfma_f32_16x16x32_bf16 v[106:109], v[170:173], v[232:235], v[106:109]
	v_mfma_f32_16x16x32_bf16 v[106:109], v[174:177], v[236:239], v[106:109]
	v_mfma_f32_16x16x32_bf16 v[42:45], v[186:189], v[232:235], v[42:45]
	v_mfma_f32_16x16x32_bf16 v[42:45], v[190:193], v[236:239], v[42:45]
	v_mfma_f32_16x16x32_bf16 v[46:49], v[178:181], v[232:235], v[46:49]
	v_mfma_f32_16x16x32_bf16 v[46:49], v[182:185], v[236:239], v[46:49]
	v_mfma_f32_16x16x32_bf16 v[38:41], v[178:181], v[240:243], v[38:41]
	v_mfma_f32_16x16x32_bf16 v[38:41], v[182:185], v[244:247], v[38:41]
	v_mfma_f32_16x16x32_bf16 v[34:37], v[186:189], v[240:243], v[34:37]
	v_mfma_f32_16x16x32_bf16 v[34:37], v[190:193], v[244:247], v[34:37]
	v_mfma_f32_16x16x32_bf16 v[98:101], v[170:173], v[240:243], v[98:101]
	v_mfma_f32_16x16x32_bf16 v[98:101], v[174:177], v[244:247], v[98:101]
	v_mfma_f32_16x16x32_bf16 v[102:105], v[142:145], v[240:243], v[102:105]
	v_mfma_f32_16x16x32_bf16 v[102:105], v[154:157], v[244:247], v[102:105]
	s_barrier
	s_setprio 0
	s_mov_b32 s66, s62
	s_mov_b32 s67, s63
	s_mov_b32 m0, s15
	ds_read_b128 v[194:197], v140 offset:16384
	buffer_load_dwordx4 v134, s[64:67], s82 offen lds
	s_add_i32 s53, s82, 0x200000
	s_mov_b32 m0, s16
	ds_read_b128 v[198:201], v140 offset:17408
	buffer_load_dwordx4 v136, s[64:67], s82 offen lds
	s_mov_b32 m0, s21
	ds_read_b128 v[202:205], v140 offset:18432
	buffer_load_dwordx4 v134, s[64:67], s53 offen lds
	s_mov_b32 m0, s23
	ds_read_b128 v[228:231], v140 offset:19456
	buffer_load_dwordx4 v136, s[64:67], s53 offen lds
	s_mov_b32 m0, s2
	ds_read_b128 v[232:235], v140 offset:20480
	buffer_load_dwordx4 v131, s[60:63], s52 offen lds
	s_mov_b32 m0, s24
	ds_read_b128 v[236:239], v140 offset:21504
	buffer_load_dwordx4 v135, s[60:63], s52 offen lds
	ds_read_b128 v[240:243], v140 offset:22528
	ds_read_b128 v[244:247], v140 offset:23552
	s_waitcnt vmcnt(8)
	s_waitcnt lgkmcnt(0)
	s_setprio 1
	s_barrier
	v_mfma_f32_16x16x32_bf16 v[94:97], v[142:145], v[194:197], v[94:97]
	v_mfma_f32_16x16x32_bf16 v[94:97], v[154:157], v[198:201], v[94:97]
	v_mfma_f32_16x16x32_bf16 v[90:93], v[170:173], v[194:197], v[90:93]
	v_mfma_f32_16x16x32_bf16 v[90:93], v[174:177], v[198:201], v[90:93]
	v_mfma_f32_16x16x32_bf16 v[26:29], v[186:189], v[194:197], v[26:29]
	v_mfma_f32_16x16x32_bf16 v[26:29], v[190:193], v[198:201], v[26:29]
	v_mfma_f32_16x16x32_bf16 v[30:33], v[178:181], v[194:197], v[30:33]
	v_mfma_f32_16x16x32_bf16 v[30:33], v[182:185], v[198:201], v[30:33]
	v_mfma_f32_16x16x32_bf16 v[22:25], v[178:181], v[202:205], v[22:25]
	v_mfma_f32_16x16x32_bf16 v[22:25], v[182:185], v[228:231], v[22:25]
	v_mfma_f32_16x16x32_bf16 v[18:21], v[186:189], v[202:205], v[18:21]
	v_mfma_f32_16x16x32_bf16 v[18:21], v[190:193], v[228:231], v[18:21]
	v_mfma_f32_16x16x32_bf16 v[82:85], v[170:173], v[202:205], v[82:85]
	v_mfma_f32_16x16x32_bf16 v[82:85], v[174:177], v[228:231], v[82:85]
	v_mfma_f32_16x16x32_bf16 v[86:89], v[142:145], v[202:205], v[86:89]
	v_mfma_f32_16x16x32_bf16 v[86:89], v[154:157], v[228:231], v[86:89]
	v_mfma_f32_16x16x32_bf16 v[78:81], v[142:145], v[232:235], v[78:81]
	v_mfma_f32_16x16x32_bf16 v[78:81], v[154:157], v[236:239], v[78:81]
	v_mfma_f32_16x16x32_bf16 v[74:77], v[170:173], v[232:235], v[74:77]
	v_mfma_f32_16x16x32_bf16 v[74:77], v[174:177], v[236:239], v[74:77]
	v_mfma_f32_16x16x32_bf16 v[10:13], v[186:189], v[232:235], v[10:13]
	v_mfma_f32_16x16x32_bf16 v[10:13], v[190:193], v[236:239], v[10:13]
	v_mfma_f32_16x16x32_bf16 v[14:17], v[178:181], v[232:235], v[14:17]
	v_mfma_f32_16x16x32_bf16 v[14:17], v[182:185], v[236:239], v[14:17]
	v_mfma_f32_16x16x32_bf16 v[6:9], v[178:181], v[240:243], v[6:9]
	v_mfma_f32_16x16x32_bf16 v[6:9], v[182:185], v[244:247], v[6:9]
	v_mfma_f32_16x16x32_bf16 v[2:5], v[186:189], v[240:243], v[2:5]
	v_mfma_f32_16x16x32_bf16 v[2:5], v[190:193], v[244:247], v[2:5]
	v_mfma_f32_16x16x32_bf16 v[66:69], v[170:173], v[240:243], v[66:69]
	v_mfma_f32_16x16x32_bf16 v[66:69], v[174:177], v[244:247], v[66:69]
	v_mfma_f32_16x16x32_bf16 v[70:73], v[142:145], v[240:243], v[70:73]
	v_mfma_f32_16x16x32_bf16 v[70:73], v[154:157], v[244:247], v[70:73]
	s_barrier
	s_setprio 0
	v_add_u32_e32 v141, 0x18000, v139
	ds_read_b128 v[142:145], v141
	ds_read_b128 v[154:157], v141 offset:1024
	ds_read_b128 v[170:173], v141 offset:2048
	ds_read_b128 v[174:177], v141 offset:3072
	v_add_u32_e32 v141, 0x1c000, v139
	ds_read_b128 v[178:181], v141
	ds_read_b128 v[182:185], v141 offset:1024
	ds_read_b128 v[186:189], v141 offset:2048
	ds_read_b128 v[190:193], v141 offset:3072
	s_add_i32 s52, s52, 0x200000
	s_mov_b32 m0, s25
	ds_read_b128 v[194:197], v140 offset:32768
	ds_read_b128 v[198:201], v140 offset:33792
	ds_read_b128 v[202:205], v140 offset:34816
	ds_read_b128 v[228:231], v140 offset:35840
	ds_read_b128 v[232:235], v140 offset:36864
	ds_read_b128 v[236:239], v140 offset:37888
	ds_read_b128 v[240:243], v140 offset:38912
	ds_read_b128 v[244:247], v140 offset:39936
	buffer_load_dwordx4 v131, s[60:63], s52 offen lds
	s_mov_b32 m0, s33
	s_nop 0
	buffer_load_dwordx4 v135, s[60:63], s52 offen lds
	s_waitcnt vmcnt(8)
	s_waitcnt lgkmcnt(0)
	s_setprio 1
	s_barrier
	v_mfma_f32_16x16x32_bf16 v[126:129], v[142:145], v[194:197], v[126:129]
	v_mfma_f32_16x16x32_bf16 v[126:129], v[154:157], v[198:201], v[126:129]
	v_mfma_f32_16x16x32_bf16 v[122:125], v[170:173], v[194:197], v[122:125]
	v_mfma_f32_16x16x32_bf16 v[122:125], v[174:177], v[198:201], v[122:125]
	v_mfma_f32_16x16x32_bf16 v[58:61], v[186:189], v[194:197], v[58:61]
	v_mfma_f32_16x16x32_bf16 v[58:61], v[190:193], v[198:201], v[58:61]
	v_mfma_f32_16x16x32_bf16 v[62:65], v[178:181], v[194:197], v[62:65]
	v_mfma_f32_16x16x32_bf16 v[62:65], v[182:185], v[198:201], v[62:65]
	v_mfma_f32_16x16x32_bf16 v[54:57], v[178:181], v[202:205], v[54:57]
	v_mfma_f32_16x16x32_bf16 v[54:57], v[182:185], v[228:231], v[54:57]
	v_mfma_f32_16x16x32_bf16 v[50:53], v[186:189], v[202:205], v[50:53]
	v_mfma_f32_16x16x32_bf16 v[50:53], v[190:193], v[228:231], v[50:53]
	v_mfma_f32_16x16x32_bf16 v[114:117], v[170:173], v[202:205], v[114:117]
	v_mfma_f32_16x16x32_bf16 v[114:117], v[174:177], v[228:231], v[114:117]
	v_mfma_f32_16x16x32_bf16 v[118:121], v[142:145], v[202:205], v[118:121]
	v_mfma_f32_16x16x32_bf16 v[118:121], v[154:157], v[228:231], v[118:121]
	v_mfma_f32_16x16x32_bf16 v[110:113], v[142:145], v[232:235], v[110:113]
	v_mfma_f32_16x16x32_bf16 v[110:113], v[154:157], v[236:239], v[110:113]
	v_mfma_f32_16x16x32_bf16 v[106:109], v[170:173], v[232:235], v[106:109]
	v_mfma_f32_16x16x32_bf16 v[106:109], v[174:177], v[236:239], v[106:109]
	v_mfma_f32_16x16x32_bf16 v[42:45], v[186:189], v[232:235], v[42:45]
	v_mfma_f32_16x16x32_bf16 v[42:45], v[190:193], v[236:239], v[42:45]
	v_mfma_f32_16x16x32_bf16 v[46:49], v[178:181], v[232:235], v[46:49]
	v_mfma_f32_16x16x32_bf16 v[46:49], v[182:185], v[236:239], v[46:49]
	v_mfma_f32_16x16x32_bf16 v[38:41], v[178:181], v[240:243], v[38:41]
	v_mfma_f32_16x16x32_bf16 v[38:41], v[182:185], v[244:247], v[38:41]
	v_mfma_f32_16x16x32_bf16 v[34:37], v[186:189], v[240:243], v[34:37]
	v_mfma_f32_16x16x32_bf16 v[34:37], v[190:193], v[244:247], v[34:37]
	v_mfma_f32_16x16x32_bf16 v[98:101], v[170:173], v[240:243], v[98:101]
	v_mfma_f32_16x16x32_bf16 v[98:101], v[174:177], v[244:247], v[98:101]
	v_mfma_f32_16x16x32_bf16 v[102:105], v[142:145], v[240:243], v[102:105]
	v_mfma_f32_16x16x32_bf16 v[102:105], v[154:157], v[244:247], v[102:105]
	s_barrier
	s_setprio 0
	s_or_b32 s52, s82, 0x80
	s_mov_b32 m0, s34
	ds_read_b128 v[194:197], v140 offset:49152
	buffer_load_dwordx4 v134, s[64:67], s52 offen lds
	s_add_i32 s82, s82, 0x200080
	s_mov_b32 m0, s35
	ds_read_b128 v[198:201], v140 offset:50176
	buffer_load_dwordx4 v136, s[64:67], s52 offen lds
	s_mov_b32 m0, s37
	ds_read_b128 v[202:205], v140 offset:51200
	buffer_load_dwordx4 v134, s[64:67], s82 offen lds
	s_mov_b32 m0, s44
	ds_read_b128 v[228:231], v140 offset:52224
	buffer_load_dwordx4 v136, s[64:67], s82 offen lds
	s_mov_b32 m0, s14
	ds_read_b128 v[232:235], v140 offset:53248
	buffer_load_dwordx4 v131, s[60:63], s73 offen lds
	s_mov_b32 m0, s36
	ds_read_b128 v[236:239], v140 offset:54272
	buffer_load_dwordx4 v135, s[60:63], s73 offen lds
	ds_read_b128 v[240:243], v140 offset:55296
	ds_read_b128 v[244:247], v140 offset:56320
	s_waitcnt vmcnt(8)
	s_waitcnt lgkmcnt(0)
	s_setprio 1
	s_barrier
	v_mfma_f32_16x16x32_bf16 v[94:97], v[142:145], v[194:197], v[94:97]
	v_mfma_f32_16x16x32_bf16 v[94:97], v[154:157], v[198:201], v[94:97]
	v_mfma_f32_16x16x32_bf16 v[90:93], v[170:173], v[194:197], v[90:93]
	v_mfma_f32_16x16x32_bf16 v[90:93], v[174:177], v[198:201], v[90:93]
	v_mfma_f32_16x16x32_bf16 v[26:29], v[186:189], v[194:197], v[26:29]
	v_mfma_f32_16x16x32_bf16 v[26:29], v[190:193], v[198:201], v[26:29]
	v_mfma_f32_16x16x32_bf16 v[30:33], v[178:181], v[194:197], v[30:33]
	v_mfma_f32_16x16x32_bf16 v[30:33], v[182:185], v[198:201], v[30:33]
	v_mfma_f32_16x16x32_bf16 v[22:25], v[178:181], v[202:205], v[22:25]
	v_mfma_f32_16x16x32_bf16 v[22:25], v[182:185], v[228:231], v[22:25]
	v_mfma_f32_16x16x32_bf16 v[18:21], v[186:189], v[202:205], v[18:21]
	v_mfma_f32_16x16x32_bf16 v[18:21], v[190:193], v[228:231], v[18:21]
	v_mfma_f32_16x16x32_bf16 v[82:85], v[170:173], v[202:205], v[82:85]
	v_mfma_f32_16x16x32_bf16 v[82:85], v[174:177], v[228:231], v[82:85]
	v_mfma_f32_16x16x32_bf16 v[86:89], v[142:145], v[202:205], v[86:89]
	v_mfma_f32_16x16x32_bf16 v[86:89], v[154:157], v[228:231], v[86:89]
	v_mfma_f32_16x16x32_bf16 v[78:81], v[142:145], v[232:235], v[78:81]
	v_mfma_f32_16x16x32_bf16 v[78:81], v[154:157], v[236:239], v[78:81]
	v_mfma_f32_16x16x32_bf16 v[74:77], v[170:173], v[232:235], v[74:77]
	v_mfma_f32_16x16x32_bf16 v[74:77], v[174:177], v[236:239], v[74:77]
	v_mfma_f32_16x16x32_bf16 v[10:13], v[186:189], v[232:235], v[10:13]
	v_mfma_f32_16x16x32_bf16 v[10:13], v[190:193], v[236:239], v[10:13]
	v_mfma_f32_16x16x32_bf16 v[14:17], v[178:181], v[232:235], v[14:17]
	v_mfma_f32_16x16x32_bf16 v[14:17], v[182:185], v[236:239], v[14:17]
	v_mfma_f32_16x16x32_bf16 v[6:9], v[178:181], v[240:243], v[6:9]
	v_mfma_f32_16x16x32_bf16 v[6:9], v[182:185], v[244:247], v[6:9]
	v_mfma_f32_16x16x32_bf16 v[2:5], v[186:189], v[240:243], v[2:5]
	v_mfma_f32_16x16x32_bf16 v[2:5], v[190:193], v[244:247], v[2:5]
	v_mfma_f32_16x16x32_bf16 v[66:69], v[170:173], v[240:243], v[66:69]
	v_mfma_f32_16x16x32_bf16 v[66:69], v[174:177], v[244:247], v[66:69]
	v_mfma_f32_16x16x32_bf16 v[70:73], v[142:145], v[240:243], v[70:73]
	v_mfma_f32_16x16x32_bf16 v[70:73], v[154:157], v[244:247], v[70:73]
	s_barrier
	s_setprio 0
	s_add_i32 s72, s72, 2
	s_addk_i32 s30, 0x100
	s_addk_i32 s31, 0x100
	s_cmpk_gt_u32 s72, 0x7d
	s_cbranch_scc0 .LBB0_1193
	s_and_b64 vcc, exec, s[42:43]
	s_cbranch_vccz .LBB0_1196
	s_barrier
	s_setprio 2

.LBB0_1219:
	s_setprio 0
	s_andn2_b64 vcc, exec, s[8:9]
	s_mov_b32 s18, s84
	s_mov_b32 s12, s82
	s_mov_b32 s22, s46
	s_mov_b32 s19, s14
	s_cbranch_vccz .LBB0_1241

.LBB0_1223:
	v_add_u32_e32 v141, 0x10000, v139
	ds_read_b128 v[142:145], v141
	ds_read_b128 v[154:157], v141 offset:1024
	ds_read_b128 v[170:173], v141 offset:2048
	ds_read_b128 v[174:177], v141 offset:3072
	v_add_u32_e32 v141, 0x14000, v139
	ds_read_b128 v[178:181], v141
	ds_read_b128 v[182:185], v141 offset:1024
	ds_read_b128 v[186:189], v141 offset:2048
	ds_read_b128 v[190:193], v141 offset:3072
	s_add_i32 s27, s19, 0xffe00080
	s_cmpk_eq_i32 s26, 0x7c
	s_cselect_b32 s52, s8, s27
	s_cselect_b32 s47, s9, s22
	s_or_b32 s27, s52, 0x80
	s_mov_b32 m0, s71
	ds_read_b128 v[194:197], v140
	ds_read_b128 v[198:201], v140 offset:1024
	ds_read_b128 v[202:205], v140 offset:2048
	ds_read_b128 v[228:231], v140 offset:3072
	ds_read_b128 v[232:235], v140 offset:4096
	ds_read_b128 v[236:239], v140 offset:5120
	ds_read_b128 v[240:243], v140 offset:6144
	ds_read_b128 v[244:247], v140 offset:7168
	buffer_load_dwordx4 v131, s[60:63], s19 offen lds
	s_mov_b32 m0, s72
	s_nop 0
	buffer_load_dwordx4 v135, s[60:63], s19 offen lds
	s_waitcnt vmcnt(8)
	s_waitcnt lgkmcnt(0)
	s_setprio 1
	s_barrier
	v_mfma_f32_16x16x32_bf16 v[126:129], v[142:145], v[194:197], v[126:129]
	v_mfma_f32_16x16x32_bf16 v[126:129], v[154:157], v[198:201], v[126:129]
	v_mfma_f32_16x16x32_bf16 v[122:125], v[170:173], v[194:197], v[122:125]
	v_mfma_f32_16x16x32_bf16 v[122:125], v[174:177], v[198:201], v[122:125]
	v_mfma_f32_16x16x32_bf16 v[58:61], v[186:189], v[194:197], v[58:61]
	v_mfma_f32_16x16x32_bf16 v[58:61], v[190:193], v[198:201], v[58:61]
	v_mfma_f32_16x16x32_bf16 v[62:65], v[178:181], v[194:197], v[62:65]
	v_mfma_f32_16x16x32_bf16 v[62:65], v[182:185], v[198:201], v[62:65]
	v_mfma_f32_16x16x32_bf16 v[54:57], v[178:181], v[202:205], v[54:57]
	v_mfma_f32_16x16x32_bf16 v[54:57], v[182:185], v[228:231], v[54:57]
	v_mfma_f32_16x16x32_bf16 v[50:53], v[186:189], v[202:205], v[50:53]
	v_mfma_f32_16x16x32_bf16 v[50:53], v[190:193], v[228:231], v[50:53]
	v_mfma_f32_16x16x32_bf16 v[114:117], v[170:173], v[202:205], v[114:117]
	v_mfma_f32_16x16x32_bf16 v[114:117], v[174:177], v[228:231], v[114:117]
	v_mfma_f32_16x16x32_bf16 v[118:121], v[142:145], v[202:205], v[118:121]
	v_mfma_f32_16x16x32_bf16 v[118:121], v[154:157], v[228:231], v[118:121]
	v_mfma_f32_16x16x32_bf16 v[110:113], v[142:145], v[232:235], v[110:113]
	v_mfma_f32_16x16x32_bf16 v[110:113], v[154:157], v[236:239], v[110:113]
	v_mfma_f32_16x16x32_bf16 v[106:109], v[170:173], v[232:235], v[106:109]
	v_mfma_f32_16x16x32_bf16 v[106:109], v[174:177], v[236:239], v[106:109]
	v_mfma_f32_16x16x32_bf16 v[42:45], v[186:189], v[232:235], v[42:45]
	v_mfma_f32_16x16x32_bf16 v[42:45], v[190:193], v[236:239], v[42:45]
	v_mfma_f32_16x16x32_bf16 v[46:49], v[178:181], v[232:235], v[46:49]
	v_mfma_f32_16x16x32_bf16 v[46:49], v[182:185], v[236:239], v[46:49]
	v_mfma_f32_16x16x32_bf16 v[38:41], v[178:181], v[240:243], v[38:41]
	v_mfma_f32_16x16x32_bf16 v[38:41], v[182:185], v[244:247], v[38:41]
	v_mfma_f32_16x16x32_bf16 v[34:37], v[186:189], v[240:243], v[34:37]
	v_mfma_f32_16x16x32_bf16 v[34:37], v[190:193], v[244:247], v[34:37]
	v_mfma_f32_16x16x32_bf16 v[98:101], v[170:173], v[240:243], v[98:101]
	v_mfma_f32_16x16x32_bf16 v[98:101], v[174:177], v[244:247], v[98:101]
	v_mfma_f32_16x16x32_bf16 v[102:105], v[142:145], v[240:243], v[102:105]
	v_mfma_f32_16x16x32_bf16 v[102:105], v[154:157], v[244:247], v[102:105]
	s_barrier
	s_setprio 0
	s_mov_b32 s66, s62
	s_mov_b32 s67, s63
	s_mov_b32 m0, s2
	ds_read_b128 v[194:197], v140 offset:16384
	buffer_load_dwordx4 v134, s[64:67], s47 offen lds
	s_add_i32 s53, s47, 0x200000
	s_mov_b32 m0, s21
	ds_read_b128 v[198:201], v140 offset:17408
	buffer_load_dwordx4 v136, s[64:67], s47 offen lds
	s_mov_b32 m0, s23
	ds_read_b128 v[202:205], v140 offset:18432
	buffer_load_dwordx4 v134, s[64:67], s53 offen lds
	s_mov_b32 m0, s24
	ds_read_b128 v[228:231], v140 offset:19456
	buffer_load_dwordx4 v136, s[64:67], s53 offen lds
	s_mov_b32 m0, s16
	ds_read_b128 v[232:235], v140 offset:20480
	buffer_load_dwordx4 v131, s[60:63], s52 offen lds
	s_mov_b32 m0, s25
	ds_read_b128 v[236:239], v140 offset:21504
	buffer_load_dwordx4 v135, s[60:63], s52 offen lds
	ds_read_b128 v[240:243], v140 offset:22528
	ds_read_b128 v[244:247], v140 offset:23552
	s_waitcnt vmcnt(8)
	s_waitcnt lgkmcnt(0)
	s_setprio 1
	s_barrier
	v_mfma_f32_16x16x32_bf16 v[94:97], v[142:145], v[194:197], v[94:97]
	v_mfma_f32_16x16x32_bf16 v[94:97], v[154:157], v[198:201], v[94:97]
	v_mfma_f32_16x16x32_bf16 v[90:93], v[170:173], v[194:197], v[90:93]
	v_mfma_f32_16x16x32_bf16 v[90:93], v[174:177], v[198:201], v[90:93]
	v_mfma_f32_16x16x32_bf16 v[26:29], v[186:189], v[194:197], v[26:29]
	v_mfma_f32_16x16x32_bf16 v[26:29], v[190:193], v[198:201], v[26:29]
	v_mfma_f32_16x16x32_bf16 v[30:33], v[178:181], v[194:197], v[30:33]
	v_mfma_f32_16x16x32_bf16 v[30:33], v[182:185], v[198:201], v[30:33]
	v_mfma_f32_16x16x32_bf16 v[22:25], v[178:181], v[202:205], v[22:25]
	v_mfma_f32_16x16x32_bf16 v[22:25], v[182:185], v[228:231], v[22:25]
	v_mfma_f32_16x16x32_bf16 v[18:21], v[186:189], v[202:205], v[18:21]
	v_mfma_f32_16x16x32_bf16 v[18:21], v[190:193], v[228:231], v[18:21]
	v_mfma_f32_16x16x32_bf16 v[82:85], v[170:173], v[202:205], v[82:85]
	v_mfma_f32_16x16x32_bf16 v[82:85], v[174:177], v[228:231], v[82:85]
	v_mfma_f32_16x16x32_bf16 v[86:89], v[142:145], v[202:205], v[86:89]
	v_mfma_f32_16x16x32_bf16 v[86:89], v[154:157], v[228:231], v[86:89]
	v_mfma_f32_16x16x32_bf16 v[78:81], v[142:145], v[232:235], v[78:81]
	v_mfma_f32_16x16x32_bf16 v[78:81], v[154:157], v[236:239], v[78:81]
	v_mfma_f32_16x16x32_bf16 v[74:77], v[170:173], v[232:235], v[74:77]
	v_mfma_f32_16x16x32_bf16 v[74:77], v[174:177], v[236:239], v[74:77]
	v_mfma_f32_16x16x32_bf16 v[10:13], v[186:189], v[232:235], v[10:13]
	v_mfma_f32_16x16x32_bf16 v[10:13], v[190:193], v[236:239], v[10:13]
	v_mfma_f32_16x16x32_bf16 v[14:17], v[178:181], v[232:235], v[14:17]
	v_mfma_f32_16x16x32_bf16 v[14:17], v[182:185], v[236:239], v[14:17]
	v_mfma_f32_16x16x32_bf16 v[6:9], v[178:181], v[240:243], v[6:9]
	v_mfma_f32_16x16x32_bf16 v[6:9], v[182:185], v[244:247], v[6:9]
	v_mfma_f32_16x16x32_bf16 v[2:5], v[186:189], v[240:243], v[2:5]
	v_mfma_f32_16x16x32_bf16 v[2:5], v[190:193], v[244:247], v[2:5]
	v_mfma_f32_16x16x32_bf16 v[66:69], v[170:173], v[240:243], v[66:69]
	v_mfma_f32_16x16x32_bf16 v[66:69], v[174:177], v[244:247], v[66:69]
	v_mfma_f32_16x16x32_bf16 v[70:73], v[142:145], v[240:243], v[70:73]
	v_mfma_f32_16x16x32_bf16 v[70:73], v[154:157], v[244:247], v[70:73]
	s_barrier
	s_setprio 0
	v_add_u32_e32 v141, 0x18000, v139
	ds_read_b128 v[142:145], v141
	ds_read_b128 v[154:157], v141 offset:1024
	ds_read_b128 v[170:173], v141 offset:2048
	ds_read_b128 v[174:177], v141 offset:3072
	v_add_u32_e32 v141, 0x1c000, v139
	ds_read_b128 v[178:181], v141
	ds_read_b128 v[182:185], v141 offset:1024
	ds_read_b128 v[186:189], v141 offset:2048
	ds_read_b128 v[190:193], v141 offset:3072
	s_add_i32 s52, s52, 0x200000
	s_mov_b32 m0, s30
	ds_read_b128 v[194:197], v140 offset:32768
	ds_read_b128 v[198:201], v140 offset:33792
	ds_read_b128 v[202:205], v140 offset:34816
	ds_read_b128 v[228:231], v140 offset:35840
	ds_read_b128 v[232:235], v140 offset:36864
	ds_read_b128 v[236:239], v140 offset:37888
	ds_read_b128 v[240:243], v140 offset:38912
	ds_read_b128 v[244:247], v140 offset:39936
	buffer_load_dwordx4 v131, s[60:63], s52 offen lds
	s_mov_b32 m0, s31
	s_nop 0
	buffer_load_dwordx4 v135, s[60:63], s52 offen lds
	s_waitcnt vmcnt(8)
	s_waitcnt lgkmcnt(0)
	s_setprio 1
	s_barrier
	v_mfma_f32_16x16x32_bf16 v[126:129], v[142:145], v[194:197], v[126:129]
	v_mfma_f32_16x16x32_bf16 v[126:129], v[154:157], v[198:201], v[126:129]
	v_mfma_f32_16x16x32_bf16 v[122:125], v[170:173], v[194:197], v[122:125]
	v_mfma_f32_16x16x32_bf16 v[122:125], v[174:177], v[198:201], v[122:125]
	v_mfma_f32_16x16x32_bf16 v[58:61], v[186:189], v[194:197], v[58:61]
	v_mfma_f32_16x16x32_bf16 v[58:61], v[190:193], v[198:201], v[58:61]
	v_mfma_f32_16x16x32_bf16 v[62:65], v[178:181], v[194:197], v[62:65]
	v_mfma_f32_16x16x32_bf16 v[62:65], v[182:185], v[198:201], v[62:65]
	v_mfma_f32_16x16x32_bf16 v[54:57], v[178:181], v[202:205], v[54:57]
	v_mfma_f32_16x16x32_bf16 v[54:57], v[182:185], v[228:231], v[54:57]
	v_mfma_f32_16x16x32_bf16 v[50:53], v[186:189], v[202:205], v[50:53]
	v_mfma_f32_16x16x32_bf16 v[50:53], v[190:193], v[228:231], v[50:53]
	v_mfma_f32_16x16x32_bf16 v[114:117], v[170:173], v[202:205], v[114:117]
	v_mfma_f32_16x16x32_bf16 v[114:117], v[174:177], v[228:231], v[114:117]
	v_mfma_f32_16x16x32_bf16 v[118:121], v[142:145], v[202:205], v[118:121]
	v_mfma_f32_16x16x32_bf16 v[118:121], v[154:157], v[228:231], v[118:121]
	v_mfma_f32_16x16x32_bf16 v[110:113], v[142:145], v[232:235], v[110:113]
	v_mfma_f32_16x16x32_bf16 v[110:113], v[154:157], v[236:239], v[110:113]
	v_mfma_f32_16x16x32_bf16 v[106:109], v[170:173], v[232:235], v[106:109]
	v_mfma_f32_16x16x32_bf16 v[106:109], v[174:177], v[236:239], v[106:109]
	v_mfma_f32_16x16x32_bf16 v[42:45], v[186:189], v[232:235], v[42:45]
	v_mfma_f32_16x16x32_bf16 v[42:45], v[190:193], v[236:239], v[42:45]
	v_mfma_f32_16x16x32_bf16 v[46:49], v[178:181], v[232:235], v[46:49]
	v_mfma_f32_16x16x32_bf16 v[46:49], v[182:185], v[236:239], v[46:49]
	v_mfma_f32_16x16x32_bf16 v[38:41], v[178:181], v[240:243], v[38:41]
	v_mfma_f32_16x16x32_bf16 v[38:41], v[182:185], v[244:247], v[38:41]
	v_mfma_f32_16x16x32_bf16 v[34:37], v[186:189], v[240:243], v[34:37]
	v_mfma_f32_16x16x32_bf16 v[34:37], v[190:193], v[244:247], v[34:37]
	v_mfma_f32_16x16x32_bf16 v[98:101], v[170:173], v[240:243], v[98:101]
	v_mfma_f32_16x16x32_bf16 v[98:101], v[174:177], v[244:247], v[98:101]
	v_mfma_f32_16x16x32_bf16 v[102:105], v[142:145], v[240:243], v[102:105]
	v_mfma_f32_16x16x32_bf16 v[102:105], v[154:157], v[244:247], v[102:105]
	s_barrier
	s_setprio 0
	s_or_b32 s52, s47, 0x80
	s_mov_b32 m0, s33
	ds_read_b128 v[194:197], v140 offset:49152
	buffer_load_dwordx4 v134, s[64:67], s52 offen lds
	s_add_i32 s47, s47, 0x200080
	s_mov_b32 m0, s34
	ds_read_b128 v[198:201], v140 offset:50176
	buffer_load_dwordx4 v136, s[64:67], s52 offen lds
	s_mov_b32 m0, s37
	ds_read_b128 v[202:205], v140 offset:51200
	buffer_load_dwordx4 v134, s[64:67], s47 offen lds
	s_mov_b32 m0, s68
	ds_read_b128 v[228:231], v140 offset:52224
	buffer_load_dwordx4 v136, s[64:67], s47 offen lds
	s_mov_b32 m0, s35
	ds_read_b128 v[232:235], v140 offset:53248
	buffer_load_dwordx4 v131, s[60:63], s27 offen lds
	s_mov_b32 m0, s36
	ds_read_b128 v[236:239], v140 offset:54272
	buffer_load_dwordx4 v135, s[60:63], s27 offen lds
	ds_read_b128 v[240:243], v140 offset:55296
	ds_read_b128 v[244:247], v140 offset:56320
	s_waitcnt vmcnt(8)
	s_waitcnt lgkmcnt(0)
	s_setprio 1
	s_barrier
	v_mfma_f32_16x16x32_bf16 v[94:97], v[142:145], v[194:197], v[94:97]
	v_mfma_f32_16x16x32_bf16 v[94:97], v[154:157], v[198:201], v[94:97]
	v_mfma_f32_16x16x32_bf16 v[90:93], v[170:173], v[194:197], v[90:93]
	v_mfma_f32_16x16x32_bf16 v[90:93], v[174:177], v[198:201], v[90:93]
	v_mfma_f32_16x16x32_bf16 v[26:29], v[186:189], v[194:197], v[26:29]
	v_mfma_f32_16x16x32_bf16 v[26:29], v[190:193], v[198:201], v[26:29]
	v_mfma_f32_16x16x32_bf16 v[30:33], v[178:181], v[194:197], v[30:33]
	v_mfma_f32_16x16x32_bf16 v[30:33], v[182:185], v[198:201], v[30:33]
	v_mfma_f32_16x16x32_bf16 v[22:25], v[178:181], v[202:205], v[22:25]
	v_mfma_f32_16x16x32_bf16 v[22:25], v[182:185], v[228:231], v[22:25]
	v_mfma_f32_16x16x32_bf16 v[18:21], v[186:189], v[202:205], v[18:21]
	v_mfma_f32_16x16x32_bf16 v[18:21], v[190:193], v[228:231], v[18:21]
	v_mfma_f32_16x16x32_bf16 v[82:85], v[170:173], v[202:205], v[82:85]
	v_mfma_f32_16x16x32_bf16 v[82:85], v[174:177], v[228:231], v[82:85]
	v_mfma_f32_16x16x32_bf16 v[86:89], v[142:145], v[202:205], v[86:89]
	v_mfma_f32_16x16x32_bf16 v[86:89], v[154:157], v[228:231], v[86:89]
	v_mfma_f32_16x16x32_bf16 v[78:81], v[142:145], v[232:235], v[78:81]
	v_mfma_f32_16x16x32_bf16 v[78:81], v[154:157], v[236:239], v[78:81]
	v_mfma_f32_16x16x32_bf16 v[74:77], v[170:173], v[232:235], v[74:77]
	v_mfma_f32_16x16x32_bf16 v[74:77], v[174:177], v[236:239], v[74:77]
	v_mfma_f32_16x16x32_bf16 v[10:13], v[186:189], v[232:235], v[10:13]
	v_mfma_f32_16x16x32_bf16 v[10:13], v[190:193], v[236:239], v[10:13]
	v_mfma_f32_16x16x32_bf16 v[14:17], v[178:181], v[232:235], v[14:17]
	v_mfma_f32_16x16x32_bf16 v[14:17], v[182:185], v[236:239], v[14:17]
	v_mfma_f32_16x16x32_bf16 v[6:9], v[178:181], v[240:243], v[6:9]
	v_mfma_f32_16x16x32_bf16 v[6:9], v[182:185], v[244:247], v[6:9]
	v_mfma_f32_16x16x32_bf16 v[2:5], v[186:189], v[240:243], v[2:5]
	v_mfma_f32_16x16x32_bf16 v[2:5], v[190:193], v[244:247], v[2:5]
	v_mfma_f32_16x16x32_bf16 v[66:69], v[170:173], v[240:243], v[66:69]
	v_mfma_f32_16x16x32_bf16 v[66:69], v[174:177], v[244:247], v[66:69]
	v_mfma_f32_16x16x32_bf16 v[70:73], v[142:145], v[240:243], v[70:73]
	v_mfma_f32_16x16x32_bf16 v[70:73], v[154:157], v[244:247], v[70:73]
	s_barrier
	s_setprio 0
	s_add_i32 s26, s26, 2
	s_addk_i32 s19, 0x100
	s_addk_i32 s22, 0x100
	s_cmpk_gt_u32 s26, 0x7d
	s_cbranch_scc0 .LBB0_1223
	s_and_b64 vcc, exec, s[42:43]
	s_cbranch_vccz .LBB0_1226
	s_barrier
	s_setprio 2

.LBB0_1249:
	s_setprio 0
	s_andn2_b64 vcc, exec, s[8:9]
	s_mov_b32 s19, s82
	s_mov_b32 s18, s73
	s_mov_b32 s27, s22
	s_mov_b32 s26, s12
	s_cbranch_vccz .LBB0_1271

.LBB0_1253:
	v_add_u32_e32 v141, 0x10000, v139
	ds_read_b128 v[142:145], v141
	ds_read_b128 v[154:157], v141 offset:1024
	ds_read_b128 v[170:173], v141 offset:2048
	ds_read_b128 v[174:177], v141 offset:3072
	v_add_u32_e32 v141, 0x14000, v139
	ds_read_b128 v[178:181], v141
	ds_read_b128 v[182:185], v141 offset:1024
	ds_read_b128 v[186:189], v141 offset:2048
	ds_read_b128 v[190:193], v141 offset:3072
	s_add_i32 s52, s26, 0xfff80080
	s_cmp_eq_u32 s83, 28
	s_cselect_b32 s52, s8, s52
	s_cselect_b32 s85, s9, s27
	s_or_b32 s84, s52, 0x80
	s_mov_b32 m0, s72
	ds_read_b128 v[194:197], v140
	ds_read_b128 v[198:201], v140 offset:1024
	ds_read_b128 v[202:205], v140 offset:2048
	ds_read_b128 v[228:231], v140 offset:3072
	ds_read_b128 v[232:235], v140 offset:4096
	ds_read_b128 v[236:239], v140 offset:5120
	ds_read_b128 v[240:243], v140 offset:6144
	ds_read_b128 v[244:247], v140 offset:7168
	buffer_load_dwordx4 v131, s[60:63], s26 offen lds
	s_mov_b32 m0, s46
	s_nop 0
	buffer_load_dwordx4 v135, s[60:63], s26 offen lds
	s_waitcnt vmcnt(8)
	s_waitcnt lgkmcnt(0)
	s_setprio 1
	s_barrier
	v_mfma_f32_16x16x32_bf16 v[126:129], v[142:145], v[194:197], v[126:129]
	v_mfma_f32_16x16x32_bf16 v[126:129], v[154:157], v[198:201], v[126:129]
	v_mfma_f32_16x16x32_bf16 v[122:125], v[170:173], v[194:197], v[122:125]
	v_mfma_f32_16x16x32_bf16 v[122:125], v[174:177], v[198:201], v[122:125]
	v_mfma_f32_16x16x32_bf16 v[58:61], v[186:189], v[194:197], v[58:61]
	v_mfma_f32_16x16x32_bf16 v[58:61], v[190:193], v[198:201], v[58:61]
	v_mfma_f32_16x16x32_bf16 v[62:65], v[178:181], v[194:197], v[62:65]
	v_mfma_f32_16x16x32_bf16 v[62:65], v[182:185], v[198:201], v[62:65]
	v_mfma_f32_16x16x32_bf16 v[54:57], v[178:181], v[202:205], v[54:57]
	v_mfma_f32_16x16x32_bf16 v[54:57], v[182:185], v[228:231], v[54:57]
	v_mfma_f32_16x16x32_bf16 v[50:53], v[186:189], v[202:205], v[50:53]
	v_mfma_f32_16x16x32_bf16 v[50:53], v[190:193], v[228:231], v[50:53]
	v_mfma_f32_16x16x32_bf16 v[114:117], v[170:173], v[202:205], v[114:117]
	v_mfma_f32_16x16x32_bf16 v[114:117], v[174:177], v[228:231], v[114:117]
	v_mfma_f32_16x16x32_bf16 v[118:121], v[142:145], v[202:205], v[118:121]
	v_mfma_f32_16x16x32_bf16 v[118:121], v[154:157], v[228:231], v[118:121]
	v_mfma_f32_16x16x32_bf16 v[110:113], v[142:145], v[232:235], v[110:113]
	v_mfma_f32_16x16x32_bf16 v[110:113], v[154:157], v[236:239], v[110:113]
	v_mfma_f32_16x16x32_bf16 v[106:109], v[170:173], v[232:235], v[106:109]
	v_mfma_f32_16x16x32_bf16 v[106:109], v[174:177], v[236:239], v[106:109]
	v_mfma_f32_16x16x32_bf16 v[42:45], v[186:189], v[232:235], v[42:45]
	v_mfma_f32_16x16x32_bf16 v[42:45], v[190:193], v[236:239], v[42:45]
	v_mfma_f32_16x16x32_bf16 v[46:49], v[178:181], v[232:235], v[46:49]
	v_mfma_f32_16x16x32_bf16 v[46:49], v[182:185], v[236:239], v[46:49]
	v_mfma_f32_16x16x32_bf16 v[38:41], v[178:181], v[240:243], v[38:41]
	v_mfma_f32_16x16x32_bf16 v[38:41], v[182:185], v[244:247], v[38:41]
	v_mfma_f32_16x16x32_bf16 v[34:37], v[186:189], v[240:243], v[34:37]
	v_mfma_f32_16x16x32_bf16 v[34:37], v[190:193], v[244:247], v[34:37]
	v_mfma_f32_16x16x32_bf16 v[98:101], v[170:173], v[240:243], v[98:101]
	v_mfma_f32_16x16x32_bf16 v[98:101], v[174:177], v[244:247], v[98:101]
	v_mfma_f32_16x16x32_bf16 v[102:105], v[142:145], v[240:243], v[102:105]
	v_mfma_f32_16x16x32_bf16 v[102:105], v[154:157], v[244:247], v[102:105]
	s_barrier
	s_setprio 0
	s_mov_b32 s70, s62
	s_mov_b32 s71, s63
	s_mov_b32 m0, s21
	ds_read_b128 v[194:197], v140 offset:16384
	buffer_load_dwordx4 v134, s[68:71], s85 offen lds
	s_add_i32 s53, s85, 0x80000
	s_mov_b32 m0, s23
	ds_read_b128 v[198:201], v140 offset:17408
	buffer_load_dwordx4 v136, s[68:71], s85 offen lds
	s_mov_b32 m0, s24
	ds_read_b128 v[202:205], v140 offset:18432
	buffer_load_dwordx4 v134, s[68:71], s53 offen lds
	s_mov_b32 m0, s25
	ds_read_b128 v[228:231], v140 offset:19456
	buffer_load_dwordx4 v136, s[68:71], s53 offen lds
	s_mov_b32 m0, s16
	ds_read_b128 v[232:235], v140 offset:20480
	buffer_load_dwordx4 v131, s[60:63], s52 offen lds
	s_mov_b32 m0, s30
	ds_read_b128 v[236:239], v140 offset:21504
	buffer_load_dwordx4 v135, s[60:63], s52 offen lds
	ds_read_b128 v[240:243], v140 offset:22528
	ds_read_b128 v[244:247], v140 offset:23552
	s_waitcnt vmcnt(8)
	s_waitcnt lgkmcnt(0)
	s_setprio 1
	s_barrier
	v_mfma_f32_16x16x32_bf16 v[94:97], v[142:145], v[194:197], v[94:97]
	v_mfma_f32_16x16x32_bf16 v[94:97], v[154:157], v[198:201], v[94:97]
	v_mfma_f32_16x16x32_bf16 v[90:93], v[170:173], v[194:197], v[90:93]
	v_mfma_f32_16x16x32_bf16 v[90:93], v[174:177], v[198:201], v[90:93]
	v_mfma_f32_16x16x32_bf16 v[26:29], v[186:189], v[194:197], v[26:29]
	v_mfma_f32_16x16x32_bf16 v[26:29], v[190:193], v[198:201], v[26:29]
	v_mfma_f32_16x16x32_bf16 v[30:33], v[178:181], v[194:197], v[30:33]
	v_mfma_f32_16x16x32_bf16 v[30:33], v[182:185], v[198:201], v[30:33]
	v_mfma_f32_16x16x32_bf16 v[22:25], v[178:181], v[202:205], v[22:25]
	v_mfma_f32_16x16x32_bf16 v[22:25], v[182:185], v[228:231], v[22:25]
	v_mfma_f32_16x16x32_bf16 v[18:21], v[186:189], v[202:205], v[18:21]
	v_mfma_f32_16x16x32_bf16 v[18:21], v[190:193], v[228:231], v[18:21]
	v_mfma_f32_16x16x32_bf16 v[82:85], v[170:173], v[202:205], v[82:85]
	v_mfma_f32_16x16x32_bf16 v[82:85], v[174:177], v[228:231], v[82:85]
	v_mfma_f32_16x16x32_bf16 v[86:89], v[142:145], v[202:205], v[86:89]
	v_mfma_f32_16x16x32_bf16 v[86:89], v[154:157], v[228:231], v[86:89]
	v_mfma_f32_16x16x32_bf16 v[78:81], v[142:145], v[232:235], v[78:81]
	v_mfma_f32_16x16x32_bf16 v[78:81], v[154:157], v[236:239], v[78:81]
	v_mfma_f32_16x16x32_bf16 v[74:77], v[170:173], v[232:235], v[74:77]
	v_mfma_f32_16x16x32_bf16 v[74:77], v[174:177], v[236:239], v[74:77]
	v_mfma_f32_16x16x32_bf16 v[10:13], v[186:189], v[232:235], v[10:13]
	v_mfma_f32_16x16x32_bf16 v[10:13], v[190:193], v[236:239], v[10:13]
	v_mfma_f32_16x16x32_bf16 v[14:17], v[178:181], v[232:235], v[14:17]
	v_mfma_f32_16x16x32_bf16 v[14:17], v[182:185], v[236:239], v[14:17]
	v_mfma_f32_16x16x32_bf16 v[6:9], v[178:181], v[240:243], v[6:9]
	v_mfma_f32_16x16x32_bf16 v[6:9], v[182:185], v[244:247], v[6:9]
	v_mfma_f32_16x16x32_bf16 v[2:5], v[186:189], v[240:243], v[2:5]
	v_mfma_f32_16x16x32_bf16 v[2:5], v[190:193], v[244:247], v[2:5]
	v_mfma_f32_16x16x32_bf16 v[66:69], v[170:173], v[240:243], v[66:69]
	v_mfma_f32_16x16x32_bf16 v[66:69], v[174:177], v[244:247], v[66:69]
	v_mfma_f32_16x16x32_bf16 v[70:73], v[142:145], v[240:243], v[70:73]
	v_mfma_f32_16x16x32_bf16 v[70:73], v[154:157], v[244:247], v[70:73]
	s_barrier
	s_setprio 0
	v_add_u32_e32 v141, 0x18000, v139
	ds_read_b128 v[142:145], v141
	ds_read_b128 v[154:157], v141 offset:1024
	ds_read_b128 v[170:173], v141 offset:2048
	ds_read_b128 v[174:177], v141 offset:3072
	v_add_u32_e32 v141, 0x1c000, v139
	ds_read_b128 v[178:181], v141
	ds_read_b128 v[182:185], v141 offset:1024
	ds_read_b128 v[186:189], v141 offset:2048
	ds_read_b128 v[190:193], v141 offset:3072
	s_add_i32 s52, s52, 0x80000
	s_mov_b32 m0, s31
	ds_read_b128 v[194:197], v140 offset:32768
	ds_read_b128 v[198:201], v140 offset:33792
	ds_read_b128 v[202:205], v140 offset:34816
	ds_read_b128 v[228:231], v140 offset:35840
	ds_read_b128 v[232:235], v140 offset:36864
	ds_read_b128 v[236:239], v140 offset:37888
	ds_read_b128 v[240:243], v140 offset:38912
	ds_read_b128 v[244:247], v140 offset:39936
	buffer_load_dwordx4 v131, s[60:63], s52 offen lds
	s_mov_b32 m0, s33
	s_nop 0
	buffer_load_dwordx4 v135, s[60:63], s52 offen lds
	s_waitcnt vmcnt(8)
	s_waitcnt lgkmcnt(0)
	s_setprio 1
	s_barrier
	v_mfma_f32_16x16x32_bf16 v[126:129], v[142:145], v[194:197], v[126:129]
	v_mfma_f32_16x16x32_bf16 v[126:129], v[154:157], v[198:201], v[126:129]
	v_mfma_f32_16x16x32_bf16 v[122:125], v[170:173], v[194:197], v[122:125]
	v_mfma_f32_16x16x32_bf16 v[122:125], v[174:177], v[198:201], v[122:125]
	v_mfma_f32_16x16x32_bf16 v[58:61], v[186:189], v[194:197], v[58:61]
	v_mfma_f32_16x16x32_bf16 v[58:61], v[190:193], v[198:201], v[58:61]
	v_mfma_f32_16x16x32_bf16 v[62:65], v[178:181], v[194:197], v[62:65]
	v_mfma_f32_16x16x32_bf16 v[62:65], v[182:185], v[198:201], v[62:65]
	v_mfma_f32_16x16x32_bf16 v[54:57], v[178:181], v[202:205], v[54:57]
	v_mfma_f32_16x16x32_bf16 v[54:57], v[182:185], v[228:231], v[54:57]
	v_mfma_f32_16x16x32_bf16 v[50:53], v[186:189], v[202:205], v[50:53]
	v_mfma_f32_16x16x32_bf16 v[50:53], v[190:193], v[228:231], v[50:53]
	v_mfma_f32_16x16x32_bf16 v[114:117], v[170:173], v[202:205], v[114:117]
	v_mfma_f32_16x16x32_bf16 v[114:117], v[174:177], v[228:231], v[114:117]
	v_mfma_f32_16x16x32_bf16 v[118:121], v[142:145], v[202:205], v[118:121]
	v_mfma_f32_16x16x32_bf16 v[118:121], v[154:157], v[228:231], v[118:121]
	v_mfma_f32_16x16x32_bf16 v[110:113], v[142:145], v[232:235], v[110:113]
	v_mfma_f32_16x16x32_bf16 v[110:113], v[154:157], v[236:239], v[110:113]
	v_mfma_f32_16x16x32_bf16 v[106:109], v[170:173], v[232:235], v[106:109]
	v_mfma_f32_16x16x32_bf16 v[106:109], v[174:177], v[236:239], v[106:109]
	v_mfma_f32_16x16x32_bf16 v[42:45], v[186:189], v[232:235], v[42:45]
	v_mfma_f32_16x16x32_bf16 v[42:45], v[190:193], v[236:239], v[42:45]
	v_mfma_f32_16x16x32_bf16 v[46:49], v[178:181], v[232:235], v[46:49]
	v_mfma_f32_16x16x32_bf16 v[46:49], v[182:185], v[236:239], v[46:49]
	v_mfma_f32_16x16x32_bf16 v[38:41], v[178:181], v[240:243], v[38:41]
	v_mfma_f32_16x16x32_bf16 v[38:41], v[182:185], v[244:247], v[38:41]
	v_mfma_f32_16x16x32_bf16 v[34:37], v[186:189], v[240:243], v[34:37]
	v_mfma_f32_16x16x32_bf16 v[34:37], v[190:193], v[244:247], v[34:37]
	v_mfma_f32_16x16x32_bf16 v[98:101], v[170:173], v[240:243], v[98:101]
	v_mfma_f32_16x16x32_bf16 v[98:101], v[174:177], v[244:247], v[98:101]
	v_mfma_f32_16x16x32_bf16 v[102:105], v[142:145], v[240:243], v[102:105]
	v_mfma_f32_16x16x32_bf16 v[102:105], v[154:157], v[244:247], v[102:105]
	s_barrier
	s_setprio 0
	s_or_b32 s52, s85, 0x80
	s_mov_b32 m0, s34
	ds_read_b128 v[194:197], v140 offset:49152
	buffer_load_dwordx4 v134, s[68:71], s52 offen lds
	s_add_i32 s85, s85, 0x80080
	s_mov_b32 m0, s35
	ds_read_b128 v[198:201], v140 offset:50176
	buffer_load_dwordx4 v136, s[68:71], s52 offen lds
	s_mov_b32 m0, s37
	ds_read_b128 v[202:205], v140 offset:51200
	buffer_load_dwordx4 v134, s[68:71], s85 offen lds
	s_mov_b32 m0, s65
	ds_read_b128 v[228:231], v140 offset:52224
	buffer_load_dwordx4 v136, s[68:71], s85 offen lds
	s_mov_b32 m0, s14
	ds_read_b128 v[232:235], v140 offset:53248
	buffer_load_dwordx4 v131, s[60:63], s84 offen lds
	s_mov_b32 m0, s36
	ds_read_b128 v[236:239], v140 offset:54272
	buffer_load_dwordx4 v135, s[60:63], s84 offen lds
	ds_read_b128 v[240:243], v140 offset:55296
	ds_read_b128 v[244:247], v140 offset:56320
	s_waitcnt vmcnt(8)
	s_waitcnt lgkmcnt(0)
	s_setprio 1
	s_barrier
	v_mfma_f32_16x16x32_bf16 v[94:97], v[142:145], v[194:197], v[94:97]
	v_mfma_f32_16x16x32_bf16 v[94:97], v[154:157], v[198:201], v[94:97]
	v_mfma_f32_16x16x32_bf16 v[90:93], v[170:173], v[194:197], v[90:93]
	v_mfma_f32_16x16x32_bf16 v[90:93], v[174:177], v[198:201], v[90:93]
	v_mfma_f32_16x16x32_bf16 v[26:29], v[186:189], v[194:197], v[26:29]
	v_mfma_f32_16x16x32_bf16 v[26:29], v[190:193], v[198:201], v[26:29]
	v_mfma_f32_16x16x32_bf16 v[30:33], v[178:181], v[194:197], v[30:33]
	v_mfma_f32_16x16x32_bf16 v[30:33], v[182:185], v[198:201], v[30:33]
	v_mfma_f32_16x16x32_bf16 v[22:25], v[178:181], v[202:205], v[22:25]
	v_mfma_f32_16x16x32_bf16 v[22:25], v[182:185], v[228:231], v[22:25]
	v_mfma_f32_16x16x32_bf16 v[18:21], v[186:189], v[202:205], v[18:21]
	v_mfma_f32_16x16x32_bf16 v[18:21], v[190:193], v[228:231], v[18:21]
	v_mfma_f32_16x16x32_bf16 v[82:85], v[170:173], v[202:205], v[82:85]
	v_mfma_f32_16x16x32_bf16 v[82:85], v[174:177], v[228:231], v[82:85]
	v_mfma_f32_16x16x32_bf16 v[86:89], v[142:145], v[202:205], v[86:89]
	v_mfma_f32_16x16x32_bf16 v[86:89], v[154:157], v[228:231], v[86:89]
	v_mfma_f32_16x16x32_bf16 v[78:81], v[142:145], v[232:235], v[78:81]
	v_mfma_f32_16x16x32_bf16 v[78:81], v[154:157], v[236:239], v[78:81]
	v_mfma_f32_16x16x32_bf16 v[74:77], v[170:173], v[232:235], v[74:77]
	v_mfma_f32_16x16x32_bf16 v[74:77], v[174:177], v[236:239], v[74:77]
	v_mfma_f32_16x16x32_bf16 v[10:13], v[186:189], v[232:235], v[10:13]
	v_mfma_f32_16x16x32_bf16 v[10:13], v[190:193], v[236:239], v[10:13]
	v_mfma_f32_16x16x32_bf16 v[14:17], v[178:181], v[232:235], v[14:17]
	v_mfma_f32_16x16x32_bf16 v[14:17], v[182:185], v[236:239], v[14:17]
	v_mfma_f32_16x16x32_bf16 v[6:9], v[178:181], v[240:243], v[6:9]
	v_mfma_f32_16x16x32_bf16 v[6:9], v[182:185], v[244:247], v[6:9]
	v_mfma_f32_16x16x32_bf16 v[2:5], v[186:189], v[240:243], v[2:5]
	v_mfma_f32_16x16x32_bf16 v[2:5], v[190:193], v[244:247], v[2:5]
	v_mfma_f32_16x16x32_bf16 v[66:69], v[170:173], v[240:243], v[66:69]
	v_mfma_f32_16x16x32_bf16 v[66:69], v[174:177], v[244:247], v[66:69]
	v_mfma_f32_16x16x32_bf16 v[70:73], v[142:145], v[240:243], v[70:73]
	v_mfma_f32_16x16x32_bf16 v[70:73], v[154:157], v[244:247], v[70:73]
	s_barrier
	s_setprio 0
	s_add_i32 s83, s83, 2
	s_addk_i32 s26, 0x100
	s_addk_i32 s27, 0x100
	s_cmp_gt_u32 s83, 29
	s_cbranch_scc0 .LBB0_1253
	s_and_b64 vcc, exec, s[44:45]
	s_cbranch_vccz .LBB0_1256
	s_barrier
	s_setprio 2

.LBB0_1279:
	s_setprio 0
	s_andn2_b64 vcc, exec, s[8:9]
	s_mov_b32 s18, s14
	s_mov_b32 s12, s85
	s_mov_b32 s22, s47
	s_mov_b32 s19, s46
	s_cbranch_vccz .LBB0_1301

.LBB0_1283:
	v_add_u32_e32 v141, 0x10000, v139
	ds_read_b128 v[142:145], v141
	ds_read_b128 v[154:157], v141 offset:1024
	ds_read_b128 v[170:173], v141 offset:2048
	ds_read_b128 v[174:177], v141 offset:3072
	v_add_u32_e32 v141, 0x14000, v139
	ds_read_b128 v[178:181], v141
	ds_read_b128 v[182:185], v141 offset:1024
	ds_read_b128 v[186:189], v141 offset:2048
	ds_read_b128 v[190:193], v141 offset:3072
	s_add_i32 s27, s19, 0xfff80080
	s_cmp_eq_u32 s26, 28
	s_cselect_b32 s52, s8, s27
	s_cselect_b32 s83, s9, s22
	s_or_b32 s27, s52, 0x80
	s_mov_b32 m0, s73
	ds_read_b128 v[194:197], v140
	ds_read_b128 v[198:201], v140 offset:1024
	ds_read_b128 v[202:205], v140 offset:2048
	ds_read_b128 v[228:231], v140 offset:3072
	ds_read_b128 v[232:235], v140 offset:4096
	ds_read_b128 v[236:239], v140 offset:5120
	ds_read_b128 v[240:243], v140 offset:6144
	ds_read_b128 v[244:247], v140 offset:7168
	buffer_load_dwordx4 v131, s[60:63], s19 offen lds
	s_mov_b32 m0, s82
	s_nop 0
	buffer_load_dwordx4 v135, s[60:63], s19 offen lds
	s_waitcnt vmcnt(8)
	s_waitcnt lgkmcnt(0)
	s_setprio 1
	s_barrier
	v_mfma_f32_16x16x32_bf16 v[126:129], v[142:145], v[194:197], v[126:129]
	v_mfma_f32_16x16x32_bf16 v[126:129], v[154:157], v[198:201], v[126:129]
	v_mfma_f32_16x16x32_bf16 v[122:125], v[170:173], v[194:197], v[122:125]
	v_mfma_f32_16x16x32_bf16 v[122:125], v[174:177], v[198:201], v[122:125]
	v_mfma_f32_16x16x32_bf16 v[58:61], v[186:189], v[194:197], v[58:61]
	v_mfma_f32_16x16x32_bf16 v[58:61], v[190:193], v[198:201], v[58:61]
	v_mfma_f32_16x16x32_bf16 v[62:65], v[178:181], v[194:197], v[62:65]
	v_mfma_f32_16x16x32_bf16 v[62:65], v[182:185], v[198:201], v[62:65]
	v_mfma_f32_16x16x32_bf16 v[54:57], v[178:181], v[202:205], v[54:57]
	v_mfma_f32_16x16x32_bf16 v[54:57], v[182:185], v[228:231], v[54:57]
	v_mfma_f32_16x16x32_bf16 v[50:53], v[186:189], v[202:205], v[50:53]
	v_mfma_f32_16x16x32_bf16 v[50:53], v[190:193], v[228:231], v[50:53]
	v_mfma_f32_16x16x32_bf16 v[114:117], v[170:173], v[202:205], v[114:117]
	v_mfma_f32_16x16x32_bf16 v[114:117], v[174:177], v[228:231], v[114:117]
	v_mfma_f32_16x16x32_bf16 v[118:121], v[142:145], v[202:205], v[118:121]
	v_mfma_f32_16x16x32_bf16 v[118:121], v[154:157], v[228:231], v[118:121]
	v_mfma_f32_16x16x32_bf16 v[110:113], v[142:145], v[232:235], v[110:113]
	v_mfma_f32_16x16x32_bf16 v[110:113], v[154:157], v[236:239], v[110:113]
	v_mfma_f32_16x16x32_bf16 v[106:109], v[170:173], v[232:235], v[106:109]
	v_mfma_f32_16x16x32_bf16 v[106:109], v[174:177], v[236:239], v[106:109]
	v_mfma_f32_16x16x32_bf16 v[42:45], v[186:189], v[232:235], v[42:45]
	v_mfma_f32_16x16x32_bf16 v[42:45], v[190:193], v[236:239], v[42:45]
	v_mfma_f32_16x16x32_bf16 v[46:49], v[178:181], v[232:235], v[46:49]
	v_mfma_f32_16x16x32_bf16 v[46:49], v[182:185], v[236:239], v[46:49]
	v_mfma_f32_16x16x32_bf16 v[38:41], v[178:181], v[240:243], v[38:41]
	v_mfma_f32_16x16x32_bf16 v[38:41], v[182:185], v[244:247], v[38:41]
	v_mfma_f32_16x16x32_bf16 v[34:37], v[186:189], v[240:243], v[34:37]
	v_mfma_f32_16x16x32_bf16 v[34:37], v[190:193], v[244:247], v[34:37]
	v_mfma_f32_16x16x32_bf16 v[98:101], v[170:173], v[240:243], v[98:101]
	v_mfma_f32_16x16x32_bf16 v[98:101], v[174:177], v[244:247], v[98:101]
	v_mfma_f32_16x16x32_bf16 v[102:105], v[142:145], v[240:243], v[102:105]
	v_mfma_f32_16x16x32_bf16 v[102:105], v[154:157], v[244:247], v[102:105]
	s_barrier
	s_setprio 0
	s_mov_b32 s70, s62
	s_mov_b32 s71, s63
	s_mov_b32 m0, s21
	ds_read_b128 v[194:197], v140 offset:16384
	buffer_load_dwordx4 v134, s[68:71], s83 offen lds
	s_add_i32 s53, s83, 0x80000
	s_mov_b32 m0, s23
	ds_read_b128 v[198:201], v140 offset:17408
	buffer_load_dwordx4 v136, s[68:71], s83 offen lds
	s_mov_b32 m0, s24
	ds_read_b128 v[202:205], v140 offset:18432
	buffer_load_dwordx4 v134, s[68:71], s53 offen lds
	s_mov_b32 m0, s25
	ds_read_b128 v[228:231], v140 offset:19456
	buffer_load_dwordx4 v136, s[68:71], s53 offen lds
	s_mov_b32 m0, s2
	ds_read_b128 v[232:235], v140 offset:20480
	buffer_load_dwordx4 v131, s[60:63], s52 offen lds
	s_mov_b32 m0, s30
	ds_read_b128 v[236:239], v140 offset:21504
	buffer_load_dwordx4 v135, s[60:63], s52 offen lds
	ds_read_b128 v[240:243], v140 offset:22528
	ds_read_b128 v[244:247], v140 offset:23552
	s_waitcnt vmcnt(8)
	s_waitcnt lgkmcnt(0)
	s_setprio 1
	s_barrier
	v_mfma_f32_16x16x32_bf16 v[94:97], v[142:145], v[194:197], v[94:97]
	v_mfma_f32_16x16x32_bf16 v[94:97], v[154:157], v[198:201], v[94:97]
	v_mfma_f32_16x16x32_bf16 v[90:93], v[170:173], v[194:197], v[90:93]
	v_mfma_f32_16x16x32_bf16 v[90:93], v[174:177], v[198:201], v[90:93]
	v_mfma_f32_16x16x32_bf16 v[26:29], v[186:189], v[194:197], v[26:29]
	v_mfma_f32_16x16x32_bf16 v[26:29], v[190:193], v[198:201], v[26:29]
	v_mfma_f32_16x16x32_bf16 v[30:33], v[178:181], v[194:197], v[30:33]
	v_mfma_f32_16x16x32_bf16 v[30:33], v[182:185], v[198:201], v[30:33]
	v_mfma_f32_16x16x32_bf16 v[22:25], v[178:181], v[202:205], v[22:25]
	v_mfma_f32_16x16x32_bf16 v[22:25], v[182:185], v[228:231], v[22:25]
	v_mfma_f32_16x16x32_bf16 v[18:21], v[186:189], v[202:205], v[18:21]
	v_mfma_f32_16x16x32_bf16 v[18:21], v[190:193], v[228:231], v[18:21]
	v_mfma_f32_16x16x32_bf16 v[82:85], v[170:173], v[202:205], v[82:85]
	v_mfma_f32_16x16x32_bf16 v[82:85], v[174:177], v[228:231], v[82:85]
	v_mfma_f32_16x16x32_bf16 v[86:89], v[142:145], v[202:205], v[86:89]
	v_mfma_f32_16x16x32_bf16 v[86:89], v[154:157], v[228:231], v[86:89]
	v_mfma_f32_16x16x32_bf16 v[78:81], v[142:145], v[232:235], v[78:81]
	v_mfma_f32_16x16x32_bf16 v[78:81], v[154:157], v[236:239], v[78:81]
	v_mfma_f32_16x16x32_bf16 v[74:77], v[170:173], v[232:235], v[74:77]
	v_mfma_f32_16x16x32_bf16 v[74:77], v[174:177], v[236:239], v[74:77]
	v_mfma_f32_16x16x32_bf16 v[10:13], v[186:189], v[232:235], v[10:13]
	v_mfma_f32_16x16x32_bf16 v[10:13], v[190:193], v[236:239], v[10:13]
	v_mfma_f32_16x16x32_bf16 v[14:17], v[178:181], v[232:235], v[14:17]
	v_mfma_f32_16x16x32_bf16 v[14:17], v[182:185], v[236:239], v[14:17]
	v_mfma_f32_16x16x32_bf16 v[6:9], v[178:181], v[240:243], v[6:9]
	v_mfma_f32_16x16x32_bf16 v[6:9], v[182:185], v[244:247], v[6:9]
	v_mfma_f32_16x16x32_bf16 v[2:5], v[186:189], v[240:243], v[2:5]
	v_mfma_f32_16x16x32_bf16 v[2:5], v[190:193], v[244:247], v[2:5]
	v_mfma_f32_16x16x32_bf16 v[66:69], v[170:173], v[240:243], v[66:69]
	v_mfma_f32_16x16x32_bf16 v[66:69], v[174:177], v[244:247], v[66:69]
	v_mfma_f32_16x16x32_bf16 v[70:73], v[142:145], v[240:243], v[70:73]
	v_mfma_f32_16x16x32_bf16 v[70:73], v[154:157], v[244:247], v[70:73]
	s_barrier
	s_setprio 0
	v_add_u32_e32 v141, 0x18000, v139
	ds_read_b128 v[142:145], v141
	ds_read_b128 v[154:157], v141 offset:1024
	ds_read_b128 v[170:173], v141 offset:2048
	ds_read_b128 v[174:177], v141 offset:3072
	v_add_u32_e32 v141, 0x1c000, v139
	ds_read_b128 v[178:181], v141
	ds_read_b128 v[182:185], v141 offset:1024
	ds_read_b128 v[186:189], v141 offset:2048
	ds_read_b128 v[190:193], v141 offset:3072
	s_add_i32 s52, s52, 0x80000
	s_mov_b32 m0, s31
	ds_read_b128 v[194:197], v140 offset:32768
	ds_read_b128 v[198:201], v140 offset:33792
	ds_read_b128 v[202:205], v140 offset:34816
	ds_read_b128 v[228:231], v140 offset:35840
	ds_read_b128 v[232:235], v140 offset:36864
	ds_read_b128 v[236:239], v140 offset:37888
	ds_read_b128 v[240:243], v140 offset:38912
	ds_read_b128 v[244:247], v140 offset:39936
	buffer_load_dwordx4 v131, s[60:63], s52 offen lds
	s_mov_b32 m0, s33
	s_nop 0
	buffer_load_dwordx4 v135, s[60:63], s52 offen lds
	s_waitcnt vmcnt(8)
	s_waitcnt lgkmcnt(0)
	s_setprio 1
	s_barrier
	v_mfma_f32_16x16x32_bf16 v[126:129], v[142:145], v[194:197], v[126:129]
	v_mfma_f32_16x16x32_bf16 v[126:129], v[154:157], v[198:201], v[126:129]
	v_mfma_f32_16x16x32_bf16 v[122:125], v[170:173], v[194:197], v[122:125]
	v_mfma_f32_16x16x32_bf16 v[122:125], v[174:177], v[198:201], v[122:125]
	v_mfma_f32_16x16x32_bf16 v[58:61], v[186:189], v[194:197], v[58:61]
	v_mfma_f32_16x16x32_bf16 v[58:61], v[190:193], v[198:201], v[58:61]
	v_mfma_f32_16x16x32_bf16 v[62:65], v[178:181], v[194:197], v[62:65]
	v_mfma_f32_16x16x32_bf16 v[62:65], v[182:185], v[198:201], v[62:65]
	v_mfma_f32_16x16x32_bf16 v[54:57], v[178:181], v[202:205], v[54:57]
	v_mfma_f32_16x16x32_bf16 v[54:57], v[182:185], v[228:231], v[54:57]
	v_mfma_f32_16x16x32_bf16 v[50:53], v[186:189], v[202:205], v[50:53]
	v_mfma_f32_16x16x32_bf16 v[50:53], v[190:193], v[228:231], v[50:53]
	v_mfma_f32_16x16x32_bf16 v[114:117], v[170:173], v[202:205], v[114:117]
	v_mfma_f32_16x16x32_bf16 v[114:117], v[174:177], v[228:231], v[114:117]
	v_mfma_f32_16x16x32_bf16 v[118:121], v[142:145], v[202:205], v[118:121]
	v_mfma_f32_16x16x32_bf16 v[118:121], v[154:157], v[228:231], v[118:121]
	v_mfma_f32_16x16x32_bf16 v[110:113], v[142:145], v[232:235], v[110:113]
	v_mfma_f32_16x16x32_bf16 v[110:113], v[154:157], v[236:239], v[110:113]
	v_mfma_f32_16x16x32_bf16 v[106:109], v[170:173], v[232:235], v[106:109]
	v_mfma_f32_16x16x32_bf16 v[106:109], v[174:177], v[236:239], v[106:109]
	v_mfma_f32_16x16x32_bf16 v[42:45], v[186:189], v[232:235], v[42:45]
	v_mfma_f32_16x16x32_bf16 v[42:45], v[190:193], v[236:239], v[42:45]
	v_mfma_f32_16x16x32_bf16 v[46:49], v[178:181], v[232:235], v[46:49]
	v_mfma_f32_16x16x32_bf16 v[46:49], v[182:185], v[236:239], v[46:49]
	v_mfma_f32_16x16x32_bf16 v[38:41], v[178:181], v[240:243], v[38:41]
	v_mfma_f32_16x16x32_bf16 v[38:41], v[182:185], v[244:247], v[38:41]
	v_mfma_f32_16x16x32_bf16 v[34:37], v[186:189], v[240:243], v[34:37]
	v_mfma_f32_16x16x32_bf16 v[34:37], v[190:193], v[244:247], v[34:37]
	v_mfma_f32_16x16x32_bf16 v[98:101], v[170:173], v[240:243], v[98:101]
	v_mfma_f32_16x16x32_bf16 v[98:101], v[174:177], v[244:247], v[98:101]
	v_mfma_f32_16x16x32_bf16 v[102:105], v[142:145], v[240:243], v[102:105]
	v_mfma_f32_16x16x32_bf16 v[102:105], v[154:157], v[244:247], v[102:105]
	s_barrier
	s_setprio 0
	s_or_b32 s52, s83, 0x80
	s_mov_b32 m0, s34
	ds_read_b128 v[194:197], v140 offset:49152
	buffer_load_dwordx4 v134, s[68:71], s52 offen lds
	s_add_i32 s83, s83, 0x80080
	s_mov_b32 m0, s35
	ds_read_b128 v[198:201], v140 offset:50176
	buffer_load_dwordx4 v136, s[68:71], s52 offen lds
	s_mov_b32 m0, s65
	ds_read_b128 v[202:205], v140 offset:51200
	buffer_load_dwordx4 v134, s[68:71], s83 offen lds
	s_mov_b32 m0, s66
	ds_read_b128 v[228:231], v140 offset:52224
	buffer_load_dwordx4 v136, s[68:71], s83 offen lds
	s_mov_b32 m0, s36
	ds_read_b128 v[232:235], v140 offset:53248
	buffer_load_dwordx4 v131, s[60:63], s27 offen lds
	s_mov_b32 m0, s37
	ds_read_b128 v[236:239], v140 offset:54272
	buffer_load_dwordx4 v135, s[60:63], s27 offen lds
	ds_read_b128 v[240:243], v140 offset:55296
	ds_read_b128 v[244:247], v140 offset:56320
	s_waitcnt vmcnt(8)
	s_waitcnt lgkmcnt(0)
	s_setprio 1
	s_barrier
	v_mfma_f32_16x16x32_bf16 v[94:97], v[142:145], v[194:197], v[94:97]
	v_mfma_f32_16x16x32_bf16 v[94:97], v[154:157], v[198:201], v[94:97]
	v_mfma_f32_16x16x32_bf16 v[90:93], v[170:173], v[194:197], v[90:93]
	v_mfma_f32_16x16x32_bf16 v[90:93], v[174:177], v[198:201], v[90:93]
	v_mfma_f32_16x16x32_bf16 v[26:29], v[186:189], v[194:197], v[26:29]
	v_mfma_f32_16x16x32_bf16 v[26:29], v[190:193], v[198:201], v[26:29]
	v_mfma_f32_16x16x32_bf16 v[30:33], v[178:181], v[194:197], v[30:33]
	v_mfma_f32_16x16x32_bf16 v[30:33], v[182:185], v[198:201], v[30:33]
	v_mfma_f32_16x16x32_bf16 v[22:25], v[178:181], v[202:205], v[22:25]
	v_mfma_f32_16x16x32_bf16 v[22:25], v[182:185], v[228:231], v[22:25]
	v_mfma_f32_16x16x32_bf16 v[18:21], v[186:189], v[202:205], v[18:21]
	v_mfma_f32_16x16x32_bf16 v[18:21], v[190:193], v[228:231], v[18:21]
	v_mfma_f32_16x16x32_bf16 v[82:85], v[170:173], v[202:205], v[82:85]
	v_mfma_f32_16x16x32_bf16 v[82:85], v[174:177], v[228:231], v[82:85]
	v_mfma_f32_16x16x32_bf16 v[86:89], v[142:145], v[202:205], v[86:89]
	v_mfma_f32_16x16x32_bf16 v[86:89], v[154:157], v[228:231], v[86:89]
	v_mfma_f32_16x16x32_bf16 v[78:81], v[142:145], v[232:235], v[78:81]
	v_mfma_f32_16x16x32_bf16 v[78:81], v[154:157], v[236:239], v[78:81]
	v_mfma_f32_16x16x32_bf16 v[74:77], v[170:173], v[232:235], v[74:77]
	v_mfma_f32_16x16x32_bf16 v[74:77], v[174:177], v[236:239], v[74:77]
	v_mfma_f32_16x16x32_bf16 v[10:13], v[186:189], v[232:235], v[10:13]
	v_mfma_f32_16x16x32_bf16 v[10:13], v[190:193], v[236:239], v[10:13]
	v_mfma_f32_16x16x32_bf16 v[14:17], v[178:181], v[232:235], v[14:17]
	v_mfma_f32_16x16x32_bf16 v[14:17], v[182:185], v[236:239], v[14:17]
	v_mfma_f32_16x16x32_bf16 v[6:9], v[178:181], v[240:243], v[6:9]
	v_mfma_f32_16x16x32_bf16 v[6:9], v[182:185], v[244:247], v[6:9]
	v_mfma_f32_16x16x32_bf16 v[2:5], v[186:189], v[240:243], v[2:5]
	v_mfma_f32_16x16x32_bf16 v[2:5], v[190:193], v[244:247], v[2:5]
	v_mfma_f32_16x16x32_bf16 v[66:69], v[170:173], v[240:243], v[66:69]
	v_mfma_f32_16x16x32_bf16 v[66:69], v[174:177], v[244:247], v[66:69]
	v_mfma_f32_16x16x32_bf16 v[70:73], v[142:145], v[240:243], v[70:73]
	v_mfma_f32_16x16x32_bf16 v[70:73], v[154:157], v[244:247], v[70:73]
	s_barrier
	s_setprio 0
	s_add_i32 s26, s26, 2
	s_addk_i32 s19, 0x100
	s_addk_i32 s22, 0x100
	s_cmp_gt_u32 s26, 29
	s_cbranch_scc0 .LBB0_1283
	s_and_b64 vcc, exec, s[44:45]
	s_cbranch_vccz .LBB0_1286
	s_barrier
	s_setprio 2

.LBB0_1585:
	s_setprio 0
	s_andn2_b64 vcc, exec, s[8:9]
	s_mov_b32 s2, s73
	s_mov_b32 s12, s84
	s_mov_b32 s21, s48
	s_mov_b32 s13, s85
	s_cbranch_vccz .LBB0_1597

.LBB0_1589:
	v_add_u32_e32 v170, 0x10000, v140
	v_add_u32_e32 v186, 0x14000, v140
	ds_read_b128 v[132:135], v170
	ds_read_b128 v[142:145], v170 offset:1024
	ds_read_b128 v[154:157], v170 offset:2048
	ds_read_b128 v[170:173], v170 offset:3072
	ds_read_b128 v[174:177], v186
	ds_read_b128 v[178:181], v186 offset:1024
	ds_read_b128 v[182:185], v186 offset:2048
	ds_read_b128 v[186:189], v186 offset:3072
	s_add_i32 s23, s13, 0xfff80080
	s_cmp_eq_u32 s22, 28
	s_cselect_b32 s27, s8, s23
	s_cselect_b32 s26, s9, s21
	s_or_b32 s23, s27, 0x80
	s_mov_b32 m0, s70
	ds_read_b128 v[190:193], v141
	ds_read_b128 v[194:197], v141 offset:1024
	ds_read_b128 v[198:201], v141 offset:2048
	ds_read_b128 v[202:205], v141 offset:3072
	ds_read_b128 v[228:231], v141 offset:4096
	ds_read_b128 v[232:235], v141 offset:5120
	ds_read_b128 v[236:239], v141 offset:6144
	ds_read_b128 v[240:243], v141 offset:7168
	buffer_load_dwordx4 v136, s[60:63], s13 offen lds
	s_mov_b32 m0, s72
	s_nop 0
	buffer_load_dwordx4 v138, s[60:63], s13 offen lds
	s_waitcnt vmcnt(8)
	s_waitcnt lgkmcnt(0)
	s_setprio 1
	s_barrier
	v_mfma_f32_16x16x32_bf16 v[126:129], v[132:135], v[190:193], v[126:129]
	v_mfma_f32_16x16x32_bf16 v[126:129], v[142:145], v[194:197], v[126:129]
	v_mfma_f32_16x16x32_bf16 v[106:109], v[154:157], v[190:193], v[106:109]
	v_mfma_f32_16x16x32_bf16 v[106:109], v[170:173], v[194:197], v[106:109]
	v_mfma_f32_16x16x32_bf16 v[110:113], v[182:185], v[190:193], v[110:113]
	v_mfma_f32_16x16x32_bf16 v[110:113], v[186:189], v[194:197], v[110:113]
	v_mfma_f32_16x16x32_bf16 v[122:125], v[174:177], v[190:193], v[122:125]
	v_mfma_f32_16x16x32_bf16 v[122:125], v[178:181], v[194:197], v[122:125]
	v_mfma_f32_16x16x32_bf16 v[102:105], v[174:177], v[198:201], v[102:105]
	v_mfma_f32_16x16x32_bf16 v[102:105], v[178:181], v[202:205], v[102:105]
	v_mfma_f32_16x16x32_bf16 v[98:101], v[182:185], v[198:201], v[98:101]
	v_mfma_f32_16x16x32_bf16 v[98:101], v[186:189], v[202:205], v[98:101]
	v_mfma_f32_16x16x32_bf16 v[114:117], v[154:157], v[198:201], v[114:117]
	v_mfma_f32_16x16x32_bf16 v[114:117], v[170:173], v[202:205], v[114:117]
	v_mfma_f32_16x16x32_bf16 v[118:121], v[132:135], v[198:201], v[118:121]
	v_mfma_f32_16x16x32_bf16 v[118:121], v[142:145], v[202:205], v[118:121]
	v_mfma_f32_16x16x32_bf16 v[94:97], v[132:135], v[228:231], v[94:97]
	v_mfma_f32_16x16x32_bf16 v[94:97], v[142:145], v[232:235], v[94:97]
	v_mfma_f32_16x16x32_bf16 v[90:93], v[154:157], v[228:231], v[90:93]
	v_mfma_f32_16x16x32_bf16 v[90:93], v[170:173], v[232:235], v[90:93]
	v_mfma_f32_16x16x32_bf16 v[82:85], v[182:185], v[228:231], v[82:85]
	v_mfma_f32_16x16x32_bf16 v[82:85], v[186:189], v[232:235], v[82:85]
	v_mfma_f32_16x16x32_bf16 v[86:89], v[174:177], v[228:231], v[86:89]
	v_mfma_f32_16x16x32_bf16 v[86:89], v[178:181], v[232:235], v[86:89]
	v_mfma_f32_16x16x32_bf16 v[70:73], v[174:177], v[236:239], v[70:73]
	v_mfma_f32_16x16x32_bf16 v[70:73], v[178:181], v[240:243], v[70:73]
	v_mfma_f32_16x16x32_bf16 v[66:69], v[182:185], v[236:239], v[66:69]
	v_mfma_f32_16x16x32_bf16 v[66:69], v[186:189], v[240:243], v[66:69]
	v_mfma_f32_16x16x32_bf16 v[74:77], v[154:157], v[236:239], v[74:77]
	v_mfma_f32_16x16x32_bf16 v[74:77], v[170:173], v[240:243], v[74:77]
	v_mfma_f32_16x16x32_bf16 v[78:81], v[132:135], v[236:239], v[78:81]
	v_mfma_f32_16x16x32_bf16 v[78:81], v[142:145], v[240:243], v[78:81]
	s_barrier
	s_setprio 0
	s_mov_b32 s46, s62
	s_mov_b32 s47, s63
	s_mov_b32 m0, s15
	ds_read_b128 v[190:193], v141 offset:16384
	buffer_load_dwordx4 v137, s[44:47], s26 offen lds
	s_add_i32 s49, s26, 0x80000
	s_mov_b32 m0, s16
	ds_read_b128 v[194:197], v141 offset:17408
	buffer_load_dwordx4 v139, s[44:47], s26 offen lds
	s_mov_b32 m0, s18
	ds_read_b128 v[198:201], v141 offset:18432
	buffer_load_dwordx4 v137, s[44:47], s49 offen lds
	s_mov_b32 m0, s19
	ds_read_b128 v[202:205], v141 offset:19456
	buffer_load_dwordx4 v139, s[44:47], s49 offen lds
	s_mov_b32 m0, s14
	ds_read_b128 v[228:231], v141 offset:20480
	buffer_load_dwordx4 v136, s[60:63], s27 offen lds
	s_mov_b32 m0, s24
	ds_read_b128 v[232:235], v141 offset:21504
	buffer_load_dwordx4 v138, s[60:63], s27 offen lds
	ds_read_b128 v[236:239], v141 offset:22528
	ds_read_b128 v[240:243], v141 offset:23552
	s_waitcnt vmcnt(8)
	s_waitcnt lgkmcnt(0)
	s_setprio 1
	s_barrier
	v_mfma_f32_16x16x32_bf16 v[62:65], v[132:135], v[190:193], v[62:65]
	v_mfma_f32_16x16x32_bf16 v[62:65], v[142:145], v[194:197], v[62:65]
	v_mfma_f32_16x16x32_bf16 v[58:61], v[154:157], v[190:193], v[58:61]
	v_mfma_f32_16x16x32_bf16 v[58:61], v[170:173], v[194:197], v[58:61]
	v_mfma_f32_16x16x32_bf16 v[50:53], v[182:185], v[190:193], v[50:53]
	v_mfma_f32_16x16x32_bf16 v[50:53], v[186:189], v[194:197], v[50:53]
	v_mfma_f32_16x16x32_bf16 v[54:57], v[174:177], v[190:193], v[54:57]
	v_mfma_f32_16x16x32_bf16 v[54:57], v[178:181], v[194:197], v[54:57]
	v_mfma_f32_16x16x32_bf16 v[38:41], v[174:177], v[198:201], v[38:41]
	v_mfma_f32_16x16x32_bf16 v[38:41], v[178:181], v[202:205], v[38:41]
	v_mfma_f32_16x16x32_bf16 v[34:37], v[182:185], v[198:201], v[34:37]
	v_mfma_f32_16x16x32_bf16 v[34:37], v[186:189], v[202:205], v[34:37]
	v_mfma_f32_16x16x32_bf16 v[42:45], v[154:157], v[198:201], v[42:45]
	v_mfma_f32_16x16x32_bf16 v[42:45], v[170:173], v[202:205], v[42:45]
	v_mfma_f32_16x16x32_bf16 v[46:49], v[132:135], v[198:201], v[46:49]
	v_mfma_f32_16x16x32_bf16 v[46:49], v[142:145], v[202:205], v[46:49]
	v_mfma_f32_16x16x32_bf16 v[30:33], v[132:135], v[228:231], v[30:33]
	v_mfma_f32_16x16x32_bf16 v[30:33], v[142:145], v[232:235], v[30:33]
	v_mfma_f32_16x16x32_bf16 v[26:29], v[154:157], v[228:231], v[26:29]
	v_mfma_f32_16x16x32_bf16 v[26:29], v[170:173], v[232:235], v[26:29]
	v_mfma_f32_16x16x32_bf16 v[18:21], v[182:185], v[228:231], v[18:21]
	v_mfma_f32_16x16x32_bf16 v[18:21], v[186:189], v[232:235], v[18:21]
	v_mfma_f32_16x16x32_bf16 v[22:25], v[174:177], v[228:231], v[22:25]
	v_mfma_f32_16x16x32_bf16 v[22:25], v[178:181], v[232:235], v[22:25]
	v_mfma_f32_16x16x32_bf16 v[6:9], v[174:177], v[236:239], v[6:9]
	v_mfma_f32_16x16x32_bf16 v[6:9], v[178:181], v[240:243], v[6:9]
	v_mfma_f32_16x16x32_bf16 v[2:5], v[182:185], v[236:239], v[2:5]
	v_mfma_f32_16x16x32_bf16 v[2:5], v[186:189], v[240:243], v[2:5]
	v_mfma_f32_16x16x32_bf16 v[10:13], v[154:157], v[236:239], v[10:13]
	v_mfma_f32_16x16x32_bf16 v[10:13], v[170:173], v[240:243], v[10:13]
	v_mfma_f32_16x16x32_bf16 v[14:17], v[132:135], v[236:239], v[14:17]
	v_mfma_f32_16x16x32_bf16 v[14:17], v[142:145], v[240:243], v[14:17]
	s_barrier
	s_setprio 0
	v_add_u32_e32 v170, 0x18000, v140
	v_add_u32_e32 v186, 0x1c000, v140
	ds_read_b128 v[132:135], v170
	ds_read_b128 v[142:145], v170 offset:1024
	ds_read_b128 v[154:157], v170 offset:2048
	ds_read_b128 v[170:173], v170 offset:3072
	ds_read_b128 v[174:177], v186
	ds_read_b128 v[178:181], v186 offset:1024
	ds_read_b128 v[182:185], v186 offset:2048
	ds_read_b128 v[186:189], v186 offset:3072
	s_add_i32 s27, s27, 0x80000
	s_mov_b32 m0, s25
	ds_read_b128 v[190:193], v141 offset:32768
	ds_read_b128 v[194:197], v141 offset:33792
	ds_read_b128 v[198:201], v141 offset:34816
	ds_read_b128 v[202:205], v141 offset:35840
	ds_read_b128 v[228:231], v141 offset:36864
	ds_read_b128 v[232:235], v141 offset:37888
	ds_read_b128 v[236:239], v141 offset:38912
	ds_read_b128 v[240:243], v141 offset:39936
	buffer_load_dwordx4 v136, s[60:63], s27 offen lds
	s_mov_b32 m0, s30
	s_nop 0
	buffer_load_dwordx4 v138, s[60:63], s27 offen lds
	s_waitcnt vmcnt(8)
	s_waitcnt lgkmcnt(0)
	s_setprio 1
	s_barrier
	v_mfma_f32_16x16x32_bf16 v[126:129], v[132:135], v[190:193], v[126:129]
	v_mfma_f32_16x16x32_bf16 v[126:129], v[142:145], v[194:197], v[126:129]
	v_mfma_f32_16x16x32_bf16 v[106:109], v[154:157], v[190:193], v[106:109]
	v_mfma_f32_16x16x32_bf16 v[106:109], v[170:173], v[194:197], v[106:109]
	v_mfma_f32_16x16x32_bf16 v[110:113], v[182:185], v[190:193], v[110:113]
	v_mfma_f32_16x16x32_bf16 v[110:113], v[186:189], v[194:197], v[110:113]
	v_mfma_f32_16x16x32_bf16 v[122:125], v[174:177], v[190:193], v[122:125]
	v_mfma_f32_16x16x32_bf16 v[122:125], v[178:181], v[194:197], v[122:125]
	v_mfma_f32_16x16x32_bf16 v[102:105], v[174:177], v[198:201], v[102:105]
	v_mfma_f32_16x16x32_bf16 v[102:105], v[178:181], v[202:205], v[102:105]
	v_mfma_f32_16x16x32_bf16 v[98:101], v[182:185], v[198:201], v[98:101]
	v_mfma_f32_16x16x32_bf16 v[98:101], v[186:189], v[202:205], v[98:101]
	v_mfma_f32_16x16x32_bf16 v[114:117], v[154:157], v[198:201], v[114:117]
	v_mfma_f32_16x16x32_bf16 v[114:117], v[170:173], v[202:205], v[114:117]
	v_mfma_f32_16x16x32_bf16 v[118:121], v[132:135], v[198:201], v[118:121]
	v_mfma_f32_16x16x32_bf16 v[118:121], v[142:145], v[202:205], v[118:121]
	v_mfma_f32_16x16x32_bf16 v[94:97], v[132:135], v[228:231], v[94:97]
	v_mfma_f32_16x16x32_bf16 v[94:97], v[142:145], v[232:235], v[94:97]
	v_mfma_f32_16x16x32_bf16 v[90:93], v[154:157], v[228:231], v[90:93]
	v_mfma_f32_16x16x32_bf16 v[90:93], v[170:173], v[232:235], v[90:93]
	v_mfma_f32_16x16x32_bf16 v[82:85], v[182:185], v[228:231], v[82:85]
	v_mfma_f32_16x16x32_bf16 v[82:85], v[186:189], v[232:235], v[82:85]
	v_mfma_f32_16x16x32_bf16 v[86:89], v[174:177], v[228:231], v[86:89]
	v_mfma_f32_16x16x32_bf16 v[86:89], v[178:181], v[232:235], v[86:89]
	v_mfma_f32_16x16x32_bf16 v[70:73], v[174:177], v[236:239], v[70:73]
	v_mfma_f32_16x16x32_bf16 v[70:73], v[178:181], v[240:243], v[70:73]
	v_mfma_f32_16x16x32_bf16 v[66:69], v[182:185], v[236:239], v[66:69]
	v_mfma_f32_16x16x32_bf16 v[66:69], v[186:189], v[240:243], v[66:69]
	v_mfma_f32_16x16x32_bf16 v[74:77], v[154:157], v[236:239], v[74:77]
	v_mfma_f32_16x16x32_bf16 v[74:77], v[170:173], v[240:243], v[74:77]
	v_mfma_f32_16x16x32_bf16 v[78:81], v[132:135], v[236:239], v[78:81]
	v_mfma_f32_16x16x32_bf16 v[78:81], v[142:145], v[240:243], v[78:81]
	s_barrier
	s_setprio 0
	s_or_b32 s27, s26, 0x80
	s_mov_b32 m0, s36
	ds_read_b128 v[190:193], v141 offset:49152
	buffer_load_dwordx4 v137, s[44:47], s27 offen lds
	s_add_i32 s26, s26, 0x80080
	s_mov_b32 m0, s37
	ds_read_b128 v[194:197], v141 offset:50176
	buffer_load_dwordx4 v139, s[44:47], s27 offen lds
	s_mov_b32 m0, s68
	ds_read_b128 v[198:201], v141 offset:51200
	buffer_load_dwordx4 v137, s[44:47], s26 offen lds
	s_mov_b32 m0, s69
	ds_read_b128 v[202:205], v141 offset:52224
	buffer_load_dwordx4 v139, s[44:47], s26 offen lds
	s_mov_b32 m0, s66
	ds_read_b128 v[228:231], v141 offset:53248
	buffer_load_dwordx4 v136, s[60:63], s23 offen lds
	s_mov_b32 m0, s67
	ds_read_b128 v[232:235], v141 offset:54272
	buffer_load_dwordx4 v138, s[60:63], s23 offen lds
	ds_read_b128 v[236:239], v141 offset:55296
	ds_read_b128 v[240:243], v141 offset:56320
	s_waitcnt vmcnt(8)
	s_waitcnt lgkmcnt(0)
	s_setprio 1
	s_barrier
	v_mfma_f32_16x16x32_bf16 v[62:65], v[132:135], v[190:193], v[62:65]
	v_mfma_f32_16x16x32_bf16 v[62:65], v[142:145], v[194:197], v[62:65]
	v_mfma_f32_16x16x32_bf16 v[58:61], v[154:157], v[190:193], v[58:61]
	v_mfma_f32_16x16x32_bf16 v[58:61], v[170:173], v[194:197], v[58:61]
	v_mfma_f32_16x16x32_bf16 v[50:53], v[182:185], v[190:193], v[50:53]
	v_mfma_f32_16x16x32_bf16 v[50:53], v[186:189], v[194:197], v[50:53]
	v_mfma_f32_16x16x32_bf16 v[54:57], v[174:177], v[190:193], v[54:57]
	v_mfma_f32_16x16x32_bf16 v[54:57], v[178:181], v[194:197], v[54:57]
	v_mfma_f32_16x16x32_bf16 v[38:41], v[174:177], v[198:201], v[38:41]
	v_mfma_f32_16x16x32_bf16 v[38:41], v[178:181], v[202:205], v[38:41]
	v_mfma_f32_16x16x32_bf16 v[34:37], v[182:185], v[198:201], v[34:37]
	v_mfma_f32_16x16x32_bf16 v[34:37], v[186:189], v[202:205], v[34:37]
	v_mfma_f32_16x16x32_bf16 v[42:45], v[154:157], v[198:201], v[42:45]
	v_mfma_f32_16x16x32_bf16 v[42:45], v[170:173], v[202:205], v[42:45]
	v_mfma_f32_16x16x32_bf16 v[46:49], v[132:135], v[198:201], v[46:49]
	v_mfma_f32_16x16x32_bf16 v[46:49], v[142:145], v[202:205], v[46:49]
	v_mfma_f32_16x16x32_bf16 v[30:33], v[132:135], v[228:231], v[30:33]
	v_mfma_f32_16x16x32_bf16 v[30:33], v[142:145], v[232:235], v[30:33]
	v_mfma_f32_16x16x32_bf16 v[26:29], v[154:157], v[228:231], v[26:29]
	v_mfma_f32_16x16x32_bf16 v[26:29], v[170:173], v[232:235], v[26:29]
	v_mfma_f32_16x16x32_bf16 v[18:21], v[182:185], v[228:231], v[18:21]
	v_mfma_f32_16x16x32_bf16 v[18:21], v[186:189], v[232:235], v[18:21]
	v_mfma_f32_16x16x32_bf16 v[22:25], v[174:177], v[228:231], v[22:25]
	v_mfma_f32_16x16x32_bf16 v[22:25], v[178:181], v[232:235], v[22:25]
	v_mfma_f32_16x16x32_bf16 v[6:9], v[174:177], v[236:239], v[6:9]
	v_mfma_f32_16x16x32_bf16 v[6:9], v[178:181], v[240:243], v[6:9]
	v_mfma_f32_16x16x32_bf16 v[2:5], v[182:185], v[236:239], v[2:5]
	v_mfma_f32_16x16x32_bf16 v[2:5], v[186:189], v[240:243], v[2:5]
	v_mfma_f32_16x16x32_bf16 v[10:13], v[154:157], v[236:239], v[10:13]
	v_mfma_f32_16x16x32_bf16 v[10:13], v[170:173], v[240:243], v[10:13]
	v_mfma_f32_16x16x32_bf16 v[14:17], v[132:135], v[236:239], v[14:17]
	v_mfma_f32_16x16x32_bf16 v[14:17], v[142:145], v[240:243], v[14:17]
	s_barrier
	s_setprio 0
	s_add_i32 s22, s22, 2
	s_addk_i32 s13, 0x100
	s_addk_i32 s21, 0x100
	s_cmp_gt_u32 s22, 29
	s_cbranch_scc0 .LBB0_1589
	s_and_b64 vcc, exec, s[64:65]
	s_cbranch_vccz .LBB0_1592
	s_barrier
	s_setprio 2

.LBB0_1869:
	s_setprio 0
	s_andn2_b64 vcc, exec, s[8:9]
	s_mov_b32 s90, s92
	s_mov_b32 s93, s91
	s_mov_b32 s94, s19
	s_mov_b32 s95, s18
	s_mov_b32 s18, s89
	s_cbranch_vccz .LBB0_1886

.LBB0_1880:
	v_add_u32_e32 v139, 0x10000, v136
	ds_read_b128 v[140:143], v139
	ds_read_b128 v[154:157], v139 offset:1024
	ds_read_b128 v[170:173], v139 offset:2048
	ds_read_b128 v[174:177], v139 offset:3072
	v_add_u32_e32 v139, 0x14000, v136
	ds_read_b128 v[178:181], v139
	ds_read_b128 v[182:185], v139 offset:1024
	ds_read_b128 v[186:189], v139 offset:2048
	ds_read_b128 v[190:193], v139 offset:3072
	s_add_i32 s42, vcc_lo, 0xfff80080
	s_cmp_eq_u32 s94, 28
	s_cselect_b32 s52, s8, s42
	s_cselect_b32 s96, s9, vcc_hi
	s_or_b32 s95, s52, 0x80
	s_mov_b32 m0, s72
	ds_read_b128 v[194:197], v137
	ds_read_b128 v[198:201], v137 offset:1024
	ds_read_b128 v[202:205], v137 offset:2048
	ds_read_b128 v[228:231], v137 offset:3072
	ds_read_b128 v[232:235], v137 offset:4096
	ds_read_b128 v[236:239], v137 offset:5120
	ds_read_b128 v[240:243], v137 offset:6144
	ds_read_b128 v[244:247], v137 offset:7168
	buffer_load_dwordx4 v132, s[60:63], vcc_lo offen lds
	s_mov_b32 m0, s47
	s_nop 0
	buffer_load_dwordx4 v134, s[60:63], vcc_lo offen lds
	s_waitcnt vmcnt(8)
	s_waitcnt lgkmcnt(0)
	s_setprio 1
	s_barrier
	v_mfma_f32_16x16x32_bf16 v[114:117], v[140:143], v[194:197], v[114:117]
	v_mfma_f32_16x16x32_bf16 v[114:117], v[154:157], v[198:201], v[114:117]
	v_mfma_f32_16x16x32_bf16 v[110:113], v[170:173], v[194:197], v[110:113]
	v_mfma_f32_16x16x32_bf16 v[110:113], v[174:177], v[198:201], v[110:113]
	v_mfma_f32_16x16x32_bf16 v[122:125], v[186:189], v[194:197], v[122:125]
	v_mfma_f32_16x16x32_bf16 v[122:125], v[190:193], v[198:201], v[122:125]
	v_mfma_f32_16x16x32_bf16 v[126:129], v[178:181], v[194:197], v[126:129]
	v_mfma_f32_16x16x32_bf16 v[126:129], v[182:185], v[198:201], v[126:129]
	v_mfma_f32_16x16x32_bf16 v[118:121], v[178:181], v[202:205], v[118:121]
	v_mfma_f32_16x16x32_bf16 v[118:121], v[182:185], v[228:231], v[118:121]
	v_mfma_f32_16x16x32_bf16 v[98:101], v[186:189], v[202:205], v[98:101]
	v_mfma_f32_16x16x32_bf16 v[98:101], v[190:193], v[228:231], v[98:101]
	v_mfma_f32_16x16x32_bf16 v[102:105], v[170:173], v[202:205], v[102:105]
	v_mfma_f32_16x16x32_bf16 v[102:105], v[174:177], v[228:231], v[102:105]
	v_mfma_f32_16x16x32_bf16 v[106:109], v[140:143], v[202:205], v[106:109]
	v_mfma_f32_16x16x32_bf16 v[106:109], v[154:157], v[228:231], v[106:109]
	v_mfma_f32_16x16x32_bf16 v[94:97], v[140:143], v[232:235], v[94:97]
	v_mfma_f32_16x16x32_bf16 v[94:97], v[154:157], v[236:239], v[94:97]
	v_mfma_f32_16x16x32_bf16 v[86:89], v[170:173], v[232:235], v[86:89]
	v_mfma_f32_16x16x32_bf16 v[86:89], v[174:177], v[236:239], v[86:89]
	v_mfma_f32_16x16x32_bf16 v[82:85], v[186:189], v[232:235], v[82:85]
	v_mfma_f32_16x16x32_bf16 v[82:85], v[190:193], v[236:239], v[82:85]
	v_mfma_f32_16x16x32_bf16 v[90:93], v[178:181], v[232:235], v[90:93]
	v_mfma_f32_16x16x32_bf16 v[90:93], v[182:185], v[236:239], v[90:93]
	v_mfma_f32_16x16x32_bf16 v[74:77], v[178:181], v[240:243], v[74:77]
	v_mfma_f32_16x16x32_bf16 v[74:77], v[182:185], v[244:247], v[74:77]
	v_mfma_f32_16x16x32_bf16 v[66:69], v[186:189], v[240:243], v[66:69]
	v_mfma_f32_16x16x32_bf16 v[66:69], v[190:193], v[244:247], v[66:69]
	v_mfma_f32_16x16x32_bf16 v[70:73], v[170:173], v[240:243], v[70:73]
	v_mfma_f32_16x16x32_bf16 v[70:73], v[174:177], v[244:247], v[70:73]
	v_mfma_f32_16x16x32_bf16 v[78:81], v[140:143], v[240:243], v[78:81]
	v_mfma_f32_16x16x32_bf16 v[78:81], v[154:157], v[244:247], v[78:81]
	s_barrier
	s_setprio 0
	s_mov_b32 s42, s62
	s_mov_b32 s43, s63
	s_mov_b32 m0, s13
	ds_read_b128 v[194:197], v137 offset:16384
	buffer_load_dwordx4 v133, s[40:43], s96 offen lds
	s_add_i32 s53, s96, 0x80000
	s_mov_b32 m0, s14
	ds_read_b128 v[198:201], v137 offset:17408
	buffer_load_dwordx4 v135, s[40:43], s96 offen lds
	s_mov_b32 m0, s15
	ds_read_b128 v[202:205], v137 offset:18432
	buffer_load_dwordx4 v133, s[40:43], s53 offen lds
	s_mov_b32 m0, s16
	ds_read_b128 v[228:231], v137 offset:19456
	buffer_load_dwordx4 v135, s[40:43], s53 offen lds
	s_mov_b32 m0, s2
	ds_read_b128 v[232:235], v137 offset:20480
	buffer_load_dwordx4 v132, s[60:63], s52 offen lds
	s_mov_b32 m0, s21
	ds_read_b128 v[236:239], v137 offset:21504
	buffer_load_dwordx4 v134, s[60:63], s52 offen lds
	ds_read_b128 v[240:243], v137 offset:22528
	ds_read_b128 v[244:247], v137 offset:23552
	s_waitcnt vmcnt(8)
	s_waitcnt lgkmcnt(0)
	s_setprio 1
	s_barrier
	v_mfma_f32_16x16x32_bf16 v[62:65], v[140:143], v[194:197], v[62:65]
	v_mfma_f32_16x16x32_bf16 v[62:65], v[154:157], v[198:201], v[62:65]
	v_mfma_f32_16x16x32_bf16 v[54:57], v[170:173], v[194:197], v[54:57]
	v_mfma_f32_16x16x32_bf16 v[54:57], v[174:177], v[198:201], v[54:57]
	v_mfma_f32_16x16x32_bf16 v[50:53], v[186:189], v[194:197], v[50:53]
	v_mfma_f32_16x16x32_bf16 v[50:53], v[190:193], v[198:201], v[50:53]
	v_mfma_f32_16x16x32_bf16 v[58:61], v[178:181], v[194:197], v[58:61]
	v_mfma_f32_16x16x32_bf16 v[58:61], v[182:185], v[198:201], v[58:61]
	v_mfma_f32_16x16x32_bf16 v[42:45], v[178:181], v[202:205], v[42:45]
	v_mfma_f32_16x16x32_bf16 v[42:45], v[182:185], v[228:231], v[42:45]
	v_mfma_f32_16x16x32_bf16 v[34:37], v[186:189], v[202:205], v[34:37]
	v_mfma_f32_16x16x32_bf16 v[34:37], v[190:193], v[228:231], v[34:37]
	v_mfma_f32_16x16x32_bf16 v[38:41], v[170:173], v[202:205], v[38:41]
	v_mfma_f32_16x16x32_bf16 v[38:41], v[174:177], v[228:231], v[38:41]
	v_mfma_f32_16x16x32_bf16 v[46:49], v[140:143], v[202:205], v[46:49]
	v_mfma_f32_16x16x32_bf16 v[46:49], v[154:157], v[228:231], v[46:49]
	v_mfma_f32_16x16x32_bf16 v[30:33], v[140:143], v[232:235], v[30:33]
	v_mfma_f32_16x16x32_bf16 v[30:33], v[154:157], v[236:239], v[30:33]
	v_mfma_f32_16x16x32_bf16 v[22:25], v[170:173], v[232:235], v[22:25]
	v_mfma_f32_16x16x32_bf16 v[22:25], v[174:177], v[236:239], v[22:25]
	v_mfma_f32_16x16x32_bf16 v[18:21], v[186:189], v[232:235], v[18:21]
	v_mfma_f32_16x16x32_bf16 v[18:21], v[190:193], v[236:239], v[18:21]
	v_mfma_f32_16x16x32_bf16 v[26:29], v[178:181], v[232:235], v[26:29]
	v_mfma_f32_16x16x32_bf16 v[26:29], v[182:185], v[236:239], v[26:29]
	v_mfma_f32_16x16x32_bf16 v[10:13], v[178:181], v[240:243], v[10:13]
	v_mfma_f32_16x16x32_bf16 v[10:13], v[182:185], v[244:247], v[10:13]
	v_mfma_f32_16x16x32_bf16 v[2:5], v[186:189], v[240:243], v[2:5]
	v_mfma_f32_16x16x32_bf16 v[2:5], v[190:193], v[244:247], v[2:5]
	v_mfma_f32_16x16x32_bf16 v[6:9], v[170:173], v[240:243], v[6:9]
	v_mfma_f32_16x16x32_bf16 v[6:9], v[174:177], v[244:247], v[6:9]
	v_mfma_f32_16x16x32_bf16 v[14:17], v[140:143], v[240:243], v[14:17]
	v_mfma_f32_16x16x32_bf16 v[14:17], v[154:157], v[244:247], v[14:17]
	s_barrier
	s_setprio 0
	v_add_u32_e32 v139, 0x18000, v136
	ds_read_b128 v[140:143], v139
	ds_read_b128 v[154:157], v139 offset:1024
	ds_read_b128 v[170:173], v139 offset:2048
	ds_read_b128 v[174:177], v139 offset:3072
	v_add_u32_e32 v139, 0x1c000, v136
	ds_read_b128 v[178:181], v139
	ds_read_b128 v[182:185], v139 offset:1024
	ds_read_b128 v[186:189], v139 offset:2048
	ds_read_b128 v[190:193], v139 offset:3072
	s_add_i32 s52, s52, 0x80000
	s_mov_b32 m0, s23
	ds_read_b128 v[194:197], v137 offset:32768
	ds_read_b128 v[198:201], v137 offset:33792
	ds_read_b128 v[202:205], v137 offset:34816
	ds_read_b128 v[228:231], v137 offset:35840
	ds_read_b128 v[232:235], v137 offset:36864
	ds_read_b128 v[236:239], v137 offset:37888
	ds_read_b128 v[240:243], v137 offset:38912
	ds_read_b128 v[244:247], v137 offset:39936
	buffer_load_dwordx4 v132, s[60:63], s52 offen lds
	s_mov_b32 m0, s24
	s_nop 0
	buffer_load_dwordx4 v134, s[60:63], s52 offen lds
	s_waitcnt vmcnt(8)
	s_waitcnt lgkmcnt(0)
	s_setprio 1
	s_barrier
	v_mfma_f32_16x16x32_bf16 v[114:117], v[140:143], v[194:197], v[114:117]
	v_mfma_f32_16x16x32_bf16 v[114:117], v[154:157], v[198:201], v[114:117]
	v_mfma_f32_16x16x32_bf16 v[110:113], v[170:173], v[194:197], v[110:113]
	v_mfma_f32_16x16x32_bf16 v[110:113], v[174:177], v[198:201], v[110:113]
	v_mfma_f32_16x16x32_bf16 v[122:125], v[186:189], v[194:197], v[122:125]
	v_mfma_f32_16x16x32_bf16 v[122:125], v[190:193], v[198:201], v[122:125]
	v_mfma_f32_16x16x32_bf16 v[126:129], v[178:181], v[194:197], v[126:129]
	v_mfma_f32_16x16x32_bf16 v[126:129], v[182:185], v[198:201], v[126:129]
	v_mfma_f32_16x16x32_bf16 v[118:121], v[178:181], v[202:205], v[118:121]
	v_mfma_f32_16x16x32_bf16 v[118:121], v[182:185], v[228:231], v[118:121]
	v_mfma_f32_16x16x32_bf16 v[98:101], v[186:189], v[202:205], v[98:101]
	v_mfma_f32_16x16x32_bf16 v[98:101], v[190:193], v[228:231], v[98:101]
	v_mfma_f32_16x16x32_bf16 v[102:105], v[170:173], v[202:205], v[102:105]
	v_mfma_f32_16x16x32_bf16 v[102:105], v[174:177], v[228:231], v[102:105]
	v_mfma_f32_16x16x32_bf16 v[106:109], v[140:143], v[202:205], v[106:109]
	v_mfma_f32_16x16x32_bf16 v[106:109], v[154:157], v[228:231], v[106:109]
	v_mfma_f32_16x16x32_bf16 v[94:97], v[140:143], v[232:235], v[94:97]
	v_mfma_f32_16x16x32_bf16 v[94:97], v[154:157], v[236:239], v[94:97]
	v_mfma_f32_16x16x32_bf16 v[86:89], v[170:173], v[232:235], v[86:89]
	v_mfma_f32_16x16x32_bf16 v[86:89], v[174:177], v[236:239], v[86:89]
	v_mfma_f32_16x16x32_bf16 v[82:85], v[186:189], v[232:235], v[82:85]
	v_mfma_f32_16x16x32_bf16 v[82:85], v[190:193], v[236:239], v[82:85]
	v_mfma_f32_16x16x32_bf16 v[90:93], v[178:181], v[232:235], v[90:93]
	v_mfma_f32_16x16x32_bf16 v[90:93], v[182:185], v[236:239], v[90:93]
	v_mfma_f32_16x16x32_bf16 v[74:77], v[178:181], v[240:243], v[74:77]
	v_mfma_f32_16x16x32_bf16 v[74:77], v[182:185], v[244:247], v[74:77]
	v_mfma_f32_16x16x32_bf16 v[66:69], v[186:189], v[240:243], v[66:69]
	v_mfma_f32_16x16x32_bf16 v[66:69], v[190:193], v[244:247], v[66:69]
	v_mfma_f32_16x16x32_bf16 v[70:73], v[170:173], v[240:243], v[70:73]
	v_mfma_f32_16x16x32_bf16 v[70:73], v[174:177], v[244:247], v[70:73]
	v_mfma_f32_16x16x32_bf16 v[78:81], v[140:143], v[240:243], v[78:81]
	v_mfma_f32_16x16x32_bf16 v[78:81], v[154:157], v[244:247], v[78:81]
	s_barrier
	s_setprio 0
	s_or_b32 s52, s96, 0x80
	s_mov_b32 m0, s31
	ds_read_b128 v[194:197], v137 offset:49152
	buffer_load_dwordx4 v133, s[40:43], s52 offen lds
	s_add_i32 s96, s96, 0x80080
	s_mov_b32 m0, s33
	ds_read_b128 v[198:201], v137 offset:50176
	buffer_load_dwordx4 v135, s[40:43], s52 offen lds
	s_mov_b32 m0, s36
	ds_read_b128 v[202:205], v137 offset:51200
	buffer_load_dwordx4 v133, s[40:43], s96 offen lds
	s_mov_b32 m0, s37
	ds_read_b128 v[228:231], v137 offset:52224
	buffer_load_dwordx4 v135, s[40:43], s96 offen lds
	s_mov_b32 m0, s34
	ds_read_b128 v[232:235], v137 offset:53248
	buffer_load_dwordx4 v132, s[60:63], s95 offen lds
	s_mov_b32 m0, s35
	ds_read_b128 v[236:239], v137 offset:54272
	buffer_load_dwordx4 v134, s[60:63], s95 offen lds
	ds_read_b128 v[240:243], v137 offset:55296
	ds_read_b128 v[244:247], v137 offset:56320
	s_waitcnt vmcnt(8)
	s_waitcnt lgkmcnt(0)
	s_setprio 1
	s_barrier
	v_mfma_f32_16x16x32_bf16 v[62:65], v[140:143], v[194:197], v[62:65]
	v_mfma_f32_16x16x32_bf16 v[62:65], v[154:157], v[198:201], v[62:65]
	v_mfma_f32_16x16x32_bf16 v[54:57], v[170:173], v[194:197], v[54:57]
	v_mfma_f32_16x16x32_bf16 v[54:57], v[174:177], v[198:201], v[54:57]
	v_mfma_f32_16x16x32_bf16 v[50:53], v[186:189], v[194:197], v[50:53]
	v_mfma_f32_16x16x32_bf16 v[50:53], v[190:193], v[198:201], v[50:53]
	v_mfma_f32_16x16x32_bf16 v[58:61], v[178:181], v[194:197], v[58:61]
	v_mfma_f32_16x16x32_bf16 v[58:61], v[182:185], v[198:201], v[58:61]
	v_mfma_f32_16x16x32_bf16 v[42:45], v[178:181], v[202:205], v[42:45]
	v_mfma_f32_16x16x32_bf16 v[42:45], v[182:185], v[228:231], v[42:45]
	v_mfma_f32_16x16x32_bf16 v[34:37], v[186:189], v[202:205], v[34:37]
	v_mfma_f32_16x16x32_bf16 v[34:37], v[190:193], v[228:231], v[34:37]
	v_mfma_f32_16x16x32_bf16 v[38:41], v[170:173], v[202:205], v[38:41]
	v_mfma_f32_16x16x32_bf16 v[38:41], v[174:177], v[228:231], v[38:41]
	v_mfma_f32_16x16x32_bf16 v[46:49], v[140:143], v[202:205], v[46:49]
	v_mfma_f32_16x16x32_bf16 v[46:49], v[154:157], v[228:231], v[46:49]
	v_mfma_f32_16x16x32_bf16 v[30:33], v[140:143], v[232:235], v[30:33]
	v_mfma_f32_16x16x32_bf16 v[30:33], v[154:157], v[236:239], v[30:33]
	v_mfma_f32_16x16x32_bf16 v[22:25], v[170:173], v[232:235], v[22:25]
	v_mfma_f32_16x16x32_bf16 v[22:25], v[174:177], v[236:239], v[22:25]
	v_mfma_f32_16x16x32_bf16 v[18:21], v[186:189], v[232:235], v[18:21]
	v_mfma_f32_16x16x32_bf16 v[18:21], v[190:193], v[236:239], v[18:21]
	v_mfma_f32_16x16x32_bf16 v[26:29], v[178:181], v[232:235], v[26:29]
	v_mfma_f32_16x16x32_bf16 v[26:29], v[182:185], v[236:239], v[26:29]
	v_mfma_f32_16x16x32_bf16 v[10:13], v[178:181], v[240:243], v[10:13]
	v_mfma_f32_16x16x32_bf16 v[10:13], v[182:185], v[244:247], v[10:13]
	v_mfma_f32_16x16x32_bf16 v[2:5], v[186:189], v[240:243], v[2:5]
	v_mfma_f32_16x16x32_bf16 v[2:5], v[190:193], v[244:247], v[2:5]
	v_mfma_f32_16x16x32_bf16 v[6:9], v[170:173], v[240:243], v[6:9]
	v_mfma_f32_16x16x32_bf16 v[6:9], v[174:177], v[244:247], v[6:9]
	v_mfma_f32_16x16x32_bf16 v[14:17], v[140:143], v[240:243], v[14:17]
	v_mfma_f32_16x16x32_bf16 v[14:17], v[154:157], v[244:247], v[14:17]
	s_barrier
	s_setprio 0
	s_add_i32 s94, s94, 2
	s_addk_i32 vcc_lo, 0x100
	s_addk_i32 vcc_hi, 0x100
	s_cmp_gt_u32 s94, 29
	s_cbranch_scc0 .LBB0_1880
	s_and_b64 vcc, exec, s[64:65]
	s_cbranch_vccz .LBB0_1883
	s_barrier
	s_setprio 2

.LBB0_2152:
	s_setprio 0
	s_andn2_b64 vcc, exec, s[8:9]
	s_mov_b32 s2, s15
	s_mov_b32 s12, s48
	s_mov_b32 s13, s23
	s_mov_b32 s21, s49
	s_cbranch_vccz .LBB0_2164

.LBB0_2156:
	v_add_u32_e32 v170, 0x10000, v140
	v_add_u32_e32 v186, 0x14000, v140
	ds_read_b128 v[132:135], v170
	ds_read_b128 v[142:145], v170 offset:1024
	ds_read_b128 v[154:157], v170 offset:2048
	ds_read_b128 v[170:173], v170 offset:3072
	ds_read_b128 v[174:177], v186
	ds_read_b128 v[178:181], v186 offset:1024
	ds_read_b128 v[182:185], v186 offset:2048
	ds_read_b128 v[186:189], v186 offset:3072
	s_add_i32 s26, s21, 0x4000
	s_cmpk_eq_i32 s22, 0x54
	s_cselect_b32 s52, s8, s26
	s_cselect_b32 s27, s9, s13
	s_or_b32 s26, s52, 0x8000
	s_mov_b32 m0, s84
	ds_read_b128 v[190:193], v141
	ds_read_b128 v[194:197], v141 offset:1024
	ds_read_b128 v[198:201], v141 offset:2048
	ds_read_b128 v[202:205], v141 offset:3072
	ds_read_b128 v[228:231], v141 offset:4096
	ds_read_b128 v[232:235], v141 offset:5120
	ds_read_b128 v[236:239], v141 offset:6144
	ds_read_b128 v[240:243], v141 offset:7168
	buffer_load_dwordx4 v136, s[60:63], s21 offen lds
	s_mov_b32 m0, s16
	s_nop 0
	buffer_load_dwordx4 v138, s[60:63], s21 offen lds
	s_waitcnt vmcnt(8)
	s_waitcnt lgkmcnt(0)
	s_setprio 1
	s_barrier
	v_mfma_f32_16x16x32_bf16 v[126:129], v[132:135], v[190:193], v[126:129]
	v_mfma_f32_16x16x32_bf16 v[126:129], v[142:145], v[194:197], v[126:129]
	v_mfma_f32_16x16x32_bf16 v[106:109], v[154:157], v[190:193], v[106:109]
	v_mfma_f32_16x16x32_bf16 v[106:109], v[170:173], v[194:197], v[106:109]
	v_mfma_f32_16x16x32_bf16 v[110:113], v[182:185], v[190:193], v[110:113]
	v_mfma_f32_16x16x32_bf16 v[110:113], v[186:189], v[194:197], v[110:113]
	v_mfma_f32_16x16x32_bf16 v[122:125], v[174:177], v[190:193], v[122:125]
	v_mfma_f32_16x16x32_bf16 v[122:125], v[178:181], v[194:197], v[122:125]
	v_mfma_f32_16x16x32_bf16 v[102:105], v[174:177], v[198:201], v[102:105]
	v_mfma_f32_16x16x32_bf16 v[102:105], v[178:181], v[202:205], v[102:105]
	v_mfma_f32_16x16x32_bf16 v[98:101], v[182:185], v[198:201], v[98:101]
	v_mfma_f32_16x16x32_bf16 v[98:101], v[186:189], v[202:205], v[98:101]
	v_mfma_f32_16x16x32_bf16 v[114:117], v[154:157], v[198:201], v[114:117]
	v_mfma_f32_16x16x32_bf16 v[114:117], v[170:173], v[202:205], v[114:117]
	v_mfma_f32_16x16x32_bf16 v[118:121], v[132:135], v[198:201], v[118:121]
	v_mfma_f32_16x16x32_bf16 v[118:121], v[142:145], v[202:205], v[118:121]
	v_mfma_f32_16x16x32_bf16 v[94:97], v[132:135], v[228:231], v[94:97]
	v_mfma_f32_16x16x32_bf16 v[94:97], v[142:145], v[232:235], v[94:97]
	v_mfma_f32_16x16x32_bf16 v[90:93], v[154:157], v[228:231], v[90:93]
	v_mfma_f32_16x16x32_bf16 v[90:93], v[170:173], v[232:235], v[90:93]
	v_mfma_f32_16x16x32_bf16 v[82:85], v[182:185], v[228:231], v[82:85]
	v_mfma_f32_16x16x32_bf16 v[82:85], v[186:189], v[232:235], v[82:85]
	v_mfma_f32_16x16x32_bf16 v[86:89], v[174:177], v[228:231], v[86:89]
	v_mfma_f32_16x16x32_bf16 v[86:89], v[178:181], v[232:235], v[86:89]
	v_mfma_f32_16x16x32_bf16 v[70:73], v[174:177], v[236:239], v[70:73]
	v_mfma_f32_16x16x32_bf16 v[70:73], v[178:181], v[240:243], v[70:73]
	v_mfma_f32_16x16x32_bf16 v[66:69], v[182:185], v[236:239], v[66:69]
	v_mfma_f32_16x16x32_bf16 v[66:69], v[186:189], v[240:243], v[66:69]
	v_mfma_f32_16x16x32_bf16 v[74:77], v[154:157], v[236:239], v[74:77]
	v_mfma_f32_16x16x32_bf16 v[74:77], v[170:173], v[240:243], v[74:77]
	v_mfma_f32_16x16x32_bf16 v[78:81], v[132:135], v[236:239], v[78:81]
	v_mfma_f32_16x16x32_bf16 v[78:81], v[142:145], v[240:243], v[78:81]
	s_barrier
	s_setprio 0
	s_mov_b32 s46, s62
	s_mov_b32 s47, s63
	s_mov_b32 m0, s18
	ds_read_b128 v[190:193], v141 offset:16384
	buffer_load_dwordx4 v137, s[44:47], s27 offen lds
	s_add_i32 s53, s27, 0x160000
	s_mov_b32 m0, s19
	ds_read_b128 v[194:197], v141 offset:17408
	buffer_load_dwordx4 v139, s[44:47], s27 offen lds
	s_mov_b32 m0, s24
	ds_read_b128 v[198:201], v141 offset:18432
	buffer_load_dwordx4 v137, s[44:47], s53 offen lds
	s_mov_b32 m0, s25
	ds_read_b128 v[202:205], v141 offset:19456
	buffer_load_dwordx4 v139, s[44:47], s53 offen lds
	s_mov_b32 m0, s14
	ds_read_b128 v[228:231], v141 offset:20480
	buffer_load_dwordx4 v136, s[60:63], s52 offen lds
	s_mov_b32 m0, s30
	ds_read_b128 v[232:235], v141 offset:21504
	buffer_load_dwordx4 v138, s[60:63], s52 offen lds
	ds_read_b128 v[236:239], v141 offset:22528
	ds_read_b128 v[240:243], v141 offset:23552
	s_waitcnt vmcnt(8)
	s_waitcnt lgkmcnt(0)
	s_setprio 1
	s_barrier
	v_mfma_f32_16x16x32_bf16 v[62:65], v[132:135], v[190:193], v[62:65]
	v_mfma_f32_16x16x32_bf16 v[62:65], v[142:145], v[194:197], v[62:65]
	v_mfma_f32_16x16x32_bf16 v[58:61], v[154:157], v[190:193], v[58:61]
	v_mfma_f32_16x16x32_bf16 v[58:61], v[170:173], v[194:197], v[58:61]
	v_mfma_f32_16x16x32_bf16 v[50:53], v[182:185], v[190:193], v[50:53]
	v_mfma_f32_16x16x32_bf16 v[50:53], v[186:189], v[194:197], v[50:53]
	v_mfma_f32_16x16x32_bf16 v[54:57], v[174:177], v[190:193], v[54:57]
	v_mfma_f32_16x16x32_bf16 v[54:57], v[178:181], v[194:197], v[54:57]
	v_mfma_f32_16x16x32_bf16 v[38:41], v[174:177], v[198:201], v[38:41]
	v_mfma_f32_16x16x32_bf16 v[38:41], v[178:181], v[202:205], v[38:41]
	v_mfma_f32_16x16x32_bf16 v[34:37], v[182:185], v[198:201], v[34:37]
	v_mfma_f32_16x16x32_bf16 v[34:37], v[186:189], v[202:205], v[34:37]
	v_mfma_f32_16x16x32_bf16 v[42:45], v[154:157], v[198:201], v[42:45]
	v_mfma_f32_16x16x32_bf16 v[42:45], v[170:173], v[202:205], v[42:45]
	v_mfma_f32_16x16x32_bf16 v[46:49], v[132:135], v[198:201], v[46:49]
	v_mfma_f32_16x16x32_bf16 v[46:49], v[142:145], v[202:205], v[46:49]
	v_mfma_f32_16x16x32_bf16 v[30:33], v[132:135], v[228:231], v[30:33]
	v_mfma_f32_16x16x32_bf16 v[30:33], v[142:145], v[232:235], v[30:33]
	v_mfma_f32_16x16x32_bf16 v[26:29], v[154:157], v[228:231], v[26:29]
	v_mfma_f32_16x16x32_bf16 v[26:29], v[170:173], v[232:235], v[26:29]
	v_mfma_f32_16x16x32_bf16 v[18:21], v[182:185], v[228:231], v[18:21]
	v_mfma_f32_16x16x32_bf16 v[18:21], v[186:189], v[232:235], v[18:21]
	v_mfma_f32_16x16x32_bf16 v[22:25], v[174:177], v[228:231], v[22:25]
	v_mfma_f32_16x16x32_bf16 v[22:25], v[178:181], v[232:235], v[22:25]
	v_mfma_f32_16x16x32_bf16 v[6:9], v[174:177], v[236:239], v[6:9]
	v_mfma_f32_16x16x32_bf16 v[6:9], v[178:181], v[240:243], v[6:9]
	v_mfma_f32_16x16x32_bf16 v[2:5], v[182:185], v[236:239], v[2:5]
	v_mfma_f32_16x16x32_bf16 v[2:5], v[186:189], v[240:243], v[2:5]
	v_mfma_f32_16x16x32_bf16 v[10:13], v[154:157], v[236:239], v[10:13]
	v_mfma_f32_16x16x32_bf16 v[10:13], v[170:173], v[240:243], v[10:13]
	v_mfma_f32_16x16x32_bf16 v[14:17], v[132:135], v[236:239], v[14:17]
	v_mfma_f32_16x16x32_bf16 v[14:17], v[142:145], v[240:243], v[14:17]
	s_barrier
	s_setprio 0
	v_add_u32_e32 v170, 0x18000, v140
	v_add_u32_e32 v186, 0x1c000, v140
	ds_read_b128 v[132:135], v170
	ds_read_b128 v[142:145], v170 offset:1024
	ds_read_b128 v[154:157], v170 offset:2048
	ds_read_b128 v[170:173], v170 offset:3072
	ds_read_b128 v[174:177], v186
	ds_read_b128 v[178:181], v186 offset:1024
	ds_read_b128 v[182:185], v186 offset:2048
	ds_read_b128 v[186:189], v186 offset:3072
	s_bitset1_b32 s52, 14
	s_mov_b32 m0, s31
	ds_read_b128 v[190:193], v141 offset:32768
	ds_read_b128 v[194:197], v141 offset:33792
	ds_read_b128 v[198:201], v141 offset:34816
	ds_read_b128 v[202:205], v141 offset:35840
	ds_read_b128 v[228:231], v141 offset:36864
	ds_read_b128 v[232:235], v141 offset:37888
	ds_read_b128 v[236:239], v141 offset:38912
	ds_read_b128 v[240:243], v141 offset:39936
	buffer_load_dwordx4 v136, s[60:63], s52 offen lds
	s_mov_b32 m0, s33
	s_nop 0
	buffer_load_dwordx4 v138, s[60:63], s52 offen lds
	s_waitcnt vmcnt(8)
	s_waitcnt lgkmcnt(0)
	s_setprio 1
	s_barrier
	v_mfma_f32_16x16x32_bf16 v[126:129], v[132:135], v[190:193], v[126:129]
	v_mfma_f32_16x16x32_bf16 v[126:129], v[142:145], v[194:197], v[126:129]
	v_mfma_f32_16x16x32_bf16 v[106:109], v[154:157], v[190:193], v[106:109]
	v_mfma_f32_16x16x32_bf16 v[106:109], v[170:173], v[194:197], v[106:109]
	v_mfma_f32_16x16x32_bf16 v[110:113], v[182:185], v[190:193], v[110:113]
	v_mfma_f32_16x16x32_bf16 v[110:113], v[186:189], v[194:197], v[110:113]
	v_mfma_f32_16x16x32_bf16 v[122:125], v[174:177], v[190:193], v[122:125]
	v_mfma_f32_16x16x32_bf16 v[122:125], v[178:181], v[194:197], v[122:125]
	v_mfma_f32_16x16x32_bf16 v[102:105], v[174:177], v[198:201], v[102:105]
	v_mfma_f32_16x16x32_bf16 v[102:105], v[178:181], v[202:205], v[102:105]
	v_mfma_f32_16x16x32_bf16 v[98:101], v[182:185], v[198:201], v[98:101]
	v_mfma_f32_16x16x32_bf16 v[98:101], v[186:189], v[202:205], v[98:101]
	v_mfma_f32_16x16x32_bf16 v[114:117], v[154:157], v[198:201], v[114:117]
	v_mfma_f32_16x16x32_bf16 v[114:117], v[170:173], v[202:205], v[114:117]
	v_mfma_f32_16x16x32_bf16 v[118:121], v[132:135], v[198:201], v[118:121]
	v_mfma_f32_16x16x32_bf16 v[118:121], v[142:145], v[202:205], v[118:121]
	v_mfma_f32_16x16x32_bf16 v[94:97], v[132:135], v[228:231], v[94:97]
	v_mfma_f32_16x16x32_bf16 v[94:97], v[142:145], v[232:235], v[94:97]
	v_mfma_f32_16x16x32_bf16 v[90:93], v[154:157], v[228:231], v[90:93]
	v_mfma_f32_16x16x32_bf16 v[90:93], v[170:173], v[232:235], v[90:93]
	v_mfma_f32_16x16x32_bf16 v[82:85], v[182:185], v[228:231], v[82:85]
	v_mfma_f32_16x16x32_bf16 v[82:85], v[186:189], v[232:235], v[82:85]
	v_mfma_f32_16x16x32_bf16 v[86:89], v[174:177], v[228:231], v[86:89]
	v_mfma_f32_16x16x32_bf16 v[86:89], v[178:181], v[232:235], v[86:89]
	v_mfma_f32_16x16x32_bf16 v[70:73], v[174:177], v[236:239], v[70:73]
	v_mfma_f32_16x16x32_bf16 v[70:73], v[178:181], v[240:243], v[70:73]
	v_mfma_f32_16x16x32_bf16 v[66:69], v[182:185], v[236:239], v[66:69]
	v_mfma_f32_16x16x32_bf16 v[66:69], v[186:189], v[240:243], v[66:69]
	v_mfma_f32_16x16x32_bf16 v[74:77], v[154:157], v[236:239], v[74:77]
	v_mfma_f32_16x16x32_bf16 v[74:77], v[170:173], v[240:243], v[74:77]
	v_mfma_f32_16x16x32_bf16 v[78:81], v[132:135], v[236:239], v[78:81]
	v_mfma_f32_16x16x32_bf16 v[78:81], v[142:145], v[240:243], v[78:81]
	s_barrier
	s_setprio 0
	s_or_b32 s52, s27, 0x80
	s_mov_b32 m0, s68
	ds_read_b128 v[190:193], v141 offset:49152
	buffer_load_dwordx4 v137, s[44:47], s52 offen lds
	s_add_i32 s27, s27, 0x160080
	s_mov_b32 m0, s69
	ds_read_b128 v[194:197], v141 offset:50176
	buffer_load_dwordx4 v139, s[44:47], s52 offen lds
	s_mov_b32 m0, s72
	ds_read_b128 v[198:201], v141 offset:51200
	buffer_load_dwordx4 v137, s[44:47], s27 offen lds
	s_mov_b32 m0, s73
	ds_read_b128 v[202:205], v141 offset:52224
	buffer_load_dwordx4 v139, s[44:47], s27 offen lds
	s_mov_b32 m0, s70
	ds_read_b128 v[228:231], v141 offset:53248
	buffer_load_dwordx4 v136, s[60:63], s26 offen lds
	s_mov_b32 m0, s71
	ds_read_b128 v[232:235], v141 offset:54272
	buffer_load_dwordx4 v138, s[60:63], s26 offen lds
	ds_read_b128 v[236:239], v141 offset:55296
	ds_read_b128 v[240:243], v141 offset:56320
	s_waitcnt vmcnt(8)
	s_waitcnt lgkmcnt(0)
	s_setprio 1
	s_barrier
	v_mfma_f32_16x16x32_bf16 v[62:65], v[132:135], v[190:193], v[62:65]
	v_mfma_f32_16x16x32_bf16 v[62:65], v[142:145], v[194:197], v[62:65]
	v_mfma_f32_16x16x32_bf16 v[58:61], v[154:157], v[190:193], v[58:61]
	v_mfma_f32_16x16x32_bf16 v[58:61], v[170:173], v[194:197], v[58:61]
	v_mfma_f32_16x16x32_bf16 v[50:53], v[182:185], v[190:193], v[50:53]
	v_mfma_f32_16x16x32_bf16 v[50:53], v[186:189], v[194:197], v[50:53]
	v_mfma_f32_16x16x32_bf16 v[54:57], v[174:177], v[190:193], v[54:57]
	v_mfma_f32_16x16x32_bf16 v[54:57], v[178:181], v[194:197], v[54:57]
	v_mfma_f32_16x16x32_bf16 v[38:41], v[174:177], v[198:201], v[38:41]
	v_mfma_f32_16x16x32_bf16 v[38:41], v[178:181], v[202:205], v[38:41]
	v_mfma_f32_16x16x32_bf16 v[34:37], v[182:185], v[198:201], v[34:37]
	v_mfma_f32_16x16x32_bf16 v[34:37], v[186:189], v[202:205], v[34:37]
	v_mfma_f32_16x16x32_bf16 v[42:45], v[154:157], v[198:201], v[42:45]
	v_mfma_f32_16x16x32_bf16 v[42:45], v[170:173], v[202:205], v[42:45]
	v_mfma_f32_16x16x32_bf16 v[46:49], v[132:135], v[198:201], v[46:49]
	v_mfma_f32_16x16x32_bf16 v[46:49], v[142:145], v[202:205], v[46:49]
	v_mfma_f32_16x16x32_bf16 v[30:33], v[132:135], v[228:231], v[30:33]
	v_mfma_f32_16x16x32_bf16 v[30:33], v[142:145], v[232:235], v[30:33]
	v_mfma_f32_16x16x32_bf16 v[26:29], v[154:157], v[228:231], v[26:29]
	v_mfma_f32_16x16x32_bf16 v[26:29], v[170:173], v[232:235], v[26:29]
	v_mfma_f32_16x16x32_bf16 v[18:21], v[182:185], v[228:231], v[18:21]
	v_mfma_f32_16x16x32_bf16 v[18:21], v[186:189], v[232:235], v[18:21]
	v_mfma_f32_16x16x32_bf16 v[22:25], v[174:177], v[228:231], v[22:25]
	v_mfma_f32_16x16x32_bf16 v[22:25], v[178:181], v[232:235], v[22:25]
	v_mfma_f32_16x16x32_bf16 v[6:9], v[174:177], v[236:239], v[6:9]
	v_mfma_f32_16x16x32_bf16 v[6:9], v[178:181], v[240:243], v[6:9]
	v_mfma_f32_16x16x32_bf16 v[2:5], v[182:185], v[236:239], v[2:5]
	v_mfma_f32_16x16x32_bf16 v[2:5], v[186:189], v[240:243], v[2:5]
	v_mfma_f32_16x16x32_bf16 v[10:13], v[154:157], v[236:239], v[10:13]
	v_mfma_f32_16x16x32_bf16 v[10:13], v[170:173], v[240:243], v[10:13]
	v_mfma_f32_16x16x32_bf16 v[14:17], v[132:135], v[236:239], v[14:17]
	v_mfma_f32_16x16x32_bf16 v[14:17], v[142:145], v[240:243], v[14:17]
	s_barrier
	s_setprio 0
	s_addk_i32 s13, 0x100
	s_add_i32 s22, s22, 2
	s_add_i32 s21, s21, 0x10000
	s_cmpk_gt_u32 s22, 0x55
	s_cbranch_scc0 .LBB0_2156
	s_and_b64 vcc, exec, s[66:67]
	s_cbranch_vccz .LBB0_2159
	s_barrier
	s_setprio 2

.LBB0_2170:
	s_setprio 0
	s_andn2_b64 vcc, exec, s[8:9]
	s_mov_b32 s71, s67
	s_mov_b32 s72, s68
	s_mov_b32 s82, s70
	s_mov_b32 s73, s69
	s_cbranch_vccz .LBB0_2182

.LBB0_2177:
	s_and_b64 vcc, exec, s[38:39]
	s_cbranch_vccz .LBB0_2179
	s_barrier
	s_setprio 2

.LBB0_2450:
	v_add_u32_e32 v142, 0x10000, v188
	v_add_u32_e32 v182, 0x14000, v188
	ds_read_b128 v[130:133], v142
	ds_read_b128 v[134:137], v142 offset:1024
	ds_read_b128 v[138:141], v142 offset:2048
	ds_read_b128 v[142:145], v142 offset:3072
	ds_read_b128 v[154:157], v182
	ds_read_b128 v[174:177], v182 offset:1024
	ds_read_b128 v[178:181], v182 offset:2048
	ds_read_b128 v[190:193], v182 offset:3072
	s_add_i32 s24, s13, 0xfff80080
	s_cmp_eq_u32 s22, 28
	s_cselect_b32 s52, s8, s24
	s_cselect_b32 s25, s9, s21
	s_or_b32 s24, s52, 0x80
	s_mov_b32 m0, s68
	ds_read_b128 v[194:197], v189
	ds_read_b128 v[198:201], v189 offset:1024
	ds_read_b128 v[202:205], v189 offset:2048
	ds_read_b128 v[228:231], v189 offset:3072
	ds_read_b128 v[232:235], v189 offset:4096
	ds_read_b128 v[236:239], v189 offset:5120
	ds_read_b128 v[240:243], v189 offset:6144
	ds_read_b128 v[244:247], v189 offset:7168
	buffer_load_dwordx4 v184, s[60:63], s13 offen lds
	s_mov_b32 m0, s70
	s_nop 0
	buffer_load_dwordx4 v186, s[60:63], s13 offen lds
	s_waitcnt vmcnt(8)
	s_waitcnt lgkmcnt(0)
	s_setprio 1
	s_barrier
	v_mfma_f32_16x16x32_bf16 v[126:129], v[130:133], v[194:197], v[126:129]
	v_mfma_f32_16x16x32_bf16 v[126:129], v[134:137], v[198:201], v[126:129]
	v_mfma_f32_16x16x32_bf16 v[122:125], v[138:141], v[194:197], v[122:125]
	v_mfma_f32_16x16x32_bf16 v[122:125], v[142:145], v[198:201], v[122:125]
	v_mfma_f32_16x16x32_bf16 v[114:117], v[178:181], v[194:197], v[114:117]
	v_mfma_f32_16x16x32_bf16 v[114:117], v[190:193], v[198:201], v[114:117]
	v_mfma_f32_16x16x32_bf16 v[118:121], v[154:157], v[194:197], v[118:121]
	v_mfma_f32_16x16x32_bf16 v[118:121], v[174:177], v[198:201], v[118:121]
	v_mfma_f32_16x16x32_bf16 v[102:105], v[154:157], v[202:205], v[102:105]
	v_mfma_f32_16x16x32_bf16 v[102:105], v[174:177], v[228:231], v[102:105]
	v_mfma_f32_16x16x32_bf16 v[98:101], v[178:181], v[202:205], v[98:101]
	v_mfma_f32_16x16x32_bf16 v[98:101], v[190:193], v[228:231], v[98:101]
	v_mfma_f32_16x16x32_bf16 v[106:109], v[138:141], v[202:205], v[106:109]
	v_mfma_f32_16x16x32_bf16 v[106:109], v[142:145], v[228:231], v[106:109]
	v_mfma_f32_16x16x32_bf16 v[110:113], v[130:133], v[202:205], v[110:113]
	v_mfma_f32_16x16x32_bf16 v[110:113], v[134:137], v[228:231], v[110:113]
	v_mfma_f32_16x16x32_bf16 v[94:97], v[130:133], v[232:235], v[94:97]
	v_mfma_f32_16x16x32_bf16 v[94:97], v[134:137], v[236:239], v[94:97]
	v_mfma_f32_16x16x32_bf16 v[90:93], v[138:141], v[232:235], v[90:93]
	v_mfma_f32_16x16x32_bf16 v[90:93], v[142:145], v[236:239], v[90:93]
	v_mfma_f32_16x16x32_bf16 v[82:85], v[178:181], v[232:235], v[82:85]
	v_mfma_f32_16x16x32_bf16 v[82:85], v[190:193], v[236:239], v[82:85]
	v_mfma_f32_16x16x32_bf16 v[86:89], v[154:157], v[232:235], v[86:89]
	v_mfma_f32_16x16x32_bf16 v[86:89], v[174:177], v[236:239], v[86:89]
	v_mfma_f32_16x16x32_bf16 v[70:73], v[154:157], v[240:243], v[70:73]
	v_mfma_f32_16x16x32_bf16 v[70:73], v[174:177], v[244:247], v[70:73]
	v_mfma_f32_16x16x32_bf16 v[66:69], v[178:181], v[240:243], v[66:69]
	v_mfma_f32_16x16x32_bf16 v[66:69], v[190:193], v[244:247], v[66:69]
	v_mfma_f32_16x16x32_bf16 v[74:77], v[138:141], v[240:243], v[74:77]
	v_mfma_f32_16x16x32_bf16 v[74:77], v[142:145], v[244:247], v[74:77]
	v_mfma_f32_16x16x32_bf16 v[78:81], v[130:133], v[240:243], v[78:81]
	v_mfma_f32_16x16x32_bf16 v[78:81], v[134:137], v[244:247], v[78:81]
	s_barrier
	s_setprio 0
	s_mov_b32 s46, s62
	s_mov_b32 s47, s63
	s_mov_b32 m0, s16
	ds_read_b128 v[194:197], v189 offset:16384
	buffer_load_dwordx4 v185, s[44:47], s25 offen lds
	s_add_i32 s53, s25, 0x80000
	s_mov_b32 m0, s18
	ds_read_b128 v[198:201], v189 offset:17408
	buffer_load_dwordx4 v187, s[44:47], s25 offen lds
	s_mov_b32 m0, s19
	ds_read_b128 v[202:205], v189 offset:18432
	buffer_load_dwordx4 v185, s[44:47], s53 offen lds
	s_mov_b32 m0, s23
	ds_read_b128 v[228:231], v189 offset:19456
	buffer_load_dwordx4 v187, s[44:47], s53 offen lds
	s_mov_b32 m0, s15
	ds_read_b128 v[232:235], v189 offset:20480
	buffer_load_dwordx4 v184, s[60:63], s52 offen lds
	s_mov_b32 m0, s26
	ds_read_b128 v[236:239], v189 offset:21504
	buffer_load_dwordx4 v186, s[60:63], s52 offen lds
	ds_read_b128 v[240:243], v189 offset:22528
	ds_read_b128 v[244:247], v189 offset:23552
	s_waitcnt vmcnt(8)
	s_waitcnt lgkmcnt(0)
	s_setprio 1
	s_barrier
	v_mfma_f32_16x16x32_bf16 v[62:65], v[130:133], v[194:197], v[62:65]
	v_mfma_f32_16x16x32_bf16 v[62:65], v[134:137], v[198:201], v[62:65]
	v_mfma_f32_16x16x32_bf16 v[58:61], v[138:141], v[194:197], v[58:61]
	v_mfma_f32_16x16x32_bf16 v[58:61], v[142:145], v[198:201], v[58:61]
	v_mfma_f32_16x16x32_bf16 v[50:53], v[178:181], v[194:197], v[50:53]
	v_mfma_f32_16x16x32_bf16 v[50:53], v[190:193], v[198:201], v[50:53]
	v_mfma_f32_16x16x32_bf16 v[54:57], v[154:157], v[194:197], v[54:57]
	v_mfma_f32_16x16x32_bf16 v[54:57], v[174:177], v[198:201], v[54:57]
	v_mfma_f32_16x16x32_bf16 v[38:41], v[154:157], v[202:205], v[38:41]
	v_mfma_f32_16x16x32_bf16 v[38:41], v[174:177], v[228:231], v[38:41]
	v_mfma_f32_16x16x32_bf16 v[34:37], v[178:181], v[202:205], v[34:37]
	v_mfma_f32_16x16x32_bf16 v[34:37], v[190:193], v[228:231], v[34:37]
	v_mfma_f32_16x16x32_bf16 v[42:45], v[138:141], v[202:205], v[42:45]
	v_mfma_f32_16x16x32_bf16 v[42:45], v[142:145], v[228:231], v[42:45]
	v_mfma_f32_16x16x32_bf16 v[46:49], v[130:133], v[202:205], v[46:49]
	v_mfma_f32_16x16x32_bf16 v[46:49], v[134:137], v[228:231], v[46:49]
	v_mfma_f32_16x16x32_bf16 v[30:33], v[130:133], v[232:235], v[30:33]
	v_mfma_f32_16x16x32_bf16 v[30:33], v[134:137], v[236:239], v[30:33]
	v_mfma_f32_16x16x32_bf16 v[26:29], v[138:141], v[232:235], v[26:29]
	v_mfma_f32_16x16x32_bf16 v[26:29], v[142:145], v[236:239], v[26:29]
	v_mfma_f32_16x16x32_bf16 v[18:21], v[178:181], v[232:235], v[18:21]
	v_mfma_f32_16x16x32_bf16 v[18:21], v[190:193], v[236:239], v[18:21]
	v_mfma_f32_16x16x32_bf16 v[22:25], v[154:157], v[232:235], v[22:25]
	v_mfma_f32_16x16x32_bf16 v[22:25], v[174:177], v[236:239], v[22:25]
	v_mfma_f32_16x16x32_bf16 v[6:9], v[154:157], v[240:243], v[6:9]
	v_mfma_f32_16x16x32_bf16 v[6:9], v[174:177], v[244:247], v[6:9]
	v_mfma_f32_16x16x32_bf16 v[2:5], v[178:181], v[240:243], v[2:5]
	v_mfma_f32_16x16x32_bf16 v[2:5], v[190:193], v[244:247], v[2:5]
	v_mfma_f32_16x16x32_bf16 v[10:13], v[138:141], v[240:243], v[10:13]
	v_mfma_f32_16x16x32_bf16 v[10:13], v[142:145], v[244:247], v[10:13]
	v_mfma_f32_16x16x32_bf16 v[14:17], v[130:133], v[240:243], v[14:17]
	v_mfma_f32_16x16x32_bf16 v[14:17], v[134:137], v[244:247], v[14:17]
	s_barrier
	s_setprio 0
	v_add_u32_e32 v142, 0x18000, v188
	v_add_u32_e32 v182, 0x1c000, v188
	ds_read_b128 v[130:133], v142
	ds_read_b128 v[134:137], v142 offset:1024
	ds_read_b128 v[138:141], v142 offset:2048
	ds_read_b128 v[142:145], v142 offset:3072
	ds_read_b128 v[154:157], v182
	ds_read_b128 v[174:177], v182 offset:1024
	ds_read_b128 v[178:181], v182 offset:2048
	ds_read_b128 v[190:193], v182 offset:3072
	s_add_i32 s52, s52, 0x80000
	s_mov_b32 m0, s27
	ds_read_b128 v[194:197], v189 offset:32768
	ds_read_b128 v[198:201], v189 offset:33792
	ds_read_b128 v[202:205], v189 offset:34816
	ds_read_b128 v[228:231], v189 offset:35840
	ds_read_b128 v[232:235], v189 offset:36864
	ds_read_b128 v[236:239], v189 offset:37888
	ds_read_b128 v[240:243], v189 offset:38912
	ds_read_b128 v[244:247], v189 offset:39936
	buffer_load_dwordx4 v184, s[60:63], s52 offen lds
	s_mov_b32 m0, s30
	s_nop 0
	buffer_load_dwordx4 v186, s[60:63], s52 offen lds
	s_waitcnt vmcnt(8)
	s_waitcnt lgkmcnt(0)
	s_setprio 1
	s_barrier
	v_mfma_f32_16x16x32_bf16 v[126:129], v[130:133], v[194:197], v[126:129]
	v_mfma_f32_16x16x32_bf16 v[126:129], v[134:137], v[198:201], v[126:129]
	v_mfma_f32_16x16x32_bf16 v[122:125], v[138:141], v[194:197], v[122:125]
	v_mfma_f32_16x16x32_bf16 v[122:125], v[142:145], v[198:201], v[122:125]
	v_mfma_f32_16x16x32_bf16 v[114:117], v[178:181], v[194:197], v[114:117]
	v_mfma_f32_16x16x32_bf16 v[114:117], v[190:193], v[198:201], v[114:117]
	v_mfma_f32_16x16x32_bf16 v[118:121], v[154:157], v[194:197], v[118:121]
	v_mfma_f32_16x16x32_bf16 v[118:121], v[174:177], v[198:201], v[118:121]
	v_mfma_f32_16x16x32_bf16 v[102:105], v[154:157], v[202:205], v[102:105]
	v_mfma_f32_16x16x32_bf16 v[102:105], v[174:177], v[228:231], v[102:105]
	v_mfma_f32_16x16x32_bf16 v[98:101], v[178:181], v[202:205], v[98:101]
	v_mfma_f32_16x16x32_bf16 v[98:101], v[190:193], v[228:231], v[98:101]
	v_mfma_f32_16x16x32_bf16 v[106:109], v[138:141], v[202:205], v[106:109]
	v_mfma_f32_16x16x32_bf16 v[106:109], v[142:145], v[228:231], v[106:109]
	v_mfma_f32_16x16x32_bf16 v[110:113], v[130:133], v[202:205], v[110:113]
	v_mfma_f32_16x16x32_bf16 v[110:113], v[134:137], v[228:231], v[110:113]
	v_mfma_f32_16x16x32_bf16 v[94:97], v[130:133], v[232:235], v[94:97]
	v_mfma_f32_16x16x32_bf16 v[94:97], v[134:137], v[236:239], v[94:97]
	v_mfma_f32_16x16x32_bf16 v[90:93], v[138:141], v[232:235], v[90:93]
	v_mfma_f32_16x16x32_bf16 v[90:93], v[142:145], v[236:239], v[90:93]
	v_mfma_f32_16x16x32_bf16 v[82:85], v[178:181], v[232:235], v[82:85]
	v_mfma_f32_16x16x32_bf16 v[82:85], v[190:193], v[236:239], v[82:85]
	v_mfma_f32_16x16x32_bf16 v[86:89], v[154:157], v[232:235], v[86:89]
	v_mfma_f32_16x16x32_bf16 v[86:89], v[174:177], v[236:239], v[86:89]
	v_mfma_f32_16x16x32_bf16 v[70:73], v[154:157], v[240:243], v[70:73]
	v_mfma_f32_16x16x32_bf16 v[70:73], v[174:177], v[244:247], v[70:73]
	v_mfma_f32_16x16x32_bf16 v[66:69], v[178:181], v[240:243], v[66:69]
	v_mfma_f32_16x16x32_bf16 v[66:69], v[190:193], v[244:247], v[66:69]
	v_mfma_f32_16x16x32_bf16 v[74:77], v[138:141], v[240:243], v[74:77]
	v_mfma_f32_16x16x32_bf16 v[74:77], v[142:145], v[244:247], v[74:77]
	v_mfma_f32_16x16x32_bf16 v[78:81], v[130:133], v[240:243], v[78:81]
	v_mfma_f32_16x16x32_bf16 v[78:81], v[134:137], v[244:247], v[78:81]
	s_barrier
	s_setprio 0
	s_or_b32 s52, s25, 0x80
	s_mov_b32 m0, s36
	ds_read_b128 v[194:197], v189 offset:49152
	buffer_load_dwordx4 v185, s[44:47], s52 offen lds
	s_add_i32 s25, s25, 0x80080
	s_mov_b32 m0, s37
	ds_read_b128 v[198:201], v189 offset:50176
	buffer_load_dwordx4 v187, s[44:47], s52 offen lds
	s_mov_b32 m0, s66
	ds_read_b128 v[202:205], v189 offset:51200
	buffer_load_dwordx4 v185, s[44:47], s25 offen lds
	s_mov_b32 m0, s67
	ds_read_b128 v[228:231], v189 offset:52224
	buffer_load_dwordx4 v187, s[44:47], s25 offen lds
	s_mov_b32 m0, s48
	ds_read_b128 v[232:235], v189 offset:53248
	buffer_load_dwordx4 v184, s[60:63], s24 offen lds
	s_mov_b32 m0, s49
	ds_read_b128 v[236:239], v189 offset:54272
	buffer_load_dwordx4 v186, s[60:63], s24 offen lds
	ds_read_b128 v[240:243], v189 offset:55296
	ds_read_b128 v[244:247], v189 offset:56320
	s_waitcnt vmcnt(8)
	s_waitcnt lgkmcnt(0)
	s_setprio 1
	s_barrier
	v_mfma_f32_16x16x32_bf16 v[62:65], v[130:133], v[194:197], v[62:65]
	v_mfma_f32_16x16x32_bf16 v[62:65], v[134:137], v[198:201], v[62:65]
	v_mfma_f32_16x16x32_bf16 v[58:61], v[138:141], v[194:197], v[58:61]
	v_mfma_f32_16x16x32_bf16 v[58:61], v[142:145], v[198:201], v[58:61]
	v_mfma_f32_16x16x32_bf16 v[50:53], v[178:181], v[194:197], v[50:53]
	v_mfma_f32_16x16x32_bf16 v[50:53], v[190:193], v[198:201], v[50:53]
	v_mfma_f32_16x16x32_bf16 v[54:57], v[154:157], v[194:197], v[54:57]
	v_mfma_f32_16x16x32_bf16 v[54:57], v[174:177], v[198:201], v[54:57]
	v_mfma_f32_16x16x32_bf16 v[38:41], v[154:157], v[202:205], v[38:41]
	v_mfma_f32_16x16x32_bf16 v[38:41], v[174:177], v[228:231], v[38:41]
	v_mfma_f32_16x16x32_bf16 v[34:37], v[178:181], v[202:205], v[34:37]
	v_mfma_f32_16x16x32_bf16 v[34:37], v[190:193], v[228:231], v[34:37]
	v_mfma_f32_16x16x32_bf16 v[42:45], v[138:141], v[202:205], v[42:45]
	v_mfma_f32_16x16x32_bf16 v[42:45], v[142:145], v[228:231], v[42:45]
	v_mfma_f32_16x16x32_bf16 v[46:49], v[130:133], v[202:205], v[46:49]
	v_mfma_f32_16x16x32_bf16 v[46:49], v[134:137], v[228:231], v[46:49]
	v_mfma_f32_16x16x32_bf16 v[30:33], v[130:133], v[232:235], v[30:33]
	v_mfma_f32_16x16x32_bf16 v[30:33], v[134:137], v[236:239], v[30:33]
	v_mfma_f32_16x16x32_bf16 v[26:29], v[138:141], v[232:235], v[26:29]
	v_mfma_f32_16x16x32_bf16 v[26:29], v[142:145], v[236:239], v[26:29]
	v_mfma_f32_16x16x32_bf16 v[18:21], v[178:181], v[232:235], v[18:21]
	v_mfma_f32_16x16x32_bf16 v[18:21], v[190:193], v[236:239], v[18:21]
	v_mfma_f32_16x16x32_bf16 v[22:25], v[154:157], v[232:235], v[22:25]
	v_mfma_f32_16x16x32_bf16 v[22:25], v[174:177], v[236:239], v[22:25]
	v_mfma_f32_16x16x32_bf16 v[6:9], v[154:157], v[240:243], v[6:9]
	v_mfma_f32_16x16x32_bf16 v[6:9], v[174:177], v[244:247], v[6:9]
	v_mfma_f32_16x16x32_bf16 v[2:5], v[178:181], v[240:243], v[2:5]
	v_mfma_f32_16x16x32_bf16 v[2:5], v[190:193], v[244:247], v[2:5]
	v_mfma_f32_16x16x32_bf16 v[10:13], v[138:141], v[240:243], v[10:13]
	v_mfma_f32_16x16x32_bf16 v[10:13], v[142:145], v[244:247], v[10:13]
	v_mfma_f32_16x16x32_bf16 v[14:17], v[130:133], v[240:243], v[14:17]
	v_mfma_f32_16x16x32_bf16 v[14:17], v[134:137], v[244:247], v[14:17]
	s_barrier
	s_setprio 0
	s_add_i32 s22, s22, 2
	s_addk_i32 s13, 0x100
	s_addk_i32 s21, 0x100
	s_cmp_gt_u32 s22, 29
	s_cbranch_scc0 .LBB0_2450
	s_and_b64 vcc, exec, s[64:65]
	s_cbranch_vccz .LBB0_2453
	s_barrier
	s_setprio 2
